# K-loop load segments: ds_reads interleaved between each m0 write and its LDS-DMA (no s_nop), vmcnt/lgkmcnt waits merged, on top of saddr DMA, LDS offsets, C=0 peel, setprio/wait trims, shift-based uni
# baseline (speedup 1.0000x reference)
; #define PG8_STAGE(bufoff, gbase, voff) do { _Pragma("unroll") for (int _i = 0; _i < 2; ++_i) \
;         __builtin_amdgcn_global_load_lds((const unsigned*)((const char*)(gbase) + (voff)[_i]), (PG8_LAS unsigned*)(lds + (bufoff) + ldsw + _i * 8192), 16, 0, 0); } while (0)
; #define PG8_LDA(dst, b, h) do { _Pragma("unroll") for (int m = 0; m < 4; ++m) _Pragma("unroll") for (int k = 0; k < 2; ++k) dst[m][k] = *(const PG8_LAS bf16x8*)(lds + PG8_SA(b, h) + aoff + m * 2048 + k * 1024); } while (0)
; #define PG8_LDB(dst, b, h) do { _Pragma("unroll") for (int n = 0; n < 2; ++n) _Pragma("unroll") for (int k = 0; k < 2; ++k) dst[n][k] = *(const PG8_LAS bf16x8*)(lds + PG8_SB(b, h) + boff + n * 2048 + k * 1024); } while (0)
; #define PG8_MMA(ai, bj, At, Bt) do { __builtin_amdgcn_s_setprio(1); _Pragma("unroll") for (int m = 0; m < 4; ++m) _Pragma("unroll") for (int n = 0; n < 2; ++n) _Pragma("unroll") for (int k = 0; k < 2; ++k) \
;         acc[ai][bj][m][n] = __builtin_amdgcn_mfma_f32_16x16x32_bf16(Bt[n][k], At[m][k], acc[ai][bj][m][n], 0, 0, 0); __builtin_amdgcn_s_setprio(0); } while (0)
; #define PG8_WAIT_V(n) asm volatile("s_waitcnt vmcnt(" #n ")" ::: "memory")
; #define PG8_WAIT_L(n) asm volatile("s_waitcnt lgkmcnt(" #n ")" ::: "memory")
; #define PG8_BAR __builtin_amdgcn_s_barrier()
; #define PG8_SCHED __builtin_amdgcn_sched_barrier(0)
; template <class Epi, class Sched, bool ALIGN_EPI = false, bool SP2 = false>
; __device__ __forceinline__ void gemm_phase(PG8_LAS unsigned char* lds, const Gemm g, const Sched& S, const Epi& E) {
;     ...
;             PG8_LDB(B0, 0, 0); PG8_LDB(B1, 0, 1); PG8_SCHED; PG8_LDA(At, 0, 0); PG8_STAGE(PG8_SA(1, 1), a1 + hstep, voffA);
;             PG8_WAIT_V(8); PG8_WAIT_L(0); PG8_BAR; PG8_MMA(0, 0, At, B0); PG8_MMA(0, 1, At, B1); PG8_BAR; PG8_SCHED;
;             PG8_LDA(At, 0, 1); PG8_STAGE(PG8_SB(0, 0), b2, voffB); PG8_STAGE(PG8_SB(0, 1), b2 + hstep, voffB); PG8_STAGE(PG8_SA(0, 0), a2, voffA);
;             PG8_WAIT_V(8); PG8_WAIT_L(0); PG8_BAR; PG8_MMA(1, 0, At, B0); PG8_MMA(1, 1, At, B1); PG8_BAR; PG8_SCHED;
.Labo_peel:
	s_add_u32 s2, s0, 0xfffc0080
	s_addc_u32 s3, s1, -1
	s_cmp_eq_u32 s56, 12
	s_cselect_b32 s5, s27, s3
	s_cselect_b32 s4, s52, s2
	s_cselect_b32 s3, s25, s55
	s_cselect_b32 s2, s53, s54
	s_add_i32 m0, s29, 0xc000
	ds_read_b128 v[68:71], v254
	ds_read_b128 v[72:75], v254 offset:1024
	ds_read_b128 v[76:79], v254 offset:2048
	ds_read_b128 v[80:83], v254 offset:3072
	ds_read_b128 v[174:177], v254 offset:16384
	ds_read_b128 v[182:185], v254 offset:17408
	ds_read_b128 v[186:189], v254 offset:18432
	ds_read_b128 v[210:213], v254 offset:19456
	global_load_lds_dwordx4 v170, s[0:1]
	s_add_i32 m0, s29, 0xe000
	ds_read_b128 v[214:217], v179
	ds_read_b128 v[218:221], v179 offset:1024
	ds_read_b128 v[222:225], v179 offset:2048
	ds_read_b128 v[226:229], v179 offset:3072
	ds_read_b128 v[230:233], v179 offset:4096
	ds_read_b128 v[234:237], v179 offset:5120
	ds_read_b128 v[238:241], v179 offset:6144
	ds_read_b128 v[242:245], v179 offset:7168
	global_load_lds_dwordx4 v172, s[0:1]
	s_waitcnt vmcnt(8) lgkmcnt(0)
	s_barrier
	s_setprio 1
	v_mfma_f32_16x16x32_bf16 v[140:143], v[68:71], v[214:217], 0
	v_mfma_f32_16x16x32_bf16 v[136:139], v[76:79], v[214:217], 0
	v_mfma_f32_16x16x32_bf16 v[124:127], v[68:71], v[222:225], 0
	v_mfma_f32_16x16x32_bf16 v[120:123], v[76:79], v[222:225], 0
	v_mfma_f32_16x16x32_bf16 v[108:111], v[68:71], v[230:233], 0
	v_mfma_f32_16x16x32_bf16 v[104:107], v[76:79], v[230:233], 0
	v_mfma_f32_16x16x32_bf16 v[92:95], v[68:71], v[238:241], 0
	v_mfma_f32_16x16x32_bf16 v[88:91], v[76:79], v[238:241], 0
	v_mfma_f32_16x16x32_bf16 v[140:143], v[72:75], v[218:221], v[140:143]
	v_mfma_f32_16x16x32_bf16 v[136:139], v[80:83], v[218:221], v[136:139]
	v_mfma_f32_16x16x32_bf16 v[124:127], v[72:75], v[226:229], v[124:127]
	v_mfma_f32_16x16x32_bf16 v[120:123], v[80:83], v[226:229], v[120:123]
	v_mfma_f32_16x16x32_bf16 v[108:111], v[72:75], v[234:237], v[108:111]
	v_mfma_f32_16x16x32_bf16 v[104:107], v[80:83], v[234:237], v[104:107]
	v_mfma_f32_16x16x32_bf16 v[92:95], v[72:75], v[242:245], v[92:95]
	v_mfma_f32_16x16x32_bf16 v[88:91], v[80:83], v[242:245], v[88:91]
	v_mfma_f32_16x16x32_bf16 v[132:135], v[174:177], v[214:217], 0
	v_mfma_f32_16x16x32_bf16 v[128:131], v[186:189], v[214:217], 0
	v_mfma_f32_16x16x32_bf16 v[116:119], v[174:177], v[222:225], 0
	v_mfma_f32_16x16x32_bf16 v[112:115], v[186:189], v[222:225], 0
	v_mfma_f32_16x16x32_bf16 v[100:103], v[174:177], v[230:233], 0
	v_mfma_f32_16x16x32_bf16 v[96:99], v[186:189], v[230:233], 0
	v_mfma_f32_16x16x32_bf16 v[84:87], v[174:177], v[238:241], 0
	v_mfma_f32_16x16x32_bf16 v[64:67], v[186:189], v[238:241], 0
	v_mfma_f32_16x16x32_bf16 v[132:135], v[182:185], v[218:221], v[132:135]
	v_mfma_f32_16x16x32_bf16 v[128:131], v[210:213], v[218:221], v[128:131]
	v_mfma_f32_16x16x32_bf16 v[116:119], v[182:185], v[226:229], v[116:119]
	v_mfma_f32_16x16x32_bf16 v[112:115], v[210:213], v[226:229], v[112:115]
	v_mfma_f32_16x16x32_bf16 v[100:103], v[182:185], v[234:237], v[100:103]
	v_mfma_f32_16x16x32_bf16 v[96:99], v[210:213], v[234:237], v[96:99]
	v_mfma_f32_16x16x32_bf16 v[84:87], v[182:185], v[242:245], v[84:87]
	v_mfma_f32_16x16x32_bf16 v[64:67], v[210:213], v[242:245], v[64:67]
	s_setprio 0
	s_barrier
	s_mov_b32 m0, s30
	s_add_u32 s58, s2, 0x40000
	s_addc_u32 s59, s3, 0
	ds_read_b128 v[214:217], v179 offset:16384
	ds_read_b128 v[218:221], v179 offset:17408
	global_load_lds_dwordx4 v166, s[2:3]
	s_mov_b32 m0, s31
	ds_read_b128 v[222:225], v179 offset:18432
	ds_read_b128 v[226:229], v179 offset:19456
	global_load_lds_dwordx4 v162, s[2:3]
	s_mov_b32 m0, s33
	ds_read_b128 v[230:233], v179 offset:20480
	global_load_lds_dwordx4 v166, s[58:59]
	s_mov_b32 m0, s34
	ds_read_b128 v[234:237], v179 offset:21504
	global_load_lds_dwordx4 v162, s[58:59]
	s_mov_b32 m0, s29
	ds_read_b128 v[238:241], v179 offset:22528
	global_load_lds_dwordx4 v168, s[4:5]
	s_mov_b32 m0, s35
	ds_read_b128 v[242:245], v179 offset:23552
	global_load_lds_dwordx4 v164, s[4:5]
	s_waitcnt vmcnt(8) lgkmcnt(0)
	s_barrier
	s_setprio 1
	v_mfma_f32_16x16x32_bf16 v[60:63], v[68:71], v[214:217], 0
	v_mfma_f32_16x16x32_bf16 v[56:59], v[76:79], v[214:217], 0
	v_mfma_f32_16x16x32_bf16 v[44:47], v[68:71], v[222:225], 0
	v_mfma_f32_16x16x32_bf16 v[40:43], v[76:79], v[222:225], 0
	v_mfma_f32_16x16x32_bf16 v[28:31], v[68:71], v[230:233], 0
	v_mfma_f32_16x16x32_bf16 v[24:27], v[76:79], v[230:233], 0
	v_mfma_f32_16x16x32_bf16 v[12:15], v[68:71], v[238:241], 0
	v_mfma_f32_16x16x32_bf16 v[8:11], v[76:79], v[238:241], 0
	v_mfma_f32_16x16x32_bf16 v[60:63], v[72:75], v[218:221], v[60:63]
	v_mfma_f32_16x16x32_bf16 v[56:59], v[80:83], v[218:221], v[56:59]
	v_mfma_f32_16x16x32_bf16 v[44:47], v[72:75], v[226:229], v[44:47]
	v_mfma_f32_16x16x32_bf16 v[40:43], v[80:83], v[226:229], v[40:43]
	v_mfma_f32_16x16x32_bf16 v[28:31], v[72:75], v[234:237], v[28:31]
	v_mfma_f32_16x16x32_bf16 v[24:27], v[80:83], v[234:237], v[24:27]
	v_mfma_f32_16x16x32_bf16 v[12:15], v[72:75], v[242:245], v[12:15]
	v_mfma_f32_16x16x32_bf16 v[8:11], v[80:83], v[242:245], v[8:11]
	v_mfma_f32_16x16x32_bf16 v[52:55], v[174:177], v[214:217], 0
	v_mfma_f32_16x16x32_bf16 v[48:51], v[186:189], v[214:217], 0
	v_mfma_f32_16x16x32_bf16 v[36:39], v[174:177], v[222:225], 0
	v_mfma_f32_16x16x32_bf16 v[32:35], v[186:189], v[222:225], 0
	v_mfma_f32_16x16x32_bf16 v[20:23], v[174:177], v[230:233], 0
	v_mfma_f32_16x16x32_bf16 v[16:19], v[186:189], v[230:233], 0
	v_mfma_f32_16x16x32_bf16 v[4:7], v[174:177], v[238:241], 0
	v_mfma_f32_16x16x32_bf16 v[0:3], v[186:189], v[238:241], 0
	v_mfma_f32_16x16x32_bf16 v[52:55], v[182:185], v[218:221], v[52:55]
	v_mfma_f32_16x16x32_bf16 v[48:51], v[210:213], v[218:221], v[48:51]
	v_mfma_f32_16x16x32_bf16 v[36:39], v[182:185], v[226:229], v[36:39]
	v_mfma_f32_16x16x32_bf16 v[32:35], v[210:213], v[226:229], v[32:35]
	v_mfma_f32_16x16x32_bf16 v[20:23], v[182:185], v[234:237], v[20:23]
	v_mfma_f32_16x16x32_bf16 v[16:19], v[210:213], v[234:237], v[16:19]
	v_mfma_f32_16x16x32_bf16 v[4:7], v[182:185], v[242:245], v[4:7]
	v_mfma_f32_16x16x32_bf16 v[0:3], v[210:213], v[242:245], v[0:3]
	s_setprio 0
	s_barrier
; #define PG8_STAGE(bufoff, gbase, voff) do { _Pragma("unroll") for (int _i = 0; _i < 2; ++_i) \
;         __builtin_amdgcn_global_load_lds((const unsigned*)((const char*)(gbase) + (voff)[_i]), (PG8_LAS unsigned*)(lds + (bufoff) + ldsw + _i * 8192), 16, 0, 0); } while (0)
; #define PG8_LDA(dst, b, h) do { _Pragma("unroll") for (int m = 0; m < 4; ++m) _Pragma("unroll") for (int k = 0; k < 2; ++k) dst[m][k] = *(const PG8_LAS bf16x8*)(lds + PG8_SA(b, h) + aoff + m * 2048 + k * 1024); } while (0)
; #define PG8_LDB(dst, b, h) do { _Pragma("unroll") for (int n = 0; n < 2; ++n) _Pragma("unroll") for (int k = 0; k < 2; ++k) dst[n][k] = *(const PG8_LAS bf16x8*)(lds + PG8_SB(b, h) + boff + n * 2048 + k * 1024); } while (0)
; #define PG8_MMA(ai, bj, At, Bt) do { __builtin_amdgcn_s_setprio(1); _Pragma("unroll") for (int m = 0; m < 4; ++m) _Pragma("unroll") for (int n = 0; n < 2; ++n) _Pragma("unroll") for (int k = 0; k < 2; ++k) \
;         acc[ai][bj][m][n] = __builtin_amdgcn_mfma_f32_16x16x32_bf16(Bt[n][k], At[m][k], acc[ai][bj][m][n], 0, 0, 0); __builtin_amdgcn_s_setprio(0); } while (0)
; #define PG8_WAIT_V(n) asm volatile("s_waitcnt vmcnt(" #n ")" ::: "memory")
; #define PG8_WAIT_L(n) asm volatile("s_waitcnt lgkmcnt(" #n ")" ::: "memory")
; #define PG8_BAR __builtin_amdgcn_s_barrier()
; #define PG8_SCHED __builtin_amdgcn_sched_barrier(0)
; template <class Epi, class Sched, bool ALIGN_EPI = false, bool SP2 = false>
; __device__ __forceinline__ void gemm_phase(PG8_LAS unsigned char* lds, const Gemm g, const Sched& S, const Epi& E) {
;     ...
;             PG8_LDB(B0, 1, 0); PG8_LDB(B1, 1, 1); PG8_SCHED; PG8_LDA(At, 1, 0); PG8_STAGE(PG8_SA(0, 1), a2 + hstep, voffA);
;             PG8_WAIT_V(8); PG8_WAIT_L(0); PG8_BAR; PG8_MMA(0, 0, At, B0); PG8_MMA(0, 1, At, B1); PG8_BAR; PG8_SCHED;
;             PG8_LDA(At, 1, 1); PG8_STAGE(PG8_SB(1, 0), b3, voffB); PG8_STAGE(PG8_SB(1, 1), b3 + hstep, voffB); PG8_STAGE(PG8_SA(1, 0), a3, voffA);
;             PG8_WAIT_V(8); PG8_WAIT_L(0); PG8_BAR; PG8_MMA(1, 0, At, B0); PG8_MMA(1, 1, At, B1); PG8_BAR; PG8_SCHED;
	s_add_u32 s4, s4, 0x40000
	s_addc_u32 s5, s5, 0
	s_mov_b32 m0, s40
	ds_read_b128 v[68:71], v254 offset:32768
	ds_read_b128 v[72:75], v254 offset:33792
	ds_read_b128 v[76:79], v254 offset:34816
	ds_read_b128 v[80:83], v254 offset:35840
	ds_read_b128 v[174:177], v254 offset:49152
	ds_read_b128 v[182:185], v254 offset:50176
	ds_read_b128 v[186:189], v254 offset:51200
	ds_read_b128 v[210:213], v254 offset:52224
	global_load_lds_dwordx4 v168, s[4:5]
	s_mov_b32 m0, s41
	ds_read_b128 v[214:217], v179 offset:32768
	ds_read_b128 v[218:221], v179 offset:33792
	ds_read_b128 v[222:225], v179 offset:34816
	ds_read_b128 v[226:229], v179 offset:35840
	ds_read_b128 v[230:233], v179 offset:36864
	ds_read_b128 v[234:237], v179 offset:37888
	ds_read_b128 v[238:241], v179 offset:38912
	ds_read_b128 v[242:245], v179 offset:39936
	global_load_lds_dwordx4 v164, s[4:5]
	s_waitcnt vmcnt(8) lgkmcnt(0)
	s_barrier
	s_setprio 1
	v_mfma_f32_16x16x32_bf16 v[140:143], v[68:71], v[214:217], v[140:143]
	v_mfma_f32_16x16x32_bf16 v[136:139], v[76:79], v[214:217], v[136:139]
	v_mfma_f32_16x16x32_bf16 v[124:127], v[68:71], v[222:225], v[124:127]
	v_mfma_f32_16x16x32_bf16 v[120:123], v[76:79], v[222:225], v[120:123]
	v_mfma_f32_16x16x32_bf16 v[108:111], v[68:71], v[230:233], v[108:111]
	v_mfma_f32_16x16x32_bf16 v[104:107], v[76:79], v[230:233], v[104:107]
	v_mfma_f32_16x16x32_bf16 v[92:95], v[68:71], v[238:241], v[92:95]
	v_mfma_f32_16x16x32_bf16 v[88:91], v[76:79], v[238:241], v[88:91]
	v_mfma_f32_16x16x32_bf16 v[140:143], v[72:75], v[218:221], v[140:143]
	v_mfma_f32_16x16x32_bf16 v[136:139], v[80:83], v[218:221], v[136:139]
	v_mfma_f32_16x16x32_bf16 v[124:127], v[72:75], v[226:229], v[124:127]
	v_mfma_f32_16x16x32_bf16 v[120:123], v[80:83], v[226:229], v[120:123]
	v_mfma_f32_16x16x32_bf16 v[108:111], v[72:75], v[234:237], v[108:111]
	v_mfma_f32_16x16x32_bf16 v[104:107], v[80:83], v[234:237], v[104:107]
	v_mfma_f32_16x16x32_bf16 v[92:95], v[72:75], v[242:245], v[92:95]
	v_mfma_f32_16x16x32_bf16 v[88:91], v[80:83], v[242:245], v[88:91]
	v_mfma_f32_16x16x32_bf16 v[132:135], v[174:177], v[214:217], v[132:135]
	v_mfma_f32_16x16x32_bf16 v[128:131], v[186:189], v[214:217], v[128:131]
	v_mfma_f32_16x16x32_bf16 v[116:119], v[174:177], v[222:225], v[116:119]
	v_mfma_f32_16x16x32_bf16 v[112:115], v[186:189], v[222:225], v[112:115]
	v_mfma_f32_16x16x32_bf16 v[100:103], v[174:177], v[230:233], v[100:103]
	v_mfma_f32_16x16x32_bf16 v[96:99], v[186:189], v[230:233], v[96:99]
	v_mfma_f32_16x16x32_bf16 v[84:87], v[174:177], v[238:241], v[84:87]
	v_mfma_f32_16x16x32_bf16 v[64:67], v[186:189], v[238:241], v[64:67]
	v_mfma_f32_16x16x32_bf16 v[132:135], v[182:185], v[218:221], v[132:135]
	v_mfma_f32_16x16x32_bf16 v[128:131], v[210:213], v[218:221], v[128:131]
	v_mfma_f32_16x16x32_bf16 v[116:119], v[182:185], v[226:229], v[116:119]
	v_mfma_f32_16x16x32_bf16 v[112:115], v[210:213], v[226:229], v[112:115]
	v_mfma_f32_16x16x32_bf16 v[100:103], v[182:185], v[234:237], v[100:103]
	v_mfma_f32_16x16x32_bf16 v[96:99], v[210:213], v[234:237], v[96:99]
	v_mfma_f32_16x16x32_bf16 v[84:87], v[182:185], v[242:245], v[84:87]
	v_mfma_f32_16x16x32_bf16 v[64:67], v[210:213], v[242:245], v[64:67]
	s_setprio 0
	s_barrier
	s_mov_b32 m0, s45
	s_add_u32 s2, s2, 0x40080
	s_addc_u32 s3, s3, 0
	s_add_u32 s98, s2, 0xfffc0000
	s_addc_u32 s99, s3, -1
	ds_read_b128 v[214:217], v179 offset:49152
	ds_read_b128 v[218:221], v179 offset:50176
	global_load_lds_dwordx4 v166, s[98:99]
	s_mov_b32 m0, s46
	ds_read_b128 v[222:225], v179 offset:51200
	ds_read_b128 v[226:229], v179 offset:52224
	global_load_lds_dwordx4 v162, s[98:99]
	s_mov_b32 m0, s49
	ds_read_b128 v[230:233], v179 offset:53248
	global_load_lds_dwordx4 v166, s[2:3]
	s_mov_b32 m0, s50
	ds_read_b128 v[234:237], v179 offset:54272
	global_load_lds_dwordx4 v162, s[2:3]
	s_mov_b32 m0, s47
	s_add_u32 s100, s4, 0xfffc0080
	s_addc_u32 s101, s5, -1
	ds_read_b128 v[238:241], v179 offset:55296
	global_load_lds_dwordx4 v168, s[100:101]
	s_mov_b32 m0, s48
	ds_read_b128 v[242:245], v179 offset:56320
	global_load_lds_dwordx4 v164, s[100:101]
	s_waitcnt vmcnt(8) lgkmcnt(0)
	s_barrier
	s_setprio 1
	v_mfma_f32_16x16x32_bf16 v[60:63], v[68:71], v[214:217], v[60:63]
	v_mfma_f32_16x16x32_bf16 v[56:59], v[76:79], v[214:217], v[56:59]
	v_mfma_f32_16x16x32_bf16 v[44:47], v[68:71], v[222:225], v[44:47]
	v_mfma_f32_16x16x32_bf16 v[40:43], v[76:79], v[222:225], v[40:43]
	v_mfma_f32_16x16x32_bf16 v[28:31], v[68:71], v[230:233], v[28:31]
	v_mfma_f32_16x16x32_bf16 v[24:27], v[76:79], v[230:233], v[24:27]
	v_mfma_f32_16x16x32_bf16 v[12:15], v[68:71], v[238:241], v[12:15]
	v_mfma_f32_16x16x32_bf16 v[8:11], v[76:79], v[238:241], v[8:11]
	v_mfma_f32_16x16x32_bf16 v[60:63], v[72:75], v[218:221], v[60:63]
	v_mfma_f32_16x16x32_bf16 v[56:59], v[80:83], v[218:221], v[56:59]
	v_mfma_f32_16x16x32_bf16 v[44:47], v[72:75], v[226:229], v[44:47]
	v_mfma_f32_16x16x32_bf16 v[40:43], v[80:83], v[226:229], v[40:43]
	v_mfma_f32_16x16x32_bf16 v[28:31], v[72:75], v[234:237], v[28:31]
	v_mfma_f32_16x16x32_bf16 v[24:27], v[80:83], v[234:237], v[24:27]
	v_mfma_f32_16x16x32_bf16 v[12:15], v[72:75], v[242:245], v[12:15]
	v_mfma_f32_16x16x32_bf16 v[8:11], v[80:83], v[242:245], v[8:11]
	v_mfma_f32_16x16x32_bf16 v[52:55], v[174:177], v[214:217], v[52:55]
	v_mfma_f32_16x16x32_bf16 v[48:51], v[186:189], v[214:217], v[48:51]
	v_mfma_f32_16x16x32_bf16 v[36:39], v[174:177], v[222:225], v[36:39]
	v_mfma_f32_16x16x32_bf16 v[32:35], v[186:189], v[222:225], v[32:35]
	v_mfma_f32_16x16x32_bf16 v[20:23], v[174:177], v[230:233], v[20:23]
	v_mfma_f32_16x16x32_bf16 v[16:19], v[186:189], v[230:233], v[16:19]
	v_mfma_f32_16x16x32_bf16 v[4:7], v[174:177], v[238:241], v[4:7]
	v_mfma_f32_16x16x32_bf16 v[0:3], v[186:189], v[238:241], v[0:3]
	v_mfma_f32_16x16x32_bf16 v[52:55], v[182:185], v[218:221], v[52:55]
	v_mfma_f32_16x16x32_bf16 v[48:51], v[210:213], v[218:221], v[48:51]
	v_mfma_f32_16x16x32_bf16 v[36:39], v[182:185], v[226:229], v[36:39]
	v_mfma_f32_16x16x32_bf16 v[32:35], v[210:213], v[226:229], v[32:35]
	v_mfma_f32_16x16x32_bf16 v[20:23], v[182:185], v[234:237], v[20:23]
	v_mfma_f32_16x16x32_bf16 v[16:19], v[210:213], v[234:237], v[16:19]
	v_mfma_f32_16x16x32_bf16 v[4:7], v[182:185], v[242:245], v[4:7]
	v_mfma_f32_16x16x32_bf16 v[0:3], v[210:213], v[242:245], v[0:3]
	s_setprio 0
	s_barrier
	s_add_i32 s56, s56, 2
	s_add_u32 s0, s0, 0x100
	s_addc_u32 s1, s1, 0
	s_add_u32 s54, s54, 0x100
	s_addc_u32 s55, s55, 0
	s_cmp_gt_u32 s56, 13
; #define PG8_STAGE(bufoff, gbase, voff) do { _Pragma("unroll") for (int _i = 0; _i < 2; ++_i) \
;         __builtin_amdgcn_global_load_lds((const unsigned*)((const char*)(gbase) + (voff)[_i]), (PG8_LAS unsigned*)(lds + (bufoff) + ldsw + _i * 8192), 16, 0, 0); } while (0)
; #define PG8_LDA(dst, b, h) do { _Pragma("unroll") for (int m = 0; m < 4; ++m) _Pragma("unroll") for (int k = 0; k < 2; ++k) dst[m][k] = *(const PG8_LAS bf16x8*)(lds + PG8_SA(b, h) + aoff + m * 2048 + k * 1024); } while (0)
; #define PG8_LDB(dst, b, h) do { _Pragma("unroll") for (int n = 0; n < 2; ++n) _Pragma("unroll") for (int k = 0; k < 2; ++k) dst[n][k] = *(const PG8_LAS bf16x8*)(lds + PG8_SB(b, h) + boff + n * 2048 + k * 1024); } while (0)
; #define PG8_MMA(ai, bj, At, Bt) do { __builtin_amdgcn_s_setprio(1); _Pragma("unroll") for (int m = 0; m < 4; ++m) _Pragma("unroll") for (int n = 0; n < 2; ++n) _Pragma("unroll") for (int k = 0; k < 2; ++k) \
;         acc[ai][bj][m][n] = __builtin_amdgcn_mfma_f32_16x16x32_bf16(Bt[n][k], At[m][k], acc[ai][bj][m][n], 0, 0, 0); __builtin_amdgcn_s_setprio(0); } while (0)
; #define PG8_WAIT_V(n) asm volatile("s_waitcnt vmcnt(" #n ")" ::: "memory")
; #define PG8_WAIT_L(n) asm volatile("s_waitcnt lgkmcnt(" #n ")" ::: "memory")
; #define PG8_BAR __builtin_amdgcn_s_barrier()
; #define PG8_SCHED __builtin_amdgcn_sched_barrier(0)
; template <class Epi, class Sched, bool ALIGN_EPI = false, bool SP2 = false>
; __device__ __forceinline__ void gemm_phase(PG8_LAS unsigned char* lds, const Gemm g, const Sched& S, const Epi& E) {
;     ...
;             PG8_LDB(B0, 0, 0); PG8_LDB(B1, 0, 1); PG8_SCHED; PG8_LDA(At, 0, 0); PG8_STAGE(PG8_SA(1, 1), a1 + hstep, voffA);
;             PG8_WAIT_V(8); PG8_WAIT_L(0); PG8_BAR; PG8_MMA(0, 0, At, B0); PG8_MMA(0, 1, At, B1); PG8_BAR; PG8_SCHED;
;             PG8_LDA(At, 0, 1); PG8_STAGE(PG8_SB(0, 0), b2, voffB); PG8_STAGE(PG8_SB(0, 1), b2 + hstep, voffB); PG8_STAGE(PG8_SA(0, 0), a2, voffA);
;             PG8_WAIT_V(8); PG8_WAIT_L(0); PG8_BAR; PG8_MMA(1, 0, At, B0); PG8_MMA(1, 1, At, B1); PG8_BAR; PG8_SCHED;
.LBB0_327:
	s_add_u32 s2, s0, 0xfffc0080
	s_addc_u32 s3, s1, -1
	s_cmp_eq_u32 s56, 12
	s_cselect_b32 s5, s27, s3
	s_cselect_b32 s4, s52, s2
	s_cselect_b32 s3, s25, s55
	s_cselect_b32 s2, s53, s54
	s_add_i32 m0, s29, 0xc000
	ds_read_b128 v[68:71], v254
	ds_read_b128 v[72:75], v254 offset:1024
	ds_read_b128 v[76:79], v254 offset:2048
	ds_read_b128 v[80:83], v254 offset:3072
	ds_read_b128 v[174:177], v254 offset:16384
	ds_read_b128 v[182:185], v254 offset:17408
	ds_read_b128 v[186:189], v254 offset:18432
	ds_read_b128 v[210:213], v254 offset:19456
	global_load_lds_dwordx4 v170, s[0:1]
	s_add_i32 m0, s29, 0xe000
	ds_read_b128 v[214:217], v179
	ds_read_b128 v[218:221], v179 offset:1024
	ds_read_b128 v[222:225], v179 offset:2048
	ds_read_b128 v[226:229], v179 offset:3072
	ds_read_b128 v[230:233], v179 offset:4096
	ds_read_b128 v[234:237], v179 offset:5120
	ds_read_b128 v[238:241], v179 offset:6144
	ds_read_b128 v[242:245], v179 offset:7168
	global_load_lds_dwordx4 v172, s[0:1]
	s_waitcnt vmcnt(8) lgkmcnt(0)
	s_barrier
	s_setprio 1
	v_mfma_f32_16x16x32_bf16 v[140:143], v[68:71], v[214:217], v[140:143]
	v_mfma_f32_16x16x32_bf16 v[136:139], v[76:79], v[214:217], v[136:139]
	v_mfma_f32_16x16x32_bf16 v[124:127], v[68:71], v[222:225], v[124:127]
	v_mfma_f32_16x16x32_bf16 v[120:123], v[76:79], v[222:225], v[120:123]
	v_mfma_f32_16x16x32_bf16 v[108:111], v[68:71], v[230:233], v[108:111]
	v_mfma_f32_16x16x32_bf16 v[104:107], v[76:79], v[230:233], v[104:107]
	v_mfma_f32_16x16x32_bf16 v[92:95], v[68:71], v[238:241], v[92:95]
	v_mfma_f32_16x16x32_bf16 v[88:91], v[76:79], v[238:241], v[88:91]
	v_mfma_f32_16x16x32_bf16 v[140:143], v[72:75], v[218:221], v[140:143]
	v_mfma_f32_16x16x32_bf16 v[136:139], v[80:83], v[218:221], v[136:139]
	v_mfma_f32_16x16x32_bf16 v[124:127], v[72:75], v[226:229], v[124:127]
	v_mfma_f32_16x16x32_bf16 v[120:123], v[80:83], v[226:229], v[120:123]
	v_mfma_f32_16x16x32_bf16 v[108:111], v[72:75], v[234:237], v[108:111]
	v_mfma_f32_16x16x32_bf16 v[104:107], v[80:83], v[234:237], v[104:107]
	v_mfma_f32_16x16x32_bf16 v[92:95], v[72:75], v[242:245], v[92:95]
	v_mfma_f32_16x16x32_bf16 v[88:91], v[80:83], v[242:245], v[88:91]
	v_mfma_f32_16x16x32_bf16 v[132:135], v[174:177], v[214:217], v[132:135]
	v_mfma_f32_16x16x32_bf16 v[128:131], v[186:189], v[214:217], v[128:131]
	v_mfma_f32_16x16x32_bf16 v[116:119], v[174:177], v[222:225], v[116:119]
	v_mfma_f32_16x16x32_bf16 v[112:115], v[186:189], v[222:225], v[112:115]
	v_mfma_f32_16x16x32_bf16 v[100:103], v[174:177], v[230:233], v[100:103]
	v_mfma_f32_16x16x32_bf16 v[96:99], v[186:189], v[230:233], v[96:99]
	v_mfma_f32_16x16x32_bf16 v[84:87], v[174:177], v[238:241], v[84:87]
	v_mfma_f32_16x16x32_bf16 v[64:67], v[186:189], v[238:241], v[64:67]
	v_mfma_f32_16x16x32_bf16 v[132:135], v[182:185], v[218:221], v[132:135]
	v_mfma_f32_16x16x32_bf16 v[128:131], v[210:213], v[218:221], v[128:131]
	v_mfma_f32_16x16x32_bf16 v[116:119], v[182:185], v[226:229], v[116:119]
	v_mfma_f32_16x16x32_bf16 v[112:115], v[210:213], v[226:229], v[112:115]
	v_mfma_f32_16x16x32_bf16 v[100:103], v[182:185], v[234:237], v[100:103]
	v_mfma_f32_16x16x32_bf16 v[96:99], v[210:213], v[234:237], v[96:99]
	v_mfma_f32_16x16x32_bf16 v[84:87], v[182:185], v[242:245], v[84:87]
	v_mfma_f32_16x16x32_bf16 v[64:67], v[210:213], v[242:245], v[64:67]
	s_setprio 0
	s_barrier
	s_mov_b32 m0, s30
	s_add_u32 s58, s2, 0x40000
	s_addc_u32 s59, s3, 0
	ds_read_b128 v[214:217], v179 offset:16384
	ds_read_b128 v[218:221], v179 offset:17408
	global_load_lds_dwordx4 v166, s[2:3]
	s_mov_b32 m0, s31
	ds_read_b128 v[222:225], v179 offset:18432
	ds_read_b128 v[226:229], v179 offset:19456
	global_load_lds_dwordx4 v162, s[2:3]
	s_mov_b32 m0, s33
	ds_read_b128 v[230:233], v179 offset:20480
	global_load_lds_dwordx4 v166, s[58:59]
	s_mov_b32 m0, s34
	ds_read_b128 v[234:237], v179 offset:21504
	global_load_lds_dwordx4 v162, s[58:59]
	s_mov_b32 m0, s29
	ds_read_b128 v[238:241], v179 offset:22528
	global_load_lds_dwordx4 v168, s[4:5]
	s_mov_b32 m0, s35
	ds_read_b128 v[242:245], v179 offset:23552
	global_load_lds_dwordx4 v164, s[4:5]
	s_waitcnt vmcnt(8) lgkmcnt(0)
	s_barrier
	s_setprio 1
	v_mfma_f32_16x16x32_bf16 v[60:63], v[68:71], v[214:217], v[60:63]
	v_mfma_f32_16x16x32_bf16 v[56:59], v[76:79], v[214:217], v[56:59]
	v_mfma_f32_16x16x32_bf16 v[44:47], v[68:71], v[222:225], v[44:47]
	v_mfma_f32_16x16x32_bf16 v[40:43], v[76:79], v[222:225], v[40:43]
	v_mfma_f32_16x16x32_bf16 v[28:31], v[68:71], v[230:233], v[28:31]
	v_mfma_f32_16x16x32_bf16 v[24:27], v[76:79], v[230:233], v[24:27]
	v_mfma_f32_16x16x32_bf16 v[12:15], v[68:71], v[238:241], v[12:15]
	v_mfma_f32_16x16x32_bf16 v[8:11], v[76:79], v[238:241], v[8:11]
	v_mfma_f32_16x16x32_bf16 v[60:63], v[72:75], v[218:221], v[60:63]
	v_mfma_f32_16x16x32_bf16 v[56:59], v[80:83], v[218:221], v[56:59]
	v_mfma_f32_16x16x32_bf16 v[44:47], v[72:75], v[226:229], v[44:47]
	v_mfma_f32_16x16x32_bf16 v[40:43], v[80:83], v[226:229], v[40:43]
	v_mfma_f32_16x16x32_bf16 v[28:31], v[72:75], v[234:237], v[28:31]
	v_mfma_f32_16x16x32_bf16 v[24:27], v[80:83], v[234:237], v[24:27]
	v_mfma_f32_16x16x32_bf16 v[12:15], v[72:75], v[242:245], v[12:15]
	v_mfma_f32_16x16x32_bf16 v[8:11], v[80:83], v[242:245], v[8:11]
	v_mfma_f32_16x16x32_bf16 v[52:55], v[174:177], v[214:217], v[52:55]
	v_mfma_f32_16x16x32_bf16 v[48:51], v[186:189], v[214:217], v[48:51]
	v_mfma_f32_16x16x32_bf16 v[36:39], v[174:177], v[222:225], v[36:39]
	v_mfma_f32_16x16x32_bf16 v[32:35], v[186:189], v[222:225], v[32:35]
	v_mfma_f32_16x16x32_bf16 v[20:23], v[174:177], v[230:233], v[20:23]
	v_mfma_f32_16x16x32_bf16 v[16:19], v[186:189], v[230:233], v[16:19]
	v_mfma_f32_16x16x32_bf16 v[4:7], v[174:177], v[238:241], v[4:7]
	v_mfma_f32_16x16x32_bf16 v[0:3], v[186:189], v[238:241], v[0:3]
	v_mfma_f32_16x16x32_bf16 v[52:55], v[182:185], v[218:221], v[52:55]
	v_mfma_f32_16x16x32_bf16 v[48:51], v[210:213], v[218:221], v[48:51]
	v_mfma_f32_16x16x32_bf16 v[36:39], v[182:185], v[226:229], v[36:39]
	v_mfma_f32_16x16x32_bf16 v[32:35], v[210:213], v[226:229], v[32:35]
	v_mfma_f32_16x16x32_bf16 v[20:23], v[182:185], v[234:237], v[20:23]
	v_mfma_f32_16x16x32_bf16 v[16:19], v[210:213], v[234:237], v[16:19]
	v_mfma_f32_16x16x32_bf16 v[4:7], v[182:185], v[242:245], v[4:7]
	v_mfma_f32_16x16x32_bf16 v[0:3], v[210:213], v[242:245], v[0:3]
	s_setprio 0
	s_barrier
; #define PG8_STAGE(bufoff, gbase, voff) do { _Pragma("unroll") for (int _i = 0; _i < 2; ++_i) \
;         __builtin_amdgcn_global_load_lds((const unsigned*)((const char*)(gbase) + (voff)[_i]), (PG8_LAS unsigned*)(lds + (bufoff) + ldsw + _i * 8192), 16, 0, 0); } while (0)
; #define PG8_LDA(dst, b, h) do { _Pragma("unroll") for (int m = 0; m < 4; ++m) _Pragma("unroll") for (int k = 0; k < 2; ++k) dst[m][k] = *(const PG8_LAS bf16x8*)(lds + PG8_SA(b, h) + aoff + m * 2048 + k * 1024); } while (0)
; #define PG8_LDB(dst, b, h) do { _Pragma("unroll") for (int n = 0; n < 2; ++n) _Pragma("unroll") for (int k = 0; k < 2; ++k) dst[n][k] = *(const PG8_LAS bf16x8*)(lds + PG8_SB(b, h) + boff + n * 2048 + k * 1024); } while (0)
; #define PG8_MMA(ai, bj, At, Bt) do { __builtin_amdgcn_s_setprio(1); _Pragma("unroll") for (int m = 0; m < 4; ++m) _Pragma("unroll") for (int n = 0; n < 2; ++n) _Pragma("unroll") for (int k = 0; k < 2; ++k) \
;         acc[ai][bj][m][n] = __builtin_amdgcn_mfma_f32_16x16x32_bf16(Bt[n][k], At[m][k], acc[ai][bj][m][n], 0, 0, 0); __builtin_amdgcn_s_setprio(0); } while (0)
; #define PG8_WAIT_V(n) asm volatile("s_waitcnt vmcnt(" #n ")" ::: "memory")
; #define PG8_WAIT_L(n) asm volatile("s_waitcnt lgkmcnt(" #n ")" ::: "memory")
; #define PG8_BAR __builtin_amdgcn_s_barrier()
; #define PG8_SCHED __builtin_amdgcn_sched_barrier(0)
; template <class Epi, class Sched, bool ALIGN_EPI = false, bool SP2 = false>
; __device__ __forceinline__ void gemm_phase(PG8_LAS unsigned char* lds, const Gemm g, const Sched& S, const Epi& E) {
;     ...
;             PG8_LDB(B0, 1, 0); PG8_LDB(B1, 1, 1); PG8_SCHED; PG8_LDA(At, 1, 0); PG8_STAGE(PG8_SA(0, 1), a2 + hstep, voffA);
;             PG8_WAIT_V(8); PG8_WAIT_L(0); PG8_BAR; PG8_MMA(0, 0, At, B0); PG8_MMA(0, 1, At, B1); PG8_BAR; PG8_SCHED;
;             PG8_LDA(At, 1, 1); PG8_STAGE(PG8_SB(1, 0), b3, voffB); PG8_STAGE(PG8_SB(1, 1), b3 + hstep, voffB); PG8_STAGE(PG8_SA(1, 0), a3, voffA);
;             PG8_WAIT_V(8); PG8_WAIT_L(0); PG8_BAR; PG8_MMA(1, 0, At, B0); PG8_MMA(1, 1, At, B1); PG8_BAR; PG8_SCHED;
;     ...
;         if constexpr (ALIGN_EPI) { if (wr == 0) PG8_BAR; }
	s_add_u32 s4, s4, 0x40000
	s_addc_u32 s5, s5, 0
	s_mov_b32 m0, s40
	ds_read_b128 v[68:71], v254 offset:32768
	ds_read_b128 v[72:75], v254 offset:33792
	ds_read_b128 v[76:79], v254 offset:34816
	ds_read_b128 v[80:83], v254 offset:35840
	ds_read_b128 v[174:177], v254 offset:49152
	ds_read_b128 v[182:185], v254 offset:50176
	ds_read_b128 v[186:189], v254 offset:51200
	ds_read_b128 v[210:213], v254 offset:52224
	global_load_lds_dwordx4 v168, s[4:5]
	s_mov_b32 m0, s41
	ds_read_b128 v[214:217], v179 offset:32768
	ds_read_b128 v[218:221], v179 offset:33792
	ds_read_b128 v[222:225], v179 offset:34816
	ds_read_b128 v[226:229], v179 offset:35840
	ds_read_b128 v[230:233], v179 offset:36864
	ds_read_b128 v[234:237], v179 offset:37888
	ds_read_b128 v[238:241], v179 offset:38912
	ds_read_b128 v[242:245], v179 offset:39936
	global_load_lds_dwordx4 v164, s[4:5]
	s_waitcnt vmcnt(8) lgkmcnt(0)
	s_barrier
	s_setprio 1
	v_mfma_f32_16x16x32_bf16 v[140:143], v[68:71], v[214:217], v[140:143]
	v_mfma_f32_16x16x32_bf16 v[136:139], v[76:79], v[214:217], v[136:139]
	v_mfma_f32_16x16x32_bf16 v[124:127], v[68:71], v[222:225], v[124:127]
	v_mfma_f32_16x16x32_bf16 v[120:123], v[76:79], v[222:225], v[120:123]
	v_mfma_f32_16x16x32_bf16 v[108:111], v[68:71], v[230:233], v[108:111]
	v_mfma_f32_16x16x32_bf16 v[104:107], v[76:79], v[230:233], v[104:107]
	v_mfma_f32_16x16x32_bf16 v[92:95], v[68:71], v[238:241], v[92:95]
	v_mfma_f32_16x16x32_bf16 v[88:91], v[76:79], v[238:241], v[88:91]
	v_mfma_f32_16x16x32_bf16 v[140:143], v[72:75], v[218:221], v[140:143]
	v_mfma_f32_16x16x32_bf16 v[136:139], v[80:83], v[218:221], v[136:139]
	v_mfma_f32_16x16x32_bf16 v[124:127], v[72:75], v[226:229], v[124:127]
	v_mfma_f32_16x16x32_bf16 v[120:123], v[80:83], v[226:229], v[120:123]
	v_mfma_f32_16x16x32_bf16 v[108:111], v[72:75], v[234:237], v[108:111]
	v_mfma_f32_16x16x32_bf16 v[104:107], v[80:83], v[234:237], v[104:107]
	v_mfma_f32_16x16x32_bf16 v[92:95], v[72:75], v[242:245], v[92:95]
	v_mfma_f32_16x16x32_bf16 v[88:91], v[80:83], v[242:245], v[88:91]
	v_mfma_f32_16x16x32_bf16 v[132:135], v[174:177], v[214:217], v[132:135]
	v_mfma_f32_16x16x32_bf16 v[128:131], v[186:189], v[214:217], v[128:131]
	v_mfma_f32_16x16x32_bf16 v[116:119], v[174:177], v[222:225], v[116:119]
	v_mfma_f32_16x16x32_bf16 v[112:115], v[186:189], v[222:225], v[112:115]
	v_mfma_f32_16x16x32_bf16 v[100:103], v[174:177], v[230:233], v[100:103]
	v_mfma_f32_16x16x32_bf16 v[96:99], v[186:189], v[230:233], v[96:99]
	v_mfma_f32_16x16x32_bf16 v[84:87], v[174:177], v[238:241], v[84:87]
	v_mfma_f32_16x16x32_bf16 v[64:67], v[186:189], v[238:241], v[64:67]
	v_mfma_f32_16x16x32_bf16 v[132:135], v[182:185], v[218:221], v[132:135]
	v_mfma_f32_16x16x32_bf16 v[128:131], v[210:213], v[218:221], v[128:131]
	v_mfma_f32_16x16x32_bf16 v[116:119], v[182:185], v[226:229], v[116:119]
	v_mfma_f32_16x16x32_bf16 v[112:115], v[210:213], v[226:229], v[112:115]
	v_mfma_f32_16x16x32_bf16 v[100:103], v[182:185], v[234:237], v[100:103]
	v_mfma_f32_16x16x32_bf16 v[96:99], v[210:213], v[234:237], v[96:99]
	v_mfma_f32_16x16x32_bf16 v[84:87], v[182:185], v[242:245], v[84:87]
	v_mfma_f32_16x16x32_bf16 v[64:67], v[210:213], v[242:245], v[64:67]
	s_setprio 0
	s_barrier
	s_mov_b32 m0, s45
	s_add_u32 s2, s2, 0x40080
	s_addc_u32 s3, s3, 0
	s_add_u32 s98, s2, 0xfffc0000
	s_addc_u32 s99, s3, -1
	ds_read_b128 v[214:217], v179 offset:49152
	ds_read_b128 v[218:221], v179 offset:50176
	global_load_lds_dwordx4 v166, s[98:99]
	s_mov_b32 m0, s46
	ds_read_b128 v[222:225], v179 offset:51200
	ds_read_b128 v[226:229], v179 offset:52224
	global_load_lds_dwordx4 v162, s[98:99]
	s_mov_b32 m0, s49
	ds_read_b128 v[230:233], v179 offset:53248
	global_load_lds_dwordx4 v166, s[2:3]
	s_mov_b32 m0, s50
	ds_read_b128 v[234:237], v179 offset:54272
	global_load_lds_dwordx4 v162, s[2:3]
	s_mov_b32 m0, s47
	s_add_u32 s100, s4, 0xfffc0080
	s_addc_u32 s101, s5, -1
	ds_read_b128 v[238:241], v179 offset:55296
	global_load_lds_dwordx4 v168, s[100:101]
	s_mov_b32 m0, s48
	ds_read_b128 v[242:245], v179 offset:56320
	global_load_lds_dwordx4 v164, s[100:101]
	s_waitcnt vmcnt(8) lgkmcnt(0)
	s_barrier
	s_setprio 1
	v_mfma_f32_16x16x32_bf16 v[60:63], v[68:71], v[214:217], v[60:63]
	v_mfma_f32_16x16x32_bf16 v[56:59], v[76:79], v[214:217], v[56:59]
	v_mfma_f32_16x16x32_bf16 v[44:47], v[68:71], v[222:225], v[44:47]
	v_mfma_f32_16x16x32_bf16 v[40:43], v[76:79], v[222:225], v[40:43]
	v_mfma_f32_16x16x32_bf16 v[28:31], v[68:71], v[230:233], v[28:31]
	v_mfma_f32_16x16x32_bf16 v[24:27], v[76:79], v[230:233], v[24:27]
	v_mfma_f32_16x16x32_bf16 v[12:15], v[68:71], v[238:241], v[12:15]
	v_mfma_f32_16x16x32_bf16 v[8:11], v[76:79], v[238:241], v[8:11]
	v_mfma_f32_16x16x32_bf16 v[60:63], v[72:75], v[218:221], v[60:63]
	v_mfma_f32_16x16x32_bf16 v[56:59], v[80:83], v[218:221], v[56:59]
	v_mfma_f32_16x16x32_bf16 v[44:47], v[72:75], v[226:229], v[44:47]
	v_mfma_f32_16x16x32_bf16 v[40:43], v[80:83], v[226:229], v[40:43]
	v_mfma_f32_16x16x32_bf16 v[28:31], v[72:75], v[234:237], v[28:31]
	v_mfma_f32_16x16x32_bf16 v[24:27], v[80:83], v[234:237], v[24:27]
	v_mfma_f32_16x16x32_bf16 v[12:15], v[72:75], v[242:245], v[12:15]
	v_mfma_f32_16x16x32_bf16 v[8:11], v[80:83], v[242:245], v[8:11]
	v_mfma_f32_16x16x32_bf16 v[52:55], v[174:177], v[214:217], v[52:55]
	v_mfma_f32_16x16x32_bf16 v[48:51], v[186:189], v[214:217], v[48:51]
	v_mfma_f32_16x16x32_bf16 v[36:39], v[174:177], v[222:225], v[36:39]
	v_mfma_f32_16x16x32_bf16 v[32:35], v[186:189], v[222:225], v[32:35]
	v_mfma_f32_16x16x32_bf16 v[20:23], v[174:177], v[230:233], v[20:23]
	v_mfma_f32_16x16x32_bf16 v[16:19], v[186:189], v[230:233], v[16:19]
	v_mfma_f32_16x16x32_bf16 v[4:7], v[174:177], v[238:241], v[4:7]
	v_mfma_f32_16x16x32_bf16 v[0:3], v[186:189], v[238:241], v[0:3]
	v_mfma_f32_16x16x32_bf16 v[52:55], v[182:185], v[218:221], v[52:55]
	v_mfma_f32_16x16x32_bf16 v[48:51], v[210:213], v[218:221], v[48:51]
	v_mfma_f32_16x16x32_bf16 v[36:39], v[182:185], v[226:229], v[36:39]
	v_mfma_f32_16x16x32_bf16 v[32:35], v[210:213], v[226:229], v[32:35]
	v_mfma_f32_16x16x32_bf16 v[20:23], v[182:185], v[234:237], v[20:23]
	v_mfma_f32_16x16x32_bf16 v[16:19], v[210:213], v[234:237], v[16:19]
	v_mfma_f32_16x16x32_bf16 v[4:7], v[182:185], v[242:245], v[4:7]
	v_mfma_f32_16x16x32_bf16 v[0:3], v[210:213], v[242:245], v[0:3]
	s_setprio 0
	s_barrier
	s_add_i32 s56, s56, 2
	s_add_u32 s0, s0, 0x100
	s_addc_u32 s1, s1, 0
	s_add_u32 s54, s54, 0x100
	s_addc_u32 s55, s55, 0
	s_cmp_gt_u32 s56, 13
	s_cbranch_scc0 .LBB0_327
	s_and_b64 vcc, exec, s[22:23]
	s_cbranch_vccz .LBB0_330
	s_barrier

; #define PG8_STAGE(bufoff, gbase, voff) do { _Pragma("unroll") for (int _i = 0; _i < 2; ++_i) \
;         __builtin_amdgcn_global_load_lds((const unsigned*)((const char*)(gbase) + (voff)[_i]), (PG8_LAS unsigned*)(lds + (bufoff) + ldsw + _i * 8192), 16, 0, 0); } while (0)
; #define PG8_LDA(dst, b, h) do { _Pragma("unroll") for (int m = 0; m < 4; ++m) _Pragma("unroll") for (int k = 0; k < 2; ++k) dst[m][k] = *(const PG8_LAS bf16x8*)(lds + PG8_SA(b, h) + aoff + m * 2048 + k * 1024); } while (0)
; #define PG8_LDB(dst, b, h) do { _Pragma("unroll") for (int n = 0; n < 2; ++n) _Pragma("unroll") for (int k = 0; k < 2; ++k) dst[n][k] = *(const PG8_LAS bf16x8*)(lds + PG8_SB(b, h) + boff + n * 2048 + k * 1024); } while (0)
; #define PG8_MMA(ai, bj, At, Bt) do { __builtin_amdgcn_s_setprio(1); _Pragma("unroll") for (int m = 0; m < 4; ++m) _Pragma("unroll") for (int n = 0; n < 2; ++n) _Pragma("unroll") for (int k = 0; k < 2; ++k) \
;         acc[ai][bj][m][n] = __builtin_amdgcn_mfma_f32_16x16x32_bf16(Bt[n][k], At[m][k], acc[ai][bj][m][n], 0, 0, 0); __builtin_amdgcn_s_setprio(0); } while (0)
; #define PG8_WAIT_V(n) asm volatile("s_waitcnt vmcnt(" #n ")" ::: "memory")
; #define PG8_WAIT_L(n) asm volatile("s_waitcnt lgkmcnt(" #n ")" ::: "memory")
; #define PG8_BAR __builtin_amdgcn_s_barrier()
; #define PG8_SCHED __builtin_amdgcn_sched_barrier(0)
; template <class Epi, class Sched, bool ALIGN_EPI = false, bool SP2 = false>
; __device__ __forceinline__ void gemm_phase(PG8_LAS unsigned char* lds, const Gemm g, const Sched& S, const Epi& E) {
;     ...
;             PG8_LDB(B0, 0, 0); PG8_LDB(B1, 0, 1); PG8_SCHED; PG8_LDA(At, 0, 0); PG8_STAGE(PG8_SA(1, 1), a1 + hstep, voffA);
;             PG8_WAIT_V(8); PG8_WAIT_L(0); PG8_BAR; PG8_MMA(0, 0, At, B0); PG8_MMA(0, 1, At, B1); PG8_BAR; PG8_SCHED;
;             PG8_LDA(At, 0, 1); PG8_STAGE(PG8_SB(0, 0), b2, voffB); PG8_STAGE(PG8_SB(0, 1), b2 + hstep, voffB); PG8_STAGE(PG8_SA(0, 0), a2, voffA);
;             PG8_WAIT_V(8); PG8_WAIT_L(0); PG8_BAR; PG8_MMA(1, 0, At, B0); PG8_MMA(1, 1, At, B1); PG8_BAR; PG8_SCHED;
.Lup_peel:
	s_add_u32 s16, s14, 0xfffc0080
	s_addc_u32 s17, s15, -1
	s_cmp_eq_u32 s53, 12
	s_cselect_b32 s19, s7, s17
	s_cselect_b32 s18, s49, s16
	s_cselect_b32 s17, s5, s52
	s_cselect_b32 s16, s50, s51
	s_mov_b32 m0, s43
	ds_read_b128 v[140:143], v254
	ds_read_b128 v[168:171], v254 offset:1024
	ds_read_b128 v[172:175], v254 offset:2048
	ds_read_b128 v[176:179], v254 offset:3072
	ds_read_b128 v[180:183], v254 offset:16384
	ds_read_b128 v[184:187], v254 offset:17408
	ds_read_b128 v[188:191], v254 offset:18432
	ds_read_b128 v[210:213], v254 offset:19456
	global_load_lds_dwordx4 v136, s[14:15]
	s_mov_b32 m0, s44
	ds_read_b128 v[214:217], v165
	ds_read_b128 v[218:221], v165 offset:1024
	ds_read_b128 v[222:225], v165 offset:2048
	ds_read_b128 v[226:229], v165 offset:3072
	ds_read_b128 v[230:233], v165 offset:4096
	ds_read_b128 v[234:237], v165 offset:5120
	ds_read_b128 v[238:241], v165 offset:6144
	ds_read_b128 v[242:245], v165 offset:7168
	global_load_lds_dwordx4 v138, s[14:15]
	s_waitcnt vmcnt(8) lgkmcnt(0)
	s_barrier
	s_setprio 1
	v_mfma_f32_16x16x32_bf16 v[124:127], v[140:143], v[214:217], 0
	v_mfma_f32_16x16x32_bf16 v[116:119], v[172:175], v[214:217], 0
	v_mfma_f32_16x16x32_bf16 v[108:111], v[140:143], v[222:225], 0
	v_mfma_f32_16x16x32_bf16 v[100:103], v[172:175], v[222:225], 0
	v_mfma_f32_16x16x32_bf16 v[92:95], v[140:143], v[230:233], 0
	v_mfma_f32_16x16x32_bf16 v[84:87], v[172:175], v[230:233], 0
	v_mfma_f32_16x16x32_bf16 v[76:79], v[140:143], v[238:241], 0
	v_mfma_f32_16x16x32_bf16 v[68:71], v[172:175], v[238:241], 0
	v_mfma_f32_16x16x32_bf16 v[124:127], v[168:171], v[218:221], v[124:127]
	v_mfma_f32_16x16x32_bf16 v[116:119], v[176:179], v[218:221], v[116:119]
	v_mfma_f32_16x16x32_bf16 v[108:111], v[168:171], v[226:229], v[108:111]
	v_mfma_f32_16x16x32_bf16 v[100:103], v[176:179], v[226:229], v[100:103]
	v_mfma_f32_16x16x32_bf16 v[92:95], v[168:171], v[234:237], v[92:95]
	v_mfma_f32_16x16x32_bf16 v[84:87], v[176:179], v[234:237], v[84:87]
	v_mfma_f32_16x16x32_bf16 v[76:79], v[168:171], v[242:245], v[76:79]
	v_mfma_f32_16x16x32_bf16 v[68:71], v[176:179], v[242:245], v[68:71]
	v_mfma_f32_16x16x32_bf16 v[120:123], v[180:183], v[214:217], 0
	v_mfma_f32_16x16x32_bf16 v[112:115], v[188:191], v[214:217], 0
	v_mfma_f32_16x16x32_bf16 v[104:107], v[180:183], v[222:225], 0
	v_mfma_f32_16x16x32_bf16 v[96:99], v[188:191], v[222:225], 0
	v_mfma_f32_16x16x32_bf16 v[88:91], v[180:183], v[230:233], 0
	v_mfma_f32_16x16x32_bf16 v[80:83], v[188:191], v[230:233], 0
	v_mfma_f32_16x16x32_bf16 v[72:75], v[180:183], v[238:241], 0
	v_mfma_f32_16x16x32_bf16 v[64:67], v[188:191], v[238:241], 0
	v_mfma_f32_16x16x32_bf16 v[120:123], v[184:187], v[218:221], v[120:123]
	v_mfma_f32_16x16x32_bf16 v[112:115], v[210:213], v[218:221], v[112:115]
	v_mfma_f32_16x16x32_bf16 v[104:107], v[184:187], v[226:229], v[104:107]
	v_mfma_f32_16x16x32_bf16 v[96:99], v[210:213], v[226:229], v[96:99]
	v_mfma_f32_16x16x32_bf16 v[88:91], v[184:187], v[234:237], v[88:91]
	v_mfma_f32_16x16x32_bf16 v[80:83], v[210:213], v[234:237], v[80:83]
	v_mfma_f32_16x16x32_bf16 v[72:75], v[184:187], v[242:245], v[72:75]
	v_mfma_f32_16x16x32_bf16 v[64:67], v[210:213], v[242:245], v[64:67]
	s_setprio 0
	s_barrier
	s_mov_b32 m0, s27
	s_add_u32 s54, s16, 0x40000
	s_addc_u32 s55, s17, 0
	ds_read_b128 v[214:217], v165 offset:16384
	ds_read_b128 v[218:221], v165 offset:17408
	global_load_lds_dwordx4 v132, s[16:17]
	s_mov_b32 m0, s28
	ds_read_b128 v[222:225], v165 offset:18432
	ds_read_b128 v[226:229], v165 offset:19456
	global_load_lds_dwordx4 v128, s[16:17]
	s_mov_b32 m0, s29
	ds_read_b128 v[230:233], v165 offset:20480
	global_load_lds_dwordx4 v132, s[54:55]
	s_mov_b32 m0, s30
	ds_read_b128 v[234:237], v165 offset:21504
	global_load_lds_dwordx4 v128, s[54:55]
	s_mov_b32 m0, s22
	ds_read_b128 v[238:241], v165 offset:22528
	global_load_lds_dwordx4 v134, s[18:19]
	s_mov_b32 m0, s31
	ds_read_b128 v[242:245], v165 offset:23552
	global_load_lds_dwordx4 v130, s[18:19]
	s_waitcnt vmcnt(8) lgkmcnt(0)
	s_barrier
	s_setprio 1
	v_mfma_f32_16x16x32_bf16 v[60:63], v[140:143], v[214:217], 0
	v_mfma_f32_16x16x32_bf16 v[52:55], v[172:175], v[214:217], 0
	v_mfma_f32_16x16x32_bf16 v[44:47], v[140:143], v[222:225], 0
	v_mfma_f32_16x16x32_bf16 v[36:39], v[172:175], v[222:225], 0
	v_mfma_f32_16x16x32_bf16 v[28:31], v[140:143], v[230:233], 0
	v_mfma_f32_16x16x32_bf16 v[20:23], v[172:175], v[230:233], 0
	v_mfma_f32_16x16x32_bf16 v[12:15], v[140:143], v[238:241], 0
	v_mfma_f32_16x16x32_bf16 v[4:7], v[172:175], v[238:241], 0
	v_mfma_f32_16x16x32_bf16 v[60:63], v[168:171], v[218:221], v[60:63]
	v_mfma_f32_16x16x32_bf16 v[52:55], v[176:179], v[218:221], v[52:55]
	v_mfma_f32_16x16x32_bf16 v[44:47], v[168:171], v[226:229], v[44:47]
	v_mfma_f32_16x16x32_bf16 v[36:39], v[176:179], v[226:229], v[36:39]
	v_mfma_f32_16x16x32_bf16 v[28:31], v[168:171], v[234:237], v[28:31]
	v_mfma_f32_16x16x32_bf16 v[20:23], v[176:179], v[234:237], v[20:23]
	v_mfma_f32_16x16x32_bf16 v[12:15], v[168:171], v[242:245], v[12:15]
	v_mfma_f32_16x16x32_bf16 v[4:7], v[176:179], v[242:245], v[4:7]
	v_mfma_f32_16x16x32_bf16 v[56:59], v[180:183], v[214:217], 0
	v_mfma_f32_16x16x32_bf16 v[48:51], v[188:191], v[214:217], 0
	v_mfma_f32_16x16x32_bf16 v[40:43], v[180:183], v[222:225], 0
	v_mfma_f32_16x16x32_bf16 v[32:35], v[188:191], v[222:225], 0
	v_mfma_f32_16x16x32_bf16 v[24:27], v[180:183], v[230:233], 0
	v_mfma_f32_16x16x32_bf16 v[16:19], v[188:191], v[230:233], 0
	v_mfma_f32_16x16x32_bf16 v[8:11], v[180:183], v[238:241], 0
	v_mfma_f32_16x16x32_bf16 v[0:3], v[188:191], v[238:241], 0
	v_mfma_f32_16x16x32_bf16 v[56:59], v[184:187], v[218:221], v[56:59]
	v_mfma_f32_16x16x32_bf16 v[48:51], v[210:213], v[218:221], v[48:51]
	v_mfma_f32_16x16x32_bf16 v[40:43], v[184:187], v[226:229], v[40:43]
	v_mfma_f32_16x16x32_bf16 v[32:35], v[210:213], v[226:229], v[32:35]
	v_mfma_f32_16x16x32_bf16 v[24:27], v[184:187], v[234:237], v[24:27]
	v_mfma_f32_16x16x32_bf16 v[16:19], v[210:213], v[234:237], v[16:19]
	v_mfma_f32_16x16x32_bf16 v[8:11], v[184:187], v[242:245], v[8:11]
	v_mfma_f32_16x16x32_bf16 v[0:3], v[210:213], v[242:245], v[0:3]
	s_setprio 0
	s_barrier
; #define PG8_STAGE(bufoff, gbase, voff) do { _Pragma("unroll") for (int _i = 0; _i < 2; ++_i) \
;         __builtin_amdgcn_global_load_lds((const unsigned*)((const char*)(gbase) + (voff)[_i]), (PG8_LAS unsigned*)(lds + (bufoff) + ldsw + _i * 8192), 16, 0, 0); } while (0)
; #define PG8_LDA(dst, b, h) do { _Pragma("unroll") for (int m = 0; m < 4; ++m) _Pragma("unroll") for (int k = 0; k < 2; ++k) dst[m][k] = *(const PG8_LAS bf16x8*)(lds + PG8_SA(b, h) + aoff + m * 2048 + k * 1024); } while (0)
; #define PG8_LDB(dst, b, h) do { _Pragma("unroll") for (int n = 0; n < 2; ++n) _Pragma("unroll") for (int k = 0; k < 2; ++k) dst[n][k] = *(const PG8_LAS bf16x8*)(lds + PG8_SB(b, h) + boff + n * 2048 + k * 1024); } while (0)
; #define PG8_MMA(ai, bj, At, Bt) do { __builtin_amdgcn_s_setprio(1); _Pragma("unroll") for (int m = 0; m < 4; ++m) _Pragma("unroll") for (int n = 0; n < 2; ++n) _Pragma("unroll") for (int k = 0; k < 2; ++k) \
;         acc[ai][bj][m][n] = __builtin_amdgcn_mfma_f32_16x16x32_bf16(Bt[n][k], At[m][k], acc[ai][bj][m][n], 0, 0, 0); __builtin_amdgcn_s_setprio(0); } while (0)
; #define PG8_WAIT_V(n) asm volatile("s_waitcnt vmcnt(" #n ")" ::: "memory")
; #define PG8_WAIT_L(n) asm volatile("s_waitcnt lgkmcnt(" #n ")" ::: "memory")
; #define PG8_BAR __builtin_amdgcn_s_barrier()
; #define PG8_SCHED __builtin_amdgcn_sched_barrier(0)
; template <class Epi, class Sched, bool ALIGN_EPI = false, bool SP2 = false>
; __device__ __forceinline__ void gemm_phase(PG8_LAS unsigned char* lds, const Gemm g, const Sched& S, const Epi& E) {
;     ...
;             PG8_LDB(B0, 1, 0); PG8_LDB(B1, 1, 1); PG8_SCHED; PG8_LDA(At, 1, 0); PG8_STAGE(PG8_SA(0, 1), a2 + hstep, voffA);
;             PG8_WAIT_V(8); PG8_WAIT_L(0); PG8_BAR; PG8_MMA(0, 0, At, B0); PG8_MMA(0, 1, At, B1); PG8_BAR; PG8_SCHED;
;             PG8_LDA(At, 1, 1); PG8_STAGE(PG8_SB(1, 0), b3, voffB); PG8_STAGE(PG8_SB(1, 1), b3 + hstep, voffB); PG8_STAGE(PG8_SA(1, 0), a3, voffA);
;             PG8_WAIT_V(8); PG8_WAIT_L(0); PG8_BAR; PG8_MMA(1, 0, At, B0); PG8_MMA(1, 1, At, B1); PG8_BAR; PG8_SCHED;
	s_add_u32 s18, s18, 0x40000
	s_addc_u32 s19, s19, 0
	s_mov_b32 m0, s33
	ds_read_b128 v[140:143], v254 offset:32768
	ds_read_b128 v[168:171], v254 offset:33792
	ds_read_b128 v[172:175], v254 offset:34816
	ds_read_b128 v[176:179], v254 offset:35840
	ds_read_b128 v[180:183], v254 offset:49152
	ds_read_b128 v[184:187], v254 offset:50176
	ds_read_b128 v[188:191], v254 offset:51200
	ds_read_b128 v[210:213], v254 offset:52224
	global_load_lds_dwordx4 v134, s[18:19]
	s_mov_b32 m0, s34
	ds_read_b128 v[214:217], v165 offset:32768
	ds_read_b128 v[218:221], v165 offset:33792
	ds_read_b128 v[222:225], v165 offset:34816
	ds_read_b128 v[226:229], v165 offset:35840
	ds_read_b128 v[230:233], v165 offset:36864
	ds_read_b128 v[234:237], v165 offset:37888
	ds_read_b128 v[238:241], v165 offset:38912
	ds_read_b128 v[242:245], v165 offset:39936
	global_load_lds_dwordx4 v130, s[18:19]
	s_waitcnt vmcnt(8) lgkmcnt(0)
	s_barrier
	s_setprio 1
	v_mfma_f32_16x16x32_bf16 v[124:127], v[140:143], v[214:217], v[124:127]
	v_mfma_f32_16x16x32_bf16 v[116:119], v[172:175], v[214:217], v[116:119]
	v_mfma_f32_16x16x32_bf16 v[108:111], v[140:143], v[222:225], v[108:111]
	v_mfma_f32_16x16x32_bf16 v[100:103], v[172:175], v[222:225], v[100:103]
	v_mfma_f32_16x16x32_bf16 v[92:95], v[140:143], v[230:233], v[92:95]
	v_mfma_f32_16x16x32_bf16 v[84:87], v[172:175], v[230:233], v[84:87]
	v_mfma_f32_16x16x32_bf16 v[76:79], v[140:143], v[238:241], v[76:79]
	v_mfma_f32_16x16x32_bf16 v[68:71], v[172:175], v[238:241], v[68:71]
	v_mfma_f32_16x16x32_bf16 v[124:127], v[168:171], v[218:221], v[124:127]
	v_mfma_f32_16x16x32_bf16 v[116:119], v[176:179], v[218:221], v[116:119]
	v_mfma_f32_16x16x32_bf16 v[108:111], v[168:171], v[226:229], v[108:111]
	v_mfma_f32_16x16x32_bf16 v[100:103], v[176:179], v[226:229], v[100:103]
	v_mfma_f32_16x16x32_bf16 v[92:95], v[168:171], v[234:237], v[92:95]
	v_mfma_f32_16x16x32_bf16 v[84:87], v[176:179], v[234:237], v[84:87]
	v_mfma_f32_16x16x32_bf16 v[76:79], v[168:171], v[242:245], v[76:79]
	v_mfma_f32_16x16x32_bf16 v[68:71], v[176:179], v[242:245], v[68:71]
	v_mfma_f32_16x16x32_bf16 v[120:123], v[180:183], v[214:217], v[120:123]
	v_mfma_f32_16x16x32_bf16 v[112:115], v[188:191], v[214:217], v[112:115]
	v_mfma_f32_16x16x32_bf16 v[104:107], v[180:183], v[222:225], v[104:107]
	v_mfma_f32_16x16x32_bf16 v[96:99], v[188:191], v[222:225], v[96:99]
	v_mfma_f32_16x16x32_bf16 v[88:91], v[180:183], v[230:233], v[88:91]
	v_mfma_f32_16x16x32_bf16 v[80:83], v[188:191], v[230:233], v[80:83]
	v_mfma_f32_16x16x32_bf16 v[72:75], v[180:183], v[238:241], v[72:75]
	v_mfma_f32_16x16x32_bf16 v[64:67], v[188:191], v[238:241], v[64:67]
	v_mfma_f32_16x16x32_bf16 v[120:123], v[184:187], v[218:221], v[120:123]
	v_mfma_f32_16x16x32_bf16 v[112:115], v[210:213], v[218:221], v[112:115]
	v_mfma_f32_16x16x32_bf16 v[104:107], v[184:187], v[226:229], v[104:107]
	v_mfma_f32_16x16x32_bf16 v[96:99], v[210:213], v[226:229], v[96:99]
	v_mfma_f32_16x16x32_bf16 v[88:91], v[184:187], v[234:237], v[88:91]
	v_mfma_f32_16x16x32_bf16 v[80:83], v[210:213], v[234:237], v[80:83]
	v_mfma_f32_16x16x32_bf16 v[72:75], v[184:187], v[242:245], v[72:75]
	v_mfma_f32_16x16x32_bf16 v[64:67], v[210:213], v[242:245], v[64:67]
	s_setprio 0
	s_barrier
	s_mov_b32 m0, s37
	s_add_u32 s16, s16, 0x40080
	s_addc_u32 s17, s17, 0
	s_add_u32 s98, s16, 0xfffc0000
	s_addc_u32 s99, s17, -1
	ds_read_b128 v[214:217], v165 offset:49152
	ds_read_b128 v[218:221], v165 offset:50176
	global_load_lds_dwordx4 v132, s[98:99]
	s_mov_b32 m0, s38
	ds_read_b128 v[222:225], v165 offset:51200
	ds_read_b128 v[226:229], v165 offset:52224
	global_load_lds_dwordx4 v128, s[98:99]
	s_mov_b32 m0, s41
	ds_read_b128 v[230:233], v165 offset:53248
	global_load_lds_dwordx4 v132, s[16:17]
	s_mov_b32 m0, s42
	ds_read_b128 v[234:237], v165 offset:54272
	global_load_lds_dwordx4 v128, s[16:17]
	s_mov_b32 m0, s39
	s_add_u32 s100, s18, 0xfffc0080
	s_addc_u32 s101, s19, -1
	ds_read_b128 v[238:241], v165 offset:55296
	global_load_lds_dwordx4 v134, s[100:101]
	s_mov_b32 m0, s40
	ds_read_b128 v[242:245], v165 offset:56320
	global_load_lds_dwordx4 v130, s[100:101]
	s_waitcnt vmcnt(8) lgkmcnt(0)
	s_barrier
	s_setprio 1
	v_mfma_f32_16x16x32_bf16 v[60:63], v[140:143], v[214:217], v[60:63]
	v_mfma_f32_16x16x32_bf16 v[52:55], v[172:175], v[214:217], v[52:55]
	v_mfma_f32_16x16x32_bf16 v[44:47], v[140:143], v[222:225], v[44:47]
	v_mfma_f32_16x16x32_bf16 v[36:39], v[172:175], v[222:225], v[36:39]
	v_mfma_f32_16x16x32_bf16 v[28:31], v[140:143], v[230:233], v[28:31]
	v_mfma_f32_16x16x32_bf16 v[20:23], v[172:175], v[230:233], v[20:23]
	v_mfma_f32_16x16x32_bf16 v[12:15], v[140:143], v[238:241], v[12:15]
	v_mfma_f32_16x16x32_bf16 v[4:7], v[172:175], v[238:241], v[4:7]
	v_mfma_f32_16x16x32_bf16 v[60:63], v[168:171], v[218:221], v[60:63]
	v_mfma_f32_16x16x32_bf16 v[52:55], v[176:179], v[218:221], v[52:55]
	v_mfma_f32_16x16x32_bf16 v[44:47], v[168:171], v[226:229], v[44:47]
	v_mfma_f32_16x16x32_bf16 v[36:39], v[176:179], v[226:229], v[36:39]
	v_mfma_f32_16x16x32_bf16 v[28:31], v[168:171], v[234:237], v[28:31]
	v_mfma_f32_16x16x32_bf16 v[20:23], v[176:179], v[234:237], v[20:23]
	v_mfma_f32_16x16x32_bf16 v[12:15], v[168:171], v[242:245], v[12:15]
	v_mfma_f32_16x16x32_bf16 v[4:7], v[176:179], v[242:245], v[4:7]
	v_mfma_f32_16x16x32_bf16 v[56:59], v[180:183], v[214:217], v[56:59]
	v_mfma_f32_16x16x32_bf16 v[48:51], v[188:191], v[214:217], v[48:51]
	v_mfma_f32_16x16x32_bf16 v[40:43], v[180:183], v[222:225], v[40:43]
	v_mfma_f32_16x16x32_bf16 v[32:35], v[188:191], v[222:225], v[32:35]
	v_mfma_f32_16x16x32_bf16 v[24:27], v[180:183], v[230:233], v[24:27]
	v_mfma_f32_16x16x32_bf16 v[16:19], v[188:191], v[230:233], v[16:19]
	v_mfma_f32_16x16x32_bf16 v[8:11], v[180:183], v[238:241], v[8:11]
	v_mfma_f32_16x16x32_bf16 v[0:3], v[188:191], v[238:241], v[0:3]
	v_mfma_f32_16x16x32_bf16 v[56:59], v[184:187], v[218:221], v[56:59]
	v_mfma_f32_16x16x32_bf16 v[48:51], v[210:213], v[218:221], v[48:51]
	v_mfma_f32_16x16x32_bf16 v[40:43], v[184:187], v[226:229], v[40:43]
	v_mfma_f32_16x16x32_bf16 v[32:35], v[210:213], v[226:229], v[32:35]
	v_mfma_f32_16x16x32_bf16 v[24:27], v[184:187], v[234:237], v[24:27]
	v_mfma_f32_16x16x32_bf16 v[16:19], v[210:213], v[234:237], v[16:19]
	v_mfma_f32_16x16x32_bf16 v[8:11], v[184:187], v[242:245], v[8:11]
	v_mfma_f32_16x16x32_bf16 v[0:3], v[210:213], v[242:245], v[0:3]
	s_setprio 0
	s_barrier
	s_add_i32 s53, s53, 2
	s_add_u32 s14, s14, 0x100
	s_addc_u32 s15, s15, 0
	s_add_u32 s51, s51, 0x100
	s_addc_u32 s52, s52, 0
	s_cmp_gt_u32 s53, 13
; #define PG8_STAGE(bufoff, gbase, voff) do { _Pragma("unroll") for (int _i = 0; _i < 2; ++_i) \
;         __builtin_amdgcn_global_load_lds((const unsigned*)((const char*)(gbase) + (voff)[_i]), (PG8_LAS unsigned*)(lds + (bufoff) + ldsw + _i * 8192), 16, 0, 0); } while (0)
; #define PG8_LDA(dst, b, h) do { _Pragma("unroll") for (int m = 0; m < 4; ++m) _Pragma("unroll") for (int k = 0; k < 2; ++k) dst[m][k] = *(const PG8_LAS bf16x8*)(lds + PG8_SA(b, h) + aoff + m * 2048 + k * 1024); } while (0)
; #define PG8_LDB(dst, b, h) do { _Pragma("unroll") for (int n = 0; n < 2; ++n) _Pragma("unroll") for (int k = 0; k < 2; ++k) dst[n][k] = *(const PG8_LAS bf16x8*)(lds + PG8_SB(b, h) + boff + n * 2048 + k * 1024); } while (0)
; #define PG8_MMA(ai, bj, At, Bt) do { __builtin_amdgcn_s_setprio(1); _Pragma("unroll") for (int m = 0; m < 4; ++m) _Pragma("unroll") for (int n = 0; n < 2; ++n) _Pragma("unroll") for (int k = 0; k < 2; ++k) \
;         acc[ai][bj][m][n] = __builtin_amdgcn_mfma_f32_16x16x32_bf16(Bt[n][k], At[m][k], acc[ai][bj][m][n], 0, 0, 0); __builtin_amdgcn_s_setprio(0); } while (0)
; #define PG8_WAIT_V(n) asm volatile("s_waitcnt vmcnt(" #n ")" ::: "memory")
; #define PG8_WAIT_L(n) asm volatile("s_waitcnt lgkmcnt(" #n ")" ::: "memory")
; #define PG8_BAR __builtin_amdgcn_s_barrier()
; #define PG8_SCHED __builtin_amdgcn_sched_barrier(0)
; template <class Epi, class Sched, bool ALIGN_EPI = false, bool SP2 = false>
; __device__ __forceinline__ void gemm_phase(PG8_LAS unsigned char* lds, const Gemm g, const Sched& S, const Epi& E) {
;     ...
;             PG8_LDB(B0, 0, 0); PG8_LDB(B1, 0, 1); PG8_SCHED; PG8_LDA(At, 0, 0); PG8_STAGE(PG8_SA(1, 1), a1 + hstep, voffA);
;             PG8_WAIT_V(8); PG8_WAIT_L(0); PG8_BAR; PG8_MMA(0, 0, At, B0); PG8_MMA(0, 1, At, B1); PG8_BAR; PG8_SCHED;
;             PG8_LDA(At, 0, 1); PG8_STAGE(PG8_SB(0, 0), b2, voffB); PG8_STAGE(PG8_SB(0, 1), b2 + hstep, voffB); PG8_STAGE(PG8_SA(0, 0), a2, voffA);
;             PG8_WAIT_V(8); PG8_WAIT_L(0); PG8_BAR; PG8_MMA(1, 0, At, B0); PG8_MMA(1, 1, At, B1); PG8_BAR; PG8_SCHED;
.LBB0_446:
	s_add_u32 s16, s14, 0xfffc0080
	s_addc_u32 s17, s15, -1
	s_cmp_eq_u32 s53, 12
	s_cselect_b32 s19, s7, s17
	s_cselect_b32 s18, s49, s16
	s_cselect_b32 s17, s5, s52
	s_cselect_b32 s16, s50, s51
	s_mov_b32 m0, s43
	ds_read_b128 v[140:143], v254
	ds_read_b128 v[168:171], v254 offset:1024
	ds_read_b128 v[172:175], v254 offset:2048
	ds_read_b128 v[176:179], v254 offset:3072
	ds_read_b128 v[180:183], v254 offset:16384
	ds_read_b128 v[184:187], v254 offset:17408
	ds_read_b128 v[188:191], v254 offset:18432
	ds_read_b128 v[210:213], v254 offset:19456
	global_load_lds_dwordx4 v136, s[14:15]
	s_mov_b32 m0, s44
	ds_read_b128 v[214:217], v165
	ds_read_b128 v[218:221], v165 offset:1024
	ds_read_b128 v[222:225], v165 offset:2048
	ds_read_b128 v[226:229], v165 offset:3072
	ds_read_b128 v[230:233], v165 offset:4096
	ds_read_b128 v[234:237], v165 offset:5120
	ds_read_b128 v[238:241], v165 offset:6144
	ds_read_b128 v[242:245], v165 offset:7168
	global_load_lds_dwordx4 v138, s[14:15]
	s_waitcnt vmcnt(8) lgkmcnt(0)
	s_barrier
	s_setprio 1
	v_mfma_f32_16x16x32_bf16 v[124:127], v[140:143], v[214:217], v[124:127]
	v_mfma_f32_16x16x32_bf16 v[116:119], v[172:175], v[214:217], v[116:119]
	v_mfma_f32_16x16x32_bf16 v[108:111], v[140:143], v[222:225], v[108:111]
	v_mfma_f32_16x16x32_bf16 v[100:103], v[172:175], v[222:225], v[100:103]
	v_mfma_f32_16x16x32_bf16 v[92:95], v[140:143], v[230:233], v[92:95]
	v_mfma_f32_16x16x32_bf16 v[84:87], v[172:175], v[230:233], v[84:87]
	v_mfma_f32_16x16x32_bf16 v[76:79], v[140:143], v[238:241], v[76:79]
	v_mfma_f32_16x16x32_bf16 v[68:71], v[172:175], v[238:241], v[68:71]
	v_mfma_f32_16x16x32_bf16 v[124:127], v[168:171], v[218:221], v[124:127]
	v_mfma_f32_16x16x32_bf16 v[116:119], v[176:179], v[218:221], v[116:119]
	v_mfma_f32_16x16x32_bf16 v[108:111], v[168:171], v[226:229], v[108:111]
	v_mfma_f32_16x16x32_bf16 v[100:103], v[176:179], v[226:229], v[100:103]
	v_mfma_f32_16x16x32_bf16 v[92:95], v[168:171], v[234:237], v[92:95]
	v_mfma_f32_16x16x32_bf16 v[84:87], v[176:179], v[234:237], v[84:87]
	v_mfma_f32_16x16x32_bf16 v[76:79], v[168:171], v[242:245], v[76:79]
	v_mfma_f32_16x16x32_bf16 v[68:71], v[176:179], v[242:245], v[68:71]
	v_mfma_f32_16x16x32_bf16 v[120:123], v[180:183], v[214:217], v[120:123]
	v_mfma_f32_16x16x32_bf16 v[112:115], v[188:191], v[214:217], v[112:115]
	v_mfma_f32_16x16x32_bf16 v[104:107], v[180:183], v[222:225], v[104:107]
	v_mfma_f32_16x16x32_bf16 v[96:99], v[188:191], v[222:225], v[96:99]
	v_mfma_f32_16x16x32_bf16 v[88:91], v[180:183], v[230:233], v[88:91]
	v_mfma_f32_16x16x32_bf16 v[80:83], v[188:191], v[230:233], v[80:83]
	v_mfma_f32_16x16x32_bf16 v[72:75], v[180:183], v[238:241], v[72:75]
	v_mfma_f32_16x16x32_bf16 v[64:67], v[188:191], v[238:241], v[64:67]
	v_mfma_f32_16x16x32_bf16 v[120:123], v[184:187], v[218:221], v[120:123]
	v_mfma_f32_16x16x32_bf16 v[112:115], v[210:213], v[218:221], v[112:115]
	v_mfma_f32_16x16x32_bf16 v[104:107], v[184:187], v[226:229], v[104:107]
	v_mfma_f32_16x16x32_bf16 v[96:99], v[210:213], v[226:229], v[96:99]
	v_mfma_f32_16x16x32_bf16 v[88:91], v[184:187], v[234:237], v[88:91]
	v_mfma_f32_16x16x32_bf16 v[80:83], v[210:213], v[234:237], v[80:83]
	v_mfma_f32_16x16x32_bf16 v[72:75], v[184:187], v[242:245], v[72:75]
	v_mfma_f32_16x16x32_bf16 v[64:67], v[210:213], v[242:245], v[64:67]
	s_setprio 0
	s_barrier
	s_mov_b32 m0, s27
	s_add_u32 s54, s16, 0x40000
	s_addc_u32 s55, s17, 0
	ds_read_b128 v[214:217], v165 offset:16384
	ds_read_b128 v[218:221], v165 offset:17408
	global_load_lds_dwordx4 v132, s[16:17]
	s_mov_b32 m0, s28
	ds_read_b128 v[222:225], v165 offset:18432
	ds_read_b128 v[226:229], v165 offset:19456
	global_load_lds_dwordx4 v128, s[16:17]
	s_mov_b32 m0, s29
	ds_read_b128 v[230:233], v165 offset:20480
	global_load_lds_dwordx4 v132, s[54:55]
	s_mov_b32 m0, s30
	ds_read_b128 v[234:237], v165 offset:21504
	global_load_lds_dwordx4 v128, s[54:55]
	s_mov_b32 m0, s22
	ds_read_b128 v[238:241], v165 offset:22528
	global_load_lds_dwordx4 v134, s[18:19]
	s_mov_b32 m0, s31
	ds_read_b128 v[242:245], v165 offset:23552
	global_load_lds_dwordx4 v130, s[18:19]
	s_waitcnt vmcnt(8) lgkmcnt(0)
	s_barrier
	s_setprio 1
	v_mfma_f32_16x16x32_bf16 v[60:63], v[140:143], v[214:217], v[60:63]
	v_mfma_f32_16x16x32_bf16 v[52:55], v[172:175], v[214:217], v[52:55]
	v_mfma_f32_16x16x32_bf16 v[44:47], v[140:143], v[222:225], v[44:47]
	v_mfma_f32_16x16x32_bf16 v[36:39], v[172:175], v[222:225], v[36:39]
	v_mfma_f32_16x16x32_bf16 v[28:31], v[140:143], v[230:233], v[28:31]
	v_mfma_f32_16x16x32_bf16 v[20:23], v[172:175], v[230:233], v[20:23]
	v_mfma_f32_16x16x32_bf16 v[12:15], v[140:143], v[238:241], v[12:15]
	v_mfma_f32_16x16x32_bf16 v[4:7], v[172:175], v[238:241], v[4:7]
	v_mfma_f32_16x16x32_bf16 v[60:63], v[168:171], v[218:221], v[60:63]
	v_mfma_f32_16x16x32_bf16 v[52:55], v[176:179], v[218:221], v[52:55]
	v_mfma_f32_16x16x32_bf16 v[44:47], v[168:171], v[226:229], v[44:47]
	v_mfma_f32_16x16x32_bf16 v[36:39], v[176:179], v[226:229], v[36:39]
	v_mfma_f32_16x16x32_bf16 v[28:31], v[168:171], v[234:237], v[28:31]
	v_mfma_f32_16x16x32_bf16 v[20:23], v[176:179], v[234:237], v[20:23]
	v_mfma_f32_16x16x32_bf16 v[12:15], v[168:171], v[242:245], v[12:15]
	v_mfma_f32_16x16x32_bf16 v[4:7], v[176:179], v[242:245], v[4:7]
	v_mfma_f32_16x16x32_bf16 v[56:59], v[180:183], v[214:217], v[56:59]
	v_mfma_f32_16x16x32_bf16 v[48:51], v[188:191], v[214:217], v[48:51]
	v_mfma_f32_16x16x32_bf16 v[40:43], v[180:183], v[222:225], v[40:43]
	v_mfma_f32_16x16x32_bf16 v[32:35], v[188:191], v[222:225], v[32:35]
	v_mfma_f32_16x16x32_bf16 v[24:27], v[180:183], v[230:233], v[24:27]
	v_mfma_f32_16x16x32_bf16 v[16:19], v[188:191], v[230:233], v[16:19]
	v_mfma_f32_16x16x32_bf16 v[8:11], v[180:183], v[238:241], v[8:11]
	v_mfma_f32_16x16x32_bf16 v[0:3], v[188:191], v[238:241], v[0:3]
	v_mfma_f32_16x16x32_bf16 v[56:59], v[184:187], v[218:221], v[56:59]
	v_mfma_f32_16x16x32_bf16 v[48:51], v[210:213], v[218:221], v[48:51]
	v_mfma_f32_16x16x32_bf16 v[40:43], v[184:187], v[226:229], v[40:43]
	v_mfma_f32_16x16x32_bf16 v[32:35], v[210:213], v[226:229], v[32:35]
	v_mfma_f32_16x16x32_bf16 v[24:27], v[184:187], v[234:237], v[24:27]
	v_mfma_f32_16x16x32_bf16 v[16:19], v[210:213], v[234:237], v[16:19]
	v_mfma_f32_16x16x32_bf16 v[8:11], v[184:187], v[242:245], v[8:11]
	v_mfma_f32_16x16x32_bf16 v[0:3], v[210:213], v[242:245], v[0:3]
	s_setprio 0
	s_barrier
; #define PG8_STAGE(bufoff, gbase, voff) do { _Pragma("unroll") for (int _i = 0; _i < 2; ++_i) \
;         __builtin_amdgcn_global_load_lds((const unsigned*)((const char*)(gbase) + (voff)[_i]), (PG8_LAS unsigned*)(lds + (bufoff) + ldsw + _i * 8192), 16, 0, 0); } while (0)
; #define PG8_LDA(dst, b, h) do { _Pragma("unroll") for (int m = 0; m < 4; ++m) _Pragma("unroll") for (int k = 0; k < 2; ++k) dst[m][k] = *(const PG8_LAS bf16x8*)(lds + PG8_SA(b, h) + aoff + m * 2048 + k * 1024); } while (0)
; #define PG8_LDB(dst, b, h) do { _Pragma("unroll") for (int n = 0; n < 2; ++n) _Pragma("unroll") for (int k = 0; k < 2; ++k) dst[n][k] = *(const PG8_LAS bf16x8*)(lds + PG8_SB(b, h) + boff + n * 2048 + k * 1024); } while (0)
; #define PG8_MMA(ai, bj, At, Bt) do { __builtin_amdgcn_s_setprio(1); _Pragma("unroll") for (int m = 0; m < 4; ++m) _Pragma("unroll") for (int n = 0; n < 2; ++n) _Pragma("unroll") for (int k = 0; k < 2; ++k) \
;         acc[ai][bj][m][n] = __builtin_amdgcn_mfma_f32_16x16x32_bf16(Bt[n][k], At[m][k], acc[ai][bj][m][n], 0, 0, 0); __builtin_amdgcn_s_setprio(0); } while (0)
; #define PG8_WAIT_V(n) asm volatile("s_waitcnt vmcnt(" #n ")" ::: "memory")
; #define PG8_WAIT_L(n) asm volatile("s_waitcnt lgkmcnt(" #n ")" ::: "memory")
; #define PG8_BAR __builtin_amdgcn_s_barrier()
; #define PG8_SCHED __builtin_amdgcn_sched_barrier(0)
; template <class Epi, class Sched, bool ALIGN_EPI = false, bool SP2 = false>
; __device__ __forceinline__ void gemm_phase(PG8_LAS unsigned char* lds, const Gemm g, const Sched& S, const Epi& E) {
;     ...
;             PG8_LDB(B0, 1, 0); PG8_LDB(B1, 1, 1); PG8_SCHED; PG8_LDA(At, 1, 0); PG8_STAGE(PG8_SA(0, 1), a2 + hstep, voffA);
;             PG8_WAIT_V(8); PG8_WAIT_L(0); PG8_BAR; PG8_MMA(0, 0, At, B0); PG8_MMA(0, 1, At, B1); PG8_BAR; PG8_SCHED;
;             PG8_LDA(At, 1, 1); PG8_STAGE(PG8_SB(1, 0), b3, voffB); PG8_STAGE(PG8_SB(1, 1), b3 + hstep, voffB); PG8_STAGE(PG8_SA(1, 0), a3, voffA);
;             PG8_WAIT_V(8); PG8_WAIT_L(0); PG8_BAR; PG8_MMA(1, 0, At, B0); PG8_MMA(1, 1, At, B1); PG8_BAR; PG8_SCHED;
;     ...
;         if constexpr (ALIGN_EPI) { if (wr == 0) PG8_BAR; }
	s_add_u32 s18, s18, 0x40000
	s_addc_u32 s19, s19, 0
	s_mov_b32 m0, s33
	ds_read_b128 v[140:143], v254 offset:32768
	ds_read_b128 v[168:171], v254 offset:33792
	ds_read_b128 v[172:175], v254 offset:34816
	ds_read_b128 v[176:179], v254 offset:35840
	ds_read_b128 v[180:183], v254 offset:49152
	ds_read_b128 v[184:187], v254 offset:50176
	ds_read_b128 v[188:191], v254 offset:51200
	ds_read_b128 v[210:213], v254 offset:52224
	global_load_lds_dwordx4 v134, s[18:19]
	s_mov_b32 m0, s34
	ds_read_b128 v[214:217], v165 offset:32768
	ds_read_b128 v[218:221], v165 offset:33792
	ds_read_b128 v[222:225], v165 offset:34816
	ds_read_b128 v[226:229], v165 offset:35840
	ds_read_b128 v[230:233], v165 offset:36864
	ds_read_b128 v[234:237], v165 offset:37888
	ds_read_b128 v[238:241], v165 offset:38912
	ds_read_b128 v[242:245], v165 offset:39936
	global_load_lds_dwordx4 v130, s[18:19]
	s_waitcnt vmcnt(8) lgkmcnt(0)
	s_barrier
	s_setprio 1
	v_mfma_f32_16x16x32_bf16 v[124:127], v[140:143], v[214:217], v[124:127]
	v_mfma_f32_16x16x32_bf16 v[116:119], v[172:175], v[214:217], v[116:119]
	v_mfma_f32_16x16x32_bf16 v[108:111], v[140:143], v[222:225], v[108:111]
	v_mfma_f32_16x16x32_bf16 v[100:103], v[172:175], v[222:225], v[100:103]
	v_mfma_f32_16x16x32_bf16 v[92:95], v[140:143], v[230:233], v[92:95]
	v_mfma_f32_16x16x32_bf16 v[84:87], v[172:175], v[230:233], v[84:87]
	v_mfma_f32_16x16x32_bf16 v[76:79], v[140:143], v[238:241], v[76:79]
	v_mfma_f32_16x16x32_bf16 v[68:71], v[172:175], v[238:241], v[68:71]
	v_mfma_f32_16x16x32_bf16 v[124:127], v[168:171], v[218:221], v[124:127]
	v_mfma_f32_16x16x32_bf16 v[116:119], v[176:179], v[218:221], v[116:119]
	v_mfma_f32_16x16x32_bf16 v[108:111], v[168:171], v[226:229], v[108:111]
	v_mfma_f32_16x16x32_bf16 v[100:103], v[176:179], v[226:229], v[100:103]
	v_mfma_f32_16x16x32_bf16 v[92:95], v[168:171], v[234:237], v[92:95]
	v_mfma_f32_16x16x32_bf16 v[84:87], v[176:179], v[234:237], v[84:87]
	v_mfma_f32_16x16x32_bf16 v[76:79], v[168:171], v[242:245], v[76:79]
	v_mfma_f32_16x16x32_bf16 v[68:71], v[176:179], v[242:245], v[68:71]
	v_mfma_f32_16x16x32_bf16 v[120:123], v[180:183], v[214:217], v[120:123]
	v_mfma_f32_16x16x32_bf16 v[112:115], v[188:191], v[214:217], v[112:115]
	v_mfma_f32_16x16x32_bf16 v[104:107], v[180:183], v[222:225], v[104:107]
	v_mfma_f32_16x16x32_bf16 v[96:99], v[188:191], v[222:225], v[96:99]
	v_mfma_f32_16x16x32_bf16 v[88:91], v[180:183], v[230:233], v[88:91]
	v_mfma_f32_16x16x32_bf16 v[80:83], v[188:191], v[230:233], v[80:83]
	v_mfma_f32_16x16x32_bf16 v[72:75], v[180:183], v[238:241], v[72:75]
	v_mfma_f32_16x16x32_bf16 v[64:67], v[188:191], v[238:241], v[64:67]
	v_mfma_f32_16x16x32_bf16 v[120:123], v[184:187], v[218:221], v[120:123]
	v_mfma_f32_16x16x32_bf16 v[112:115], v[210:213], v[218:221], v[112:115]
	v_mfma_f32_16x16x32_bf16 v[104:107], v[184:187], v[226:229], v[104:107]
	v_mfma_f32_16x16x32_bf16 v[96:99], v[210:213], v[226:229], v[96:99]
	v_mfma_f32_16x16x32_bf16 v[88:91], v[184:187], v[234:237], v[88:91]
	v_mfma_f32_16x16x32_bf16 v[80:83], v[210:213], v[234:237], v[80:83]
	v_mfma_f32_16x16x32_bf16 v[72:75], v[184:187], v[242:245], v[72:75]
	v_mfma_f32_16x16x32_bf16 v[64:67], v[210:213], v[242:245], v[64:67]
	s_setprio 0
	s_barrier
	s_mov_b32 m0, s37
	s_add_u32 s16, s16, 0x40080
	s_addc_u32 s17, s17, 0
	s_add_u32 s98, s16, 0xfffc0000
	s_addc_u32 s99, s17, -1
	ds_read_b128 v[214:217], v165 offset:49152
	ds_read_b128 v[218:221], v165 offset:50176
	global_load_lds_dwordx4 v132, s[98:99]
	s_mov_b32 m0, s38
	ds_read_b128 v[222:225], v165 offset:51200
	ds_read_b128 v[226:229], v165 offset:52224
	global_load_lds_dwordx4 v128, s[98:99]
	s_mov_b32 m0, s41
	ds_read_b128 v[230:233], v165 offset:53248
	global_load_lds_dwordx4 v132, s[16:17]
	s_mov_b32 m0, s42
	ds_read_b128 v[234:237], v165 offset:54272
	global_load_lds_dwordx4 v128, s[16:17]
	s_mov_b32 m0, s39
	s_add_u32 s100, s18, 0xfffc0080
	s_addc_u32 s101, s19, -1
	ds_read_b128 v[238:241], v165 offset:55296
	global_load_lds_dwordx4 v134, s[100:101]
	s_mov_b32 m0, s40
	ds_read_b128 v[242:245], v165 offset:56320
	global_load_lds_dwordx4 v130, s[100:101]
	s_waitcnt vmcnt(8) lgkmcnt(0)
	s_barrier
	s_setprio 1
	v_mfma_f32_16x16x32_bf16 v[60:63], v[140:143], v[214:217], v[60:63]
	v_mfma_f32_16x16x32_bf16 v[52:55], v[172:175], v[214:217], v[52:55]
	v_mfma_f32_16x16x32_bf16 v[44:47], v[140:143], v[222:225], v[44:47]
	v_mfma_f32_16x16x32_bf16 v[36:39], v[172:175], v[222:225], v[36:39]
	v_mfma_f32_16x16x32_bf16 v[28:31], v[140:143], v[230:233], v[28:31]
	v_mfma_f32_16x16x32_bf16 v[20:23], v[172:175], v[230:233], v[20:23]
	v_mfma_f32_16x16x32_bf16 v[12:15], v[140:143], v[238:241], v[12:15]
	v_mfma_f32_16x16x32_bf16 v[4:7], v[172:175], v[238:241], v[4:7]
	v_mfma_f32_16x16x32_bf16 v[60:63], v[168:171], v[218:221], v[60:63]
	v_mfma_f32_16x16x32_bf16 v[52:55], v[176:179], v[218:221], v[52:55]
	v_mfma_f32_16x16x32_bf16 v[44:47], v[168:171], v[226:229], v[44:47]
	v_mfma_f32_16x16x32_bf16 v[36:39], v[176:179], v[226:229], v[36:39]
	v_mfma_f32_16x16x32_bf16 v[28:31], v[168:171], v[234:237], v[28:31]
	v_mfma_f32_16x16x32_bf16 v[20:23], v[176:179], v[234:237], v[20:23]
	v_mfma_f32_16x16x32_bf16 v[12:15], v[168:171], v[242:245], v[12:15]
	v_mfma_f32_16x16x32_bf16 v[4:7], v[176:179], v[242:245], v[4:7]
	v_mfma_f32_16x16x32_bf16 v[56:59], v[180:183], v[214:217], v[56:59]
	v_mfma_f32_16x16x32_bf16 v[48:51], v[188:191], v[214:217], v[48:51]
	v_mfma_f32_16x16x32_bf16 v[40:43], v[180:183], v[222:225], v[40:43]
	v_mfma_f32_16x16x32_bf16 v[32:35], v[188:191], v[222:225], v[32:35]
	v_mfma_f32_16x16x32_bf16 v[24:27], v[180:183], v[230:233], v[24:27]
	v_mfma_f32_16x16x32_bf16 v[16:19], v[188:191], v[230:233], v[16:19]
	v_mfma_f32_16x16x32_bf16 v[8:11], v[180:183], v[238:241], v[8:11]
	v_mfma_f32_16x16x32_bf16 v[0:3], v[188:191], v[238:241], v[0:3]
	v_mfma_f32_16x16x32_bf16 v[56:59], v[184:187], v[218:221], v[56:59]
	v_mfma_f32_16x16x32_bf16 v[48:51], v[210:213], v[218:221], v[48:51]
	v_mfma_f32_16x16x32_bf16 v[40:43], v[184:187], v[226:229], v[40:43]
	v_mfma_f32_16x16x32_bf16 v[32:35], v[210:213], v[226:229], v[32:35]
	v_mfma_f32_16x16x32_bf16 v[24:27], v[184:187], v[234:237], v[24:27]
	v_mfma_f32_16x16x32_bf16 v[16:19], v[210:213], v[234:237], v[16:19]
	v_mfma_f32_16x16x32_bf16 v[8:11], v[184:187], v[242:245], v[8:11]
	v_mfma_f32_16x16x32_bf16 v[0:3], v[210:213], v[242:245], v[0:3]
	s_setprio 0
	s_barrier
	s_add_i32 s53, s53, 2
	s_add_u32 s14, s14, 0x100
	s_addc_u32 s15, s15, 0
	s_add_u32 s51, s51, 0x100
	s_addc_u32 s52, s52, 0
	s_cmp_gt_u32 s53, 13
	s_cbranch_scc0 .LBB0_446
	s_and_b64 vcc, exec, s[2:3]
	s_cbranch_vccz .LBB0_449
	s_barrier

; #define PG8_STAGE(bufoff, gbase, voff) do { _Pragma("unroll") for (int _i = 0; _i < 2; ++_i) \
;         __builtin_amdgcn_global_load_lds((const unsigned*)((const char*)(gbase) + (voff)[_i]), (PG8_LAS unsigned*)(lds + (bufoff) + ldsw + _i * 8192), 16, 0, 0); } while (0)
; #define PG8_LDA(dst, b, h) do { _Pragma("unroll") for (int m = 0; m < 4; ++m) _Pragma("unroll") for (int k = 0; k < 2; ++k) dst[m][k] = *(const PG8_LAS bf16x8*)(lds + PG8_SA(b, h) + aoff + m * 2048 + k * 1024); } while (0)
; #define PG8_LDB(dst, b, h) do { _Pragma("unroll") for (int n = 0; n < 2; ++n) _Pragma("unroll") for (int k = 0; k < 2; ++k) dst[n][k] = *(const PG8_LAS bf16x8*)(lds + PG8_SB(b, h) + boff + n * 2048 + k * 1024); } while (0)
; #define PG8_MMA(ai, bj, At, Bt) do { __builtin_amdgcn_s_setprio(1); _Pragma("unroll") for (int m = 0; m < 4; ++m) _Pragma("unroll") for (int n = 0; n < 2; ++n) _Pragma("unroll") for (int k = 0; k < 2; ++k) \
;         acc[ai][bj][m][n] = __builtin_amdgcn_mfma_f32_16x16x32_bf16(Bt[n][k], At[m][k], acc[ai][bj][m][n], 0, 0, 0); __builtin_amdgcn_s_setprio(0); } while (0)
; #define PG8_WAIT_V(n) asm volatile("s_waitcnt vmcnt(" #n ")" ::: "memory")
; #define PG8_WAIT_L(n) asm volatile("s_waitcnt lgkmcnt(" #n ")" ::: "memory")
; #define PG8_BAR __builtin_amdgcn_s_barrier()
; #define PG8_SCHED __builtin_amdgcn_sched_barrier(0)
; template <class Epi, class Sched, bool ALIGN_EPI = false, bool SP2 = false>
; __device__ __forceinline__ void gemm_phase(PG8_LAS unsigned char* lds, const Gemm g, const Sched& S, const Epi& E) {
;     ...
;             PG8_LDB(B0, 0, 0); PG8_LDB(B1, 0, 1); PG8_SCHED; PG8_LDA(At, 0, 0); PG8_STAGE(PG8_SA(1, 1), a1 + hstep, voffA);
;             PG8_WAIT_V(8); PG8_WAIT_L(0); PG8_BAR; PG8_MMA(0, 0, At, B0); PG8_MMA(0, 1, At, B1); PG8_BAR; PG8_SCHED;
;             PG8_LDA(At, 0, 1); PG8_STAGE(PG8_SB(0, 0), b2, voffB); PG8_STAGE(PG8_SB(0, 1), b2 + hstep, voffB); PG8_STAGE(PG8_SA(0, 0), a2, voffA);
;             PG8_WAIT_V(8); PG8_WAIT_L(0); PG8_BAR; PG8_MMA(1, 0, At, B0); PG8_MMA(1, 1, At, B1); PG8_BAR; PG8_SCHED;
.Ldn_peel:
	s_add_u32 s2, s0, 0x100
	s_addc_u32 s3, s1, 0
	s_cmp_eq_u32 s13, 40
	s_cselect_b32 s7, s27, s3
	s_cselect_b32 s6, s26, s2
	s_cselect_b32 s5, s37, s11
	s_cselect_b32 s4, s36, s10
	s_add_i32 m0, s29, 0xc000
	ds_read_b128 v[128:131], v254
	ds_read_b128 v[132:135], v254 offset:1024
	ds_read_b128 v[136:139], v254 offset:2048
	ds_read_b128 v[140:143], v254 offset:3072
	ds_read_b128 v[174:177], v254 offset:16384
	ds_read_b128 v[184:187], v254 offset:17408
	ds_read_b128 v[188:191], v254 offset:18432
	ds_read_b128 v[210:213], v254 offset:19456
	global_load_lds_dwordx4 v170, s[0:1]
	s_add_i32 m0, s29, 0xe000
	ds_read_b128 v[214:217], v181
	ds_read_b128 v[218:221], v181 offset:1024
	ds_read_b128 v[222:225], v181 offset:2048
	ds_read_b128 v[226:229], v181 offset:3072
	ds_read_b128 v[230:233], v181 offset:4096
	ds_read_b128 v[234:237], v181 offset:5120
	ds_read_b128 v[238:241], v181 offset:6144
	ds_read_b128 v[242:245], v181 offset:7168
	global_load_lds_dwordx4 v172, s[0:1]
	s_waitcnt vmcnt(8) lgkmcnt(0)
	s_barrier
	s_setprio 1
	v_mfma_f32_16x16x32_bf16 v[124:127], v[128:131], v[214:217], 0
	v_mfma_f32_16x16x32_bf16 v[120:123], v[136:139], v[214:217], 0
	v_mfma_f32_16x16x32_bf16 v[108:111], v[128:131], v[222:225], 0
	v_mfma_f32_16x16x32_bf16 v[104:107], v[136:139], v[222:225], 0
	v_mfma_f32_16x16x32_bf16 v[92:95], v[128:131], v[230:233], 0
	v_mfma_f32_16x16x32_bf16 v[88:91], v[136:139], v[230:233], 0
	v_mfma_f32_16x16x32_bf16 v[76:79], v[128:131], v[238:241], 0
	v_mfma_f32_16x16x32_bf16 v[72:75], v[136:139], v[238:241], 0
	v_mfma_f32_16x16x32_bf16 v[124:127], v[132:135], v[218:221], v[124:127]
	v_mfma_f32_16x16x32_bf16 v[120:123], v[140:143], v[218:221], v[120:123]
	v_mfma_f32_16x16x32_bf16 v[108:111], v[132:135], v[226:229], v[108:111]
	v_mfma_f32_16x16x32_bf16 v[104:107], v[140:143], v[226:229], v[104:107]
	v_mfma_f32_16x16x32_bf16 v[92:95], v[132:135], v[234:237], v[92:95]
	v_mfma_f32_16x16x32_bf16 v[88:91], v[140:143], v[234:237], v[88:91]
	v_mfma_f32_16x16x32_bf16 v[76:79], v[132:135], v[242:245], v[76:79]
	v_mfma_f32_16x16x32_bf16 v[72:75], v[140:143], v[242:245], v[72:75]
	v_mfma_f32_16x16x32_bf16 v[116:119], v[174:177], v[214:217], 0
	v_mfma_f32_16x16x32_bf16 v[112:115], v[188:191], v[214:217], 0
	v_mfma_f32_16x16x32_bf16 v[100:103], v[174:177], v[222:225], 0
	v_mfma_f32_16x16x32_bf16 v[96:99], v[188:191], v[222:225], 0
	v_mfma_f32_16x16x32_bf16 v[84:87], v[174:177], v[230:233], 0
	v_mfma_f32_16x16x32_bf16 v[80:83], v[188:191], v[230:233], 0
	v_mfma_f32_16x16x32_bf16 v[68:71], v[174:177], v[238:241], 0
	v_mfma_f32_16x16x32_bf16 v[64:67], v[188:191], v[238:241], 0
	v_mfma_f32_16x16x32_bf16 v[116:119], v[184:187], v[218:221], v[116:119]
	v_mfma_f32_16x16x32_bf16 v[112:115], v[210:213], v[218:221], v[112:115]
	v_mfma_f32_16x16x32_bf16 v[100:103], v[184:187], v[226:229], v[100:103]
	v_mfma_f32_16x16x32_bf16 v[96:99], v[210:213], v[226:229], v[96:99]
	v_mfma_f32_16x16x32_bf16 v[84:87], v[184:187], v[234:237], v[84:87]
	v_mfma_f32_16x16x32_bf16 v[80:83], v[210:213], v[234:237], v[80:83]
	v_mfma_f32_16x16x32_bf16 v[68:71], v[184:187], v[242:245], v[68:71]
	v_mfma_f32_16x16x32_bf16 v[64:67], v[210:213], v[242:245], v[64:67]
	s_setprio 0
	s_barrier
	s_mov_b32 m0, s35
	s_add_u32 s0, s4, 0xb0000
	s_addc_u32 s1, s5, 0
	ds_read_b128 v[214:217], v181 offset:16384
	ds_read_b128 v[218:221], v181 offset:17408
	global_load_lds_dwordx4 v166, s[4:5]
	s_mov_b32 m0, s38
	ds_read_b128 v[222:225], v181 offset:18432
	ds_read_b128 v[226:229], v181 offset:19456
	global_load_lds_dwordx4 v162, s[4:5]
	s_mov_b32 m0, s39
	ds_read_b128 v[230:233], v181 offset:20480
	global_load_lds_dwordx4 v166, s[0:1]
	s_mov_b32 m0, s40
	ds_read_b128 v[234:237], v181 offset:21504
	global_load_lds_dwordx4 v162, s[0:1]
	s_mov_b32 m0, s29
	ds_read_b128 v[238:241], v181 offset:22528
	global_load_lds_dwordx4 v168, s[6:7]
	s_mov_b32 m0, s41
	ds_read_b128 v[242:245], v181 offset:23552
	global_load_lds_dwordx4 v164, s[6:7]
	s_waitcnt vmcnt(8) lgkmcnt(0)
	s_barrier
	s_setprio 1
	v_mfma_f32_16x16x32_bf16 v[60:63], v[128:131], v[214:217], 0
	v_mfma_f32_16x16x32_bf16 v[56:59], v[136:139], v[214:217], 0
	v_mfma_f32_16x16x32_bf16 v[44:47], v[128:131], v[222:225], 0
	v_mfma_f32_16x16x32_bf16 v[40:43], v[136:139], v[222:225], 0
	v_mfma_f32_16x16x32_bf16 v[28:31], v[128:131], v[230:233], 0
	v_mfma_f32_16x16x32_bf16 v[24:27], v[136:139], v[230:233], 0
	v_mfma_f32_16x16x32_bf16 v[12:15], v[128:131], v[238:241], 0
	v_mfma_f32_16x16x32_bf16 v[8:11], v[136:139], v[238:241], 0
	v_mfma_f32_16x16x32_bf16 v[60:63], v[132:135], v[218:221], v[60:63]
	v_mfma_f32_16x16x32_bf16 v[56:59], v[140:143], v[218:221], v[56:59]
	v_mfma_f32_16x16x32_bf16 v[44:47], v[132:135], v[226:229], v[44:47]
	v_mfma_f32_16x16x32_bf16 v[40:43], v[140:143], v[226:229], v[40:43]
	v_mfma_f32_16x16x32_bf16 v[28:31], v[132:135], v[234:237], v[28:31]
	v_mfma_f32_16x16x32_bf16 v[24:27], v[140:143], v[234:237], v[24:27]
	v_mfma_f32_16x16x32_bf16 v[12:15], v[132:135], v[242:245], v[12:15]
	v_mfma_f32_16x16x32_bf16 v[8:11], v[140:143], v[242:245], v[8:11]
	v_mfma_f32_16x16x32_bf16 v[52:55], v[174:177], v[214:217], 0
	v_mfma_f32_16x16x32_bf16 v[48:51], v[188:191], v[214:217], 0
	v_mfma_f32_16x16x32_bf16 v[36:39], v[174:177], v[222:225], 0
	v_mfma_f32_16x16x32_bf16 v[32:35], v[188:191], v[222:225], 0
	v_mfma_f32_16x16x32_bf16 v[20:23], v[174:177], v[230:233], 0
	v_mfma_f32_16x16x32_bf16 v[16:19], v[188:191], v[230:233], 0
	v_mfma_f32_16x16x32_bf16 v[4:7], v[174:177], v[238:241], 0
	v_mfma_f32_16x16x32_bf16 v[0:3], v[188:191], v[238:241], 0
	v_mfma_f32_16x16x32_bf16 v[52:55], v[184:187], v[218:221], v[52:55]
	v_mfma_f32_16x16x32_bf16 v[48:51], v[210:213], v[218:221], v[48:51]
	v_mfma_f32_16x16x32_bf16 v[36:39], v[184:187], v[226:229], v[36:39]
	v_mfma_f32_16x16x32_bf16 v[32:35], v[210:213], v[226:229], v[32:35]
	v_mfma_f32_16x16x32_bf16 v[20:23], v[184:187], v[234:237], v[20:23]
	v_mfma_f32_16x16x32_bf16 v[16:19], v[210:213], v[234:237], v[16:19]
	v_mfma_f32_16x16x32_bf16 v[4:7], v[184:187], v[242:245], v[4:7]
	v_mfma_f32_16x16x32_bf16 v[0:3], v[210:213], v[242:245], v[0:3]
	s_setprio 0
	s_barrier
; #define PG8_STAGE(bufoff, gbase, voff) do { _Pragma("unroll") for (int _i = 0; _i < 2; ++_i) \
;         __builtin_amdgcn_global_load_lds((const unsigned*)((const char*)(gbase) + (voff)[_i]), (PG8_LAS unsigned*)(lds + (bufoff) + ldsw + _i * 8192), 16, 0, 0); } while (0)
; #define PG8_LDA(dst, b, h) do { _Pragma("unroll") for (int m = 0; m < 4; ++m) _Pragma("unroll") for (int k = 0; k < 2; ++k) dst[m][k] = *(const PG8_LAS bf16x8*)(lds + PG8_SA(b, h) + aoff + m * 2048 + k * 1024); } while (0)
; #define PG8_LDB(dst, b, h) do { _Pragma("unroll") for (int n = 0; n < 2; ++n) _Pragma("unroll") for (int k = 0; k < 2; ++k) dst[n][k] = *(const PG8_LAS bf16x8*)(lds + PG8_SB(b, h) + boff + n * 2048 + k * 1024); } while (0)
; #define PG8_MMA(ai, bj, At, Bt) do { __builtin_amdgcn_s_setprio(1); _Pragma("unroll") for (int m = 0; m < 4; ++m) _Pragma("unroll") for (int n = 0; n < 2; ++n) _Pragma("unroll") for (int k = 0; k < 2; ++k) \
;         acc[ai][bj][m][n] = __builtin_amdgcn_mfma_f32_16x16x32_bf16(Bt[n][k], At[m][k], acc[ai][bj][m][n], 0, 0, 0); __builtin_amdgcn_s_setprio(0); } while (0)
; #define PG8_WAIT_V(n) asm volatile("s_waitcnt vmcnt(" #n ")" ::: "memory")
; #define PG8_WAIT_L(n) asm volatile("s_waitcnt lgkmcnt(" #n ")" ::: "memory")
; #define PG8_BAR __builtin_amdgcn_s_barrier()
; #define PG8_SCHED __builtin_amdgcn_sched_barrier(0)
; template <class Epi, class Sched, bool ALIGN_EPI = false, bool SP2 = false>
; __device__ __forceinline__ void gemm_phase(PG8_LAS unsigned char* lds, const Gemm g, const Sched& S, const Epi& E) {
;     ...
;             PG8_LDB(B0, 1, 0); PG8_LDB(B1, 1, 1); PG8_SCHED; PG8_LDA(At, 1, 0); PG8_STAGE(PG8_SA(0, 1), a2 + hstep, voffA);
;             PG8_WAIT_V(8); PG8_WAIT_L(0); PG8_BAR; PG8_MMA(0, 0, At, B0); PG8_MMA(0, 1, At, B1); PG8_BAR; PG8_SCHED;
;             PG8_LDA(At, 1, 1); PG8_STAGE(PG8_SB(1, 0), b3, voffB); PG8_STAGE(PG8_SB(1, 1), b3 + hstep, voffB); PG8_STAGE(PG8_SA(1, 0), a3, voffA);
;             PG8_WAIT_V(8); PG8_WAIT_L(0); PG8_BAR; PG8_MMA(1, 0, At, B0); PG8_MMA(1, 1, At, B1); PG8_BAR; PG8_SCHED;
	s_add_u32 s0, s6, 0xb0000
	s_addc_u32 s1, s7, 0
	s_mov_b32 m0, s42
	ds_read_b128 v[128:131], v254 offset:32768
	ds_read_b128 v[132:135], v254 offset:33792
	ds_read_b128 v[136:139], v254 offset:34816
	ds_read_b128 v[140:143], v254 offset:35840
	ds_read_b128 v[174:177], v254 offset:49152
	ds_read_b128 v[184:187], v254 offset:50176
	ds_read_b128 v[188:191], v254 offset:51200
	ds_read_b128 v[210:213], v254 offset:52224
	global_load_lds_dwordx4 v168, s[0:1]
	s_mov_b32 m0, s43
	ds_read_b128 v[214:217], v181 offset:32768
	ds_read_b128 v[218:221], v181 offset:33792
	ds_read_b128 v[222:225], v181 offset:34816
	ds_read_b128 v[226:229], v181 offset:35840
	ds_read_b128 v[230:233], v181 offset:36864
	ds_read_b128 v[234:237], v181 offset:37888
	ds_read_b128 v[238:241], v181 offset:38912
	ds_read_b128 v[242:245], v181 offset:39936
	global_load_lds_dwordx4 v164, s[0:1]
	s_waitcnt vmcnt(8) lgkmcnt(0)
	s_barrier
	s_setprio 1
	v_mfma_f32_16x16x32_bf16 v[124:127], v[128:131], v[214:217], v[124:127]
	v_mfma_f32_16x16x32_bf16 v[120:123], v[136:139], v[214:217], v[120:123]
	v_mfma_f32_16x16x32_bf16 v[108:111], v[128:131], v[222:225], v[108:111]
	v_mfma_f32_16x16x32_bf16 v[104:107], v[136:139], v[222:225], v[104:107]
	v_mfma_f32_16x16x32_bf16 v[92:95], v[128:131], v[230:233], v[92:95]
	v_mfma_f32_16x16x32_bf16 v[88:91], v[136:139], v[230:233], v[88:91]
	v_mfma_f32_16x16x32_bf16 v[76:79], v[128:131], v[238:241], v[76:79]
	v_mfma_f32_16x16x32_bf16 v[72:75], v[136:139], v[238:241], v[72:75]
	v_mfma_f32_16x16x32_bf16 v[124:127], v[132:135], v[218:221], v[124:127]
	v_mfma_f32_16x16x32_bf16 v[120:123], v[140:143], v[218:221], v[120:123]
	v_mfma_f32_16x16x32_bf16 v[108:111], v[132:135], v[226:229], v[108:111]
	v_mfma_f32_16x16x32_bf16 v[104:107], v[140:143], v[226:229], v[104:107]
	v_mfma_f32_16x16x32_bf16 v[92:95], v[132:135], v[234:237], v[92:95]
	v_mfma_f32_16x16x32_bf16 v[88:91], v[140:143], v[234:237], v[88:91]
	v_mfma_f32_16x16x32_bf16 v[76:79], v[132:135], v[242:245], v[76:79]
	v_mfma_f32_16x16x32_bf16 v[72:75], v[140:143], v[242:245], v[72:75]
	v_mfma_f32_16x16x32_bf16 v[116:119], v[174:177], v[214:217], v[116:119]
	v_mfma_f32_16x16x32_bf16 v[112:115], v[188:191], v[214:217], v[112:115]
	v_mfma_f32_16x16x32_bf16 v[100:103], v[174:177], v[222:225], v[100:103]
	v_mfma_f32_16x16x32_bf16 v[96:99], v[188:191], v[222:225], v[96:99]
	v_mfma_f32_16x16x32_bf16 v[84:87], v[174:177], v[230:233], v[84:87]
	v_mfma_f32_16x16x32_bf16 v[80:83], v[188:191], v[230:233], v[80:83]
	v_mfma_f32_16x16x32_bf16 v[68:71], v[174:177], v[238:241], v[68:71]
	v_mfma_f32_16x16x32_bf16 v[64:67], v[188:191], v[238:241], v[64:67]
	v_mfma_f32_16x16x32_bf16 v[116:119], v[184:187], v[218:221], v[116:119]
	v_mfma_f32_16x16x32_bf16 v[112:115], v[210:213], v[218:221], v[112:115]
	v_mfma_f32_16x16x32_bf16 v[100:103], v[184:187], v[226:229], v[100:103]
	v_mfma_f32_16x16x32_bf16 v[96:99], v[210:213], v[226:229], v[96:99]
	v_mfma_f32_16x16x32_bf16 v[84:87], v[184:187], v[234:237], v[84:87]
	v_mfma_f32_16x16x32_bf16 v[80:83], v[210:213], v[234:237], v[80:83]
	v_mfma_f32_16x16x32_bf16 v[68:71], v[184:187], v[242:245], v[68:71]
	v_mfma_f32_16x16x32_bf16 v[64:67], v[210:213], v[242:245], v[64:67]
	s_setprio 0
	s_barrier
	s_mov_b32 m0, s47
	s_add_u32 s0, s4, 0xb0080
	s_addc_u32 s1, s5, 0
	s_add_u32 s98, s4, 0x80
	s_addc_u32 s99, s5, 0
	ds_read_b128 v[214:217], v181 offset:49152
	ds_read_b128 v[218:221], v181 offset:50176
	global_load_lds_dwordx4 v166, s[98:99]
	s_mov_b32 m0, s48
	ds_read_b128 v[222:225], v181 offset:51200
	ds_read_b128 v[226:229], v181 offset:52224
	global_load_lds_dwordx4 v162, s[98:99]
	s_mov_b32 m0, s51
	ds_read_b128 v[230:233], v181 offset:53248
	global_load_lds_dwordx4 v166, s[0:1]
	s_mov_b32 m0, s52
	ds_read_b128 v[234:237], v181 offset:54272
	global_load_lds_dwordx4 v162, s[0:1]
	s_mov_b32 m0, s49
	s_add_u32 s100, s6, 0x80
	s_addc_u32 s101, s7, 0
	ds_read_b128 v[238:241], v181 offset:55296
	global_load_lds_dwordx4 v168, s[100:101]
	s_mov_b32 m0, s50
	ds_read_b128 v[242:245], v181 offset:56320
	global_load_lds_dwordx4 v164, s[100:101]
	s_waitcnt vmcnt(8) lgkmcnt(0)
	s_barrier
	s_setprio 1
	v_mfma_f32_16x16x32_bf16 v[60:63], v[128:131], v[214:217], v[60:63]
	v_mfma_f32_16x16x32_bf16 v[56:59], v[136:139], v[214:217], v[56:59]
	v_mfma_f32_16x16x32_bf16 v[44:47], v[128:131], v[222:225], v[44:47]
	v_mfma_f32_16x16x32_bf16 v[40:43], v[136:139], v[222:225], v[40:43]
	v_mfma_f32_16x16x32_bf16 v[28:31], v[128:131], v[230:233], v[28:31]
	v_mfma_f32_16x16x32_bf16 v[24:27], v[136:139], v[230:233], v[24:27]
	v_mfma_f32_16x16x32_bf16 v[12:15], v[128:131], v[238:241], v[12:15]
	v_mfma_f32_16x16x32_bf16 v[8:11], v[136:139], v[238:241], v[8:11]
	v_mfma_f32_16x16x32_bf16 v[60:63], v[132:135], v[218:221], v[60:63]
	v_mfma_f32_16x16x32_bf16 v[56:59], v[140:143], v[218:221], v[56:59]
	v_mfma_f32_16x16x32_bf16 v[44:47], v[132:135], v[226:229], v[44:47]
	v_mfma_f32_16x16x32_bf16 v[40:43], v[140:143], v[226:229], v[40:43]
	v_mfma_f32_16x16x32_bf16 v[28:31], v[132:135], v[234:237], v[28:31]
	v_mfma_f32_16x16x32_bf16 v[24:27], v[140:143], v[234:237], v[24:27]
	v_mfma_f32_16x16x32_bf16 v[12:15], v[132:135], v[242:245], v[12:15]
	v_mfma_f32_16x16x32_bf16 v[8:11], v[140:143], v[242:245], v[8:11]
	v_mfma_f32_16x16x32_bf16 v[52:55], v[174:177], v[214:217], v[52:55]
	v_mfma_f32_16x16x32_bf16 v[48:51], v[188:191], v[214:217], v[48:51]
	v_mfma_f32_16x16x32_bf16 v[36:39], v[174:177], v[222:225], v[36:39]
	v_mfma_f32_16x16x32_bf16 v[32:35], v[188:191], v[222:225], v[32:35]
	v_mfma_f32_16x16x32_bf16 v[20:23], v[174:177], v[230:233], v[20:23]
	v_mfma_f32_16x16x32_bf16 v[16:19], v[188:191], v[230:233], v[16:19]
	v_mfma_f32_16x16x32_bf16 v[4:7], v[174:177], v[238:241], v[4:7]
	v_mfma_f32_16x16x32_bf16 v[0:3], v[188:191], v[238:241], v[0:3]
	v_mfma_f32_16x16x32_bf16 v[52:55], v[184:187], v[218:221], v[52:55]
	v_mfma_f32_16x16x32_bf16 v[48:51], v[210:213], v[218:221], v[48:51]
	v_mfma_f32_16x16x32_bf16 v[36:39], v[184:187], v[226:229], v[36:39]
	v_mfma_f32_16x16x32_bf16 v[32:35], v[210:213], v[226:229], v[32:35]
	v_mfma_f32_16x16x32_bf16 v[20:23], v[184:187], v[234:237], v[20:23]
	v_mfma_f32_16x16x32_bf16 v[16:19], v[210:213], v[234:237], v[16:19]
	v_mfma_f32_16x16x32_bf16 v[4:7], v[184:187], v[242:245], v[4:7]
	v_mfma_f32_16x16x32_bf16 v[0:3], v[210:213], v[242:245], v[0:3]
	s_setprio 0
	s_barrier
	s_add_i32 s13, s13, 2
	s_add_u32 s10, s10, 0x100
	s_addc_u32 s11, s11, 0
	s_cmp_gt_u32 s13, 41
	s_mov_b64 s[0:1], s[2:3]
; #define PG8_STAGE(bufoff, gbase, voff) do { _Pragma("unroll") for (int _i = 0; _i < 2; ++_i) \
;         __builtin_amdgcn_global_load_lds((const unsigned*)((const char*)(gbase) + (voff)[_i]), (PG8_LAS unsigned*)(lds + (bufoff) + ldsw + _i * 8192), 16, 0, 0); } while (0)
; #define PG8_LDA(dst, b, h) do { _Pragma("unroll") for (int m = 0; m < 4; ++m) _Pragma("unroll") for (int k = 0; k < 2; ++k) dst[m][k] = *(const PG8_LAS bf16x8*)(lds + PG8_SA(b, h) + aoff + m * 2048 + k * 1024); } while (0)
; #define PG8_LDB(dst, b, h) do { _Pragma("unroll") for (int n = 0; n < 2; ++n) _Pragma("unroll") for (int k = 0; k < 2; ++k) dst[n][k] = *(const PG8_LAS bf16x8*)(lds + PG8_SB(b, h) + boff + n * 2048 + k * 1024); } while (0)
; #define PG8_MMA(ai, bj, At, Bt) do { __builtin_amdgcn_s_setprio(1); _Pragma("unroll") for (int m = 0; m < 4; ++m) _Pragma("unroll") for (int n = 0; n < 2; ++n) _Pragma("unroll") for (int k = 0; k < 2; ++k) \
;         acc[ai][bj][m][n] = __builtin_amdgcn_mfma_f32_16x16x32_bf16(Bt[n][k], At[m][k], acc[ai][bj][m][n], 0, 0, 0); __builtin_amdgcn_s_setprio(0); } while (0)
; #define PG8_WAIT_V(n) asm volatile("s_waitcnt vmcnt(" #n ")" ::: "memory")
; #define PG8_WAIT_L(n) asm volatile("s_waitcnt lgkmcnt(" #n ")" ::: "memory")
; #define PG8_BAR __builtin_amdgcn_s_barrier()
; #define PG8_SCHED __builtin_amdgcn_sched_barrier(0)
; template <class Epi, class Sched, bool ALIGN_EPI = false, bool SP2 = false>
; __device__ __forceinline__ void gemm_phase(PG8_LAS unsigned char* lds, const Gemm g, const Sched& S, const Epi& E) {
;     ...
;             PG8_LDB(B0, 0, 0); PG8_LDB(B1, 0, 1); PG8_SCHED; PG8_LDA(At, 0, 0); PG8_STAGE(PG8_SA(1, 1), a1 + hstep, voffA);
;             PG8_WAIT_V(8); PG8_WAIT_L(0); PG8_BAR; PG8_MMA(0, 0, At, B0); PG8_MMA(0, 1, At, B1); PG8_BAR; PG8_SCHED;
;             PG8_LDA(At, 0, 1); PG8_STAGE(PG8_SB(0, 0), b2, voffB); PG8_STAGE(PG8_SB(0, 1), b2 + hstep, voffB); PG8_STAGE(PG8_SA(0, 0), a2, voffA);
;             PG8_WAIT_V(8); PG8_WAIT_L(0); PG8_BAR; PG8_MMA(1, 0, At, B0); PG8_MMA(1, 1, At, B1); PG8_BAR; PG8_SCHED;
.LBB0_545:
	s_add_u32 s2, s0, 0x100
	s_addc_u32 s3, s1, 0
	s_cmp_eq_u32 s13, 40
	s_cselect_b32 s7, s27, s3
	s_cselect_b32 s6, s26, s2
	s_cselect_b32 s5, s37, s11
	s_cselect_b32 s4, s36, s10
	s_add_i32 m0, s29, 0xc000
	ds_read_b128 v[128:131], v254
	ds_read_b128 v[132:135], v254 offset:1024
	ds_read_b128 v[136:139], v254 offset:2048
	ds_read_b128 v[140:143], v254 offset:3072
	ds_read_b128 v[174:177], v254 offset:16384
	ds_read_b128 v[184:187], v254 offset:17408
	ds_read_b128 v[188:191], v254 offset:18432
	ds_read_b128 v[210:213], v254 offset:19456
	global_load_lds_dwordx4 v170, s[0:1]
	s_add_i32 m0, s29, 0xe000
	ds_read_b128 v[214:217], v181
	ds_read_b128 v[218:221], v181 offset:1024
	ds_read_b128 v[222:225], v181 offset:2048
	ds_read_b128 v[226:229], v181 offset:3072
	ds_read_b128 v[230:233], v181 offset:4096
	ds_read_b128 v[234:237], v181 offset:5120
	ds_read_b128 v[238:241], v181 offset:6144
	ds_read_b128 v[242:245], v181 offset:7168
	global_load_lds_dwordx4 v172, s[0:1]
	s_waitcnt vmcnt(8) lgkmcnt(0)
	s_barrier
	s_setprio 1
	v_mfma_f32_16x16x32_bf16 v[124:127], v[128:131], v[214:217], v[124:127]
	v_mfma_f32_16x16x32_bf16 v[120:123], v[136:139], v[214:217], v[120:123]
	v_mfma_f32_16x16x32_bf16 v[108:111], v[128:131], v[222:225], v[108:111]
	v_mfma_f32_16x16x32_bf16 v[104:107], v[136:139], v[222:225], v[104:107]
	v_mfma_f32_16x16x32_bf16 v[92:95], v[128:131], v[230:233], v[92:95]
	v_mfma_f32_16x16x32_bf16 v[88:91], v[136:139], v[230:233], v[88:91]
	v_mfma_f32_16x16x32_bf16 v[76:79], v[128:131], v[238:241], v[76:79]
	v_mfma_f32_16x16x32_bf16 v[72:75], v[136:139], v[238:241], v[72:75]
	v_mfma_f32_16x16x32_bf16 v[124:127], v[132:135], v[218:221], v[124:127]
	v_mfma_f32_16x16x32_bf16 v[120:123], v[140:143], v[218:221], v[120:123]
	v_mfma_f32_16x16x32_bf16 v[108:111], v[132:135], v[226:229], v[108:111]
	v_mfma_f32_16x16x32_bf16 v[104:107], v[140:143], v[226:229], v[104:107]
	v_mfma_f32_16x16x32_bf16 v[92:95], v[132:135], v[234:237], v[92:95]
	v_mfma_f32_16x16x32_bf16 v[88:91], v[140:143], v[234:237], v[88:91]
	v_mfma_f32_16x16x32_bf16 v[76:79], v[132:135], v[242:245], v[76:79]
	v_mfma_f32_16x16x32_bf16 v[72:75], v[140:143], v[242:245], v[72:75]
	v_mfma_f32_16x16x32_bf16 v[116:119], v[174:177], v[214:217], v[116:119]
	v_mfma_f32_16x16x32_bf16 v[112:115], v[188:191], v[214:217], v[112:115]
	v_mfma_f32_16x16x32_bf16 v[100:103], v[174:177], v[222:225], v[100:103]
	v_mfma_f32_16x16x32_bf16 v[96:99], v[188:191], v[222:225], v[96:99]
	v_mfma_f32_16x16x32_bf16 v[84:87], v[174:177], v[230:233], v[84:87]
	v_mfma_f32_16x16x32_bf16 v[80:83], v[188:191], v[230:233], v[80:83]
	v_mfma_f32_16x16x32_bf16 v[68:71], v[174:177], v[238:241], v[68:71]
	v_mfma_f32_16x16x32_bf16 v[64:67], v[188:191], v[238:241], v[64:67]
	v_mfma_f32_16x16x32_bf16 v[116:119], v[184:187], v[218:221], v[116:119]
	v_mfma_f32_16x16x32_bf16 v[112:115], v[210:213], v[218:221], v[112:115]
	v_mfma_f32_16x16x32_bf16 v[100:103], v[184:187], v[226:229], v[100:103]
	v_mfma_f32_16x16x32_bf16 v[96:99], v[210:213], v[226:229], v[96:99]
	v_mfma_f32_16x16x32_bf16 v[84:87], v[184:187], v[234:237], v[84:87]
	v_mfma_f32_16x16x32_bf16 v[80:83], v[210:213], v[234:237], v[80:83]
	v_mfma_f32_16x16x32_bf16 v[68:71], v[184:187], v[242:245], v[68:71]
	v_mfma_f32_16x16x32_bf16 v[64:67], v[210:213], v[242:245], v[64:67]
	s_setprio 0
	s_barrier
	s_mov_b32 m0, s35
	s_add_u32 s0, s4, 0xb0000
	s_addc_u32 s1, s5, 0
	ds_read_b128 v[214:217], v181 offset:16384
	ds_read_b128 v[218:221], v181 offset:17408
	global_load_lds_dwordx4 v166, s[4:5]
	s_mov_b32 m0, s38
	ds_read_b128 v[222:225], v181 offset:18432
	ds_read_b128 v[226:229], v181 offset:19456
	global_load_lds_dwordx4 v162, s[4:5]
	s_mov_b32 m0, s39
	ds_read_b128 v[230:233], v181 offset:20480
	global_load_lds_dwordx4 v166, s[0:1]
	s_mov_b32 m0, s40
	ds_read_b128 v[234:237], v181 offset:21504
	global_load_lds_dwordx4 v162, s[0:1]
	s_mov_b32 m0, s29
	ds_read_b128 v[238:241], v181 offset:22528
	global_load_lds_dwordx4 v168, s[6:7]
	s_mov_b32 m0, s41
	ds_read_b128 v[242:245], v181 offset:23552
	global_load_lds_dwordx4 v164, s[6:7]
	s_waitcnt vmcnt(8) lgkmcnt(0)
	s_barrier
	s_setprio 1
	v_mfma_f32_16x16x32_bf16 v[60:63], v[128:131], v[214:217], v[60:63]
	v_mfma_f32_16x16x32_bf16 v[56:59], v[136:139], v[214:217], v[56:59]
	v_mfma_f32_16x16x32_bf16 v[44:47], v[128:131], v[222:225], v[44:47]
	v_mfma_f32_16x16x32_bf16 v[40:43], v[136:139], v[222:225], v[40:43]
	v_mfma_f32_16x16x32_bf16 v[28:31], v[128:131], v[230:233], v[28:31]
	v_mfma_f32_16x16x32_bf16 v[24:27], v[136:139], v[230:233], v[24:27]
	v_mfma_f32_16x16x32_bf16 v[12:15], v[128:131], v[238:241], v[12:15]
	v_mfma_f32_16x16x32_bf16 v[8:11], v[136:139], v[238:241], v[8:11]
	v_mfma_f32_16x16x32_bf16 v[60:63], v[132:135], v[218:221], v[60:63]
	v_mfma_f32_16x16x32_bf16 v[56:59], v[140:143], v[218:221], v[56:59]
	v_mfma_f32_16x16x32_bf16 v[44:47], v[132:135], v[226:229], v[44:47]
	v_mfma_f32_16x16x32_bf16 v[40:43], v[140:143], v[226:229], v[40:43]
	v_mfma_f32_16x16x32_bf16 v[28:31], v[132:135], v[234:237], v[28:31]
	v_mfma_f32_16x16x32_bf16 v[24:27], v[140:143], v[234:237], v[24:27]
	v_mfma_f32_16x16x32_bf16 v[12:15], v[132:135], v[242:245], v[12:15]
	v_mfma_f32_16x16x32_bf16 v[8:11], v[140:143], v[242:245], v[8:11]
	v_mfma_f32_16x16x32_bf16 v[52:55], v[174:177], v[214:217], v[52:55]
	v_mfma_f32_16x16x32_bf16 v[48:51], v[188:191], v[214:217], v[48:51]
	v_mfma_f32_16x16x32_bf16 v[36:39], v[174:177], v[222:225], v[36:39]
	v_mfma_f32_16x16x32_bf16 v[32:35], v[188:191], v[222:225], v[32:35]
	v_mfma_f32_16x16x32_bf16 v[20:23], v[174:177], v[230:233], v[20:23]
	v_mfma_f32_16x16x32_bf16 v[16:19], v[188:191], v[230:233], v[16:19]
	v_mfma_f32_16x16x32_bf16 v[4:7], v[174:177], v[238:241], v[4:7]
	v_mfma_f32_16x16x32_bf16 v[0:3], v[188:191], v[238:241], v[0:3]
	v_mfma_f32_16x16x32_bf16 v[52:55], v[184:187], v[218:221], v[52:55]
	v_mfma_f32_16x16x32_bf16 v[48:51], v[210:213], v[218:221], v[48:51]
	v_mfma_f32_16x16x32_bf16 v[36:39], v[184:187], v[226:229], v[36:39]
	v_mfma_f32_16x16x32_bf16 v[32:35], v[210:213], v[226:229], v[32:35]
	v_mfma_f32_16x16x32_bf16 v[20:23], v[184:187], v[234:237], v[20:23]
	v_mfma_f32_16x16x32_bf16 v[16:19], v[210:213], v[234:237], v[16:19]
	v_mfma_f32_16x16x32_bf16 v[4:7], v[184:187], v[242:245], v[4:7]
	v_mfma_f32_16x16x32_bf16 v[0:3], v[210:213], v[242:245], v[0:3]
	s_setprio 0
	s_barrier
; #define PG8_STAGE(bufoff, gbase, voff) do { _Pragma("unroll") for (int _i = 0; _i < 2; ++_i) \
;         __builtin_amdgcn_global_load_lds((const unsigned*)((const char*)(gbase) + (voff)[_i]), (PG8_LAS unsigned*)(lds + (bufoff) + ldsw + _i * 8192), 16, 0, 0); } while (0)
; #define PG8_LDA(dst, b, h) do { _Pragma("unroll") for (int m = 0; m < 4; ++m) _Pragma("unroll") for (int k = 0; k < 2; ++k) dst[m][k] = *(const PG8_LAS bf16x8*)(lds + PG8_SA(b, h) + aoff + m * 2048 + k * 1024); } while (0)
; #define PG8_LDB(dst, b, h) do { _Pragma("unroll") for (int n = 0; n < 2; ++n) _Pragma("unroll") for (int k = 0; k < 2; ++k) dst[n][k] = *(const PG8_LAS bf16x8*)(lds + PG8_SB(b, h) + boff + n * 2048 + k * 1024); } while (0)
; #define PG8_MMA(ai, bj, At, Bt) do { __builtin_amdgcn_s_setprio(1); _Pragma("unroll") for (int m = 0; m < 4; ++m) _Pragma("unroll") for (int n = 0; n < 2; ++n) _Pragma("unroll") for (int k = 0; k < 2; ++k) \
;         acc[ai][bj][m][n] = __builtin_amdgcn_mfma_f32_16x16x32_bf16(Bt[n][k], At[m][k], acc[ai][bj][m][n], 0, 0, 0); __builtin_amdgcn_s_setprio(0); } while (0)
; #define PG8_WAIT_V(n) asm volatile("s_waitcnt vmcnt(" #n ")" ::: "memory")
; #define PG8_WAIT_L(n) asm volatile("s_waitcnt lgkmcnt(" #n ")" ::: "memory")
; #define PG8_BAR __builtin_amdgcn_s_barrier()
; #define PG8_SCHED __builtin_amdgcn_sched_barrier(0)
; template <class Epi, class Sched, bool ALIGN_EPI = false, bool SP2 = false>
; __device__ __forceinline__ void gemm_phase(PG8_LAS unsigned char* lds, const Gemm g, const Sched& S, const Epi& E) {
;     ...
;             PG8_LDB(B0, 1, 0); PG8_LDB(B1, 1, 1); PG8_SCHED; PG8_LDA(At, 1, 0); PG8_STAGE(PG8_SA(0, 1), a2 + hstep, voffA);
;             PG8_WAIT_V(8); PG8_WAIT_L(0); PG8_BAR; PG8_MMA(0, 0, At, B0); PG8_MMA(0, 1, At, B1); PG8_BAR; PG8_SCHED;
;             PG8_LDA(At, 1, 1); PG8_STAGE(PG8_SB(1, 0), b3, voffB); PG8_STAGE(PG8_SB(1, 1), b3 + hstep, voffB); PG8_STAGE(PG8_SA(1, 0), a3, voffA);
;             PG8_WAIT_V(8); PG8_WAIT_L(0); PG8_BAR; PG8_MMA(1, 0, At, B0); PG8_MMA(1, 1, At, B1); PG8_BAR; PG8_SCHED;
;     ...
;         if constexpr (ALIGN_EPI) { if (wr == 0) PG8_BAR; }
	s_add_u32 s0, s6, 0xb0000
	s_addc_u32 s1, s7, 0
	s_mov_b32 m0, s42
	ds_read_b128 v[128:131], v254 offset:32768
	ds_read_b128 v[132:135], v254 offset:33792
	ds_read_b128 v[136:139], v254 offset:34816
	ds_read_b128 v[140:143], v254 offset:35840
	ds_read_b128 v[174:177], v254 offset:49152
	ds_read_b128 v[184:187], v254 offset:50176
	ds_read_b128 v[188:191], v254 offset:51200
	ds_read_b128 v[210:213], v254 offset:52224
	global_load_lds_dwordx4 v168, s[0:1]
	s_mov_b32 m0, s43
	ds_read_b128 v[214:217], v181 offset:32768
	ds_read_b128 v[218:221], v181 offset:33792
	ds_read_b128 v[222:225], v181 offset:34816
	ds_read_b128 v[226:229], v181 offset:35840
	ds_read_b128 v[230:233], v181 offset:36864
	ds_read_b128 v[234:237], v181 offset:37888
	ds_read_b128 v[238:241], v181 offset:38912
	ds_read_b128 v[242:245], v181 offset:39936
	global_load_lds_dwordx4 v164, s[0:1]
	s_waitcnt vmcnt(8) lgkmcnt(0)
	s_barrier
	s_setprio 1
	v_mfma_f32_16x16x32_bf16 v[124:127], v[128:131], v[214:217], v[124:127]
	v_mfma_f32_16x16x32_bf16 v[120:123], v[136:139], v[214:217], v[120:123]
	v_mfma_f32_16x16x32_bf16 v[108:111], v[128:131], v[222:225], v[108:111]
	v_mfma_f32_16x16x32_bf16 v[104:107], v[136:139], v[222:225], v[104:107]
	v_mfma_f32_16x16x32_bf16 v[92:95], v[128:131], v[230:233], v[92:95]
	v_mfma_f32_16x16x32_bf16 v[88:91], v[136:139], v[230:233], v[88:91]
	v_mfma_f32_16x16x32_bf16 v[76:79], v[128:131], v[238:241], v[76:79]
	v_mfma_f32_16x16x32_bf16 v[72:75], v[136:139], v[238:241], v[72:75]
	v_mfma_f32_16x16x32_bf16 v[124:127], v[132:135], v[218:221], v[124:127]
	v_mfma_f32_16x16x32_bf16 v[120:123], v[140:143], v[218:221], v[120:123]
	v_mfma_f32_16x16x32_bf16 v[108:111], v[132:135], v[226:229], v[108:111]
	v_mfma_f32_16x16x32_bf16 v[104:107], v[140:143], v[226:229], v[104:107]
	v_mfma_f32_16x16x32_bf16 v[92:95], v[132:135], v[234:237], v[92:95]
	v_mfma_f32_16x16x32_bf16 v[88:91], v[140:143], v[234:237], v[88:91]
	v_mfma_f32_16x16x32_bf16 v[76:79], v[132:135], v[242:245], v[76:79]
	v_mfma_f32_16x16x32_bf16 v[72:75], v[140:143], v[242:245], v[72:75]
	v_mfma_f32_16x16x32_bf16 v[116:119], v[174:177], v[214:217], v[116:119]
	v_mfma_f32_16x16x32_bf16 v[112:115], v[188:191], v[214:217], v[112:115]
	v_mfma_f32_16x16x32_bf16 v[100:103], v[174:177], v[222:225], v[100:103]
	v_mfma_f32_16x16x32_bf16 v[96:99], v[188:191], v[222:225], v[96:99]
	v_mfma_f32_16x16x32_bf16 v[84:87], v[174:177], v[230:233], v[84:87]
	v_mfma_f32_16x16x32_bf16 v[80:83], v[188:191], v[230:233], v[80:83]
	v_mfma_f32_16x16x32_bf16 v[68:71], v[174:177], v[238:241], v[68:71]
	v_mfma_f32_16x16x32_bf16 v[64:67], v[188:191], v[238:241], v[64:67]
	v_mfma_f32_16x16x32_bf16 v[116:119], v[184:187], v[218:221], v[116:119]
	v_mfma_f32_16x16x32_bf16 v[112:115], v[210:213], v[218:221], v[112:115]
	v_mfma_f32_16x16x32_bf16 v[100:103], v[184:187], v[226:229], v[100:103]
	v_mfma_f32_16x16x32_bf16 v[96:99], v[210:213], v[226:229], v[96:99]
	v_mfma_f32_16x16x32_bf16 v[84:87], v[184:187], v[234:237], v[84:87]
	v_mfma_f32_16x16x32_bf16 v[80:83], v[210:213], v[234:237], v[80:83]
	v_mfma_f32_16x16x32_bf16 v[68:71], v[184:187], v[242:245], v[68:71]
	v_mfma_f32_16x16x32_bf16 v[64:67], v[210:213], v[242:245], v[64:67]
	s_setprio 0
	s_barrier
	s_mov_b32 m0, s47
	s_add_u32 s0, s4, 0xb0080
	s_addc_u32 s1, s5, 0
	s_add_u32 s98, s4, 0x80
	s_addc_u32 s99, s5, 0
	ds_read_b128 v[214:217], v181 offset:49152
	ds_read_b128 v[218:221], v181 offset:50176
	global_load_lds_dwordx4 v166, s[98:99]
	s_mov_b32 m0, s48
	ds_read_b128 v[222:225], v181 offset:51200
	ds_read_b128 v[226:229], v181 offset:52224
	global_load_lds_dwordx4 v162, s[98:99]
	s_mov_b32 m0, s51
	ds_read_b128 v[230:233], v181 offset:53248
	global_load_lds_dwordx4 v166, s[0:1]
	s_mov_b32 m0, s52
	ds_read_b128 v[234:237], v181 offset:54272
	global_load_lds_dwordx4 v162, s[0:1]
	s_mov_b32 m0, s49
	s_add_u32 s100, s6, 0x80
	s_addc_u32 s101, s7, 0
	ds_read_b128 v[238:241], v181 offset:55296
	global_load_lds_dwordx4 v168, s[100:101]
	s_mov_b32 m0, s50
	ds_read_b128 v[242:245], v181 offset:56320
	global_load_lds_dwordx4 v164, s[100:101]
	s_waitcnt vmcnt(8) lgkmcnt(0)
	s_barrier
	s_setprio 1
	v_mfma_f32_16x16x32_bf16 v[60:63], v[128:131], v[214:217], v[60:63]
	v_mfma_f32_16x16x32_bf16 v[56:59], v[136:139], v[214:217], v[56:59]
	v_mfma_f32_16x16x32_bf16 v[44:47], v[128:131], v[222:225], v[44:47]
	v_mfma_f32_16x16x32_bf16 v[40:43], v[136:139], v[222:225], v[40:43]
	v_mfma_f32_16x16x32_bf16 v[28:31], v[128:131], v[230:233], v[28:31]
	v_mfma_f32_16x16x32_bf16 v[24:27], v[136:139], v[230:233], v[24:27]
	v_mfma_f32_16x16x32_bf16 v[12:15], v[128:131], v[238:241], v[12:15]
	v_mfma_f32_16x16x32_bf16 v[8:11], v[136:139], v[238:241], v[8:11]
	v_mfma_f32_16x16x32_bf16 v[60:63], v[132:135], v[218:221], v[60:63]
	v_mfma_f32_16x16x32_bf16 v[56:59], v[140:143], v[218:221], v[56:59]
	v_mfma_f32_16x16x32_bf16 v[44:47], v[132:135], v[226:229], v[44:47]
	v_mfma_f32_16x16x32_bf16 v[40:43], v[140:143], v[226:229], v[40:43]
	v_mfma_f32_16x16x32_bf16 v[28:31], v[132:135], v[234:237], v[28:31]
	v_mfma_f32_16x16x32_bf16 v[24:27], v[140:143], v[234:237], v[24:27]
	v_mfma_f32_16x16x32_bf16 v[12:15], v[132:135], v[242:245], v[12:15]
	v_mfma_f32_16x16x32_bf16 v[8:11], v[140:143], v[242:245], v[8:11]
	v_mfma_f32_16x16x32_bf16 v[52:55], v[174:177], v[214:217], v[52:55]
	v_mfma_f32_16x16x32_bf16 v[48:51], v[188:191], v[214:217], v[48:51]
	v_mfma_f32_16x16x32_bf16 v[36:39], v[174:177], v[222:225], v[36:39]
	v_mfma_f32_16x16x32_bf16 v[32:35], v[188:191], v[222:225], v[32:35]
	v_mfma_f32_16x16x32_bf16 v[20:23], v[174:177], v[230:233], v[20:23]
	v_mfma_f32_16x16x32_bf16 v[16:19], v[188:191], v[230:233], v[16:19]
	v_mfma_f32_16x16x32_bf16 v[4:7], v[174:177], v[238:241], v[4:7]
	v_mfma_f32_16x16x32_bf16 v[0:3], v[188:191], v[238:241], v[0:3]
	v_mfma_f32_16x16x32_bf16 v[52:55], v[184:187], v[218:221], v[52:55]
	v_mfma_f32_16x16x32_bf16 v[48:51], v[210:213], v[218:221], v[48:51]
	v_mfma_f32_16x16x32_bf16 v[36:39], v[184:187], v[226:229], v[36:39]
	v_mfma_f32_16x16x32_bf16 v[32:35], v[210:213], v[226:229], v[32:35]
	v_mfma_f32_16x16x32_bf16 v[20:23], v[184:187], v[234:237], v[20:23]
	v_mfma_f32_16x16x32_bf16 v[16:19], v[210:213], v[234:237], v[16:19]
	v_mfma_f32_16x16x32_bf16 v[4:7], v[184:187], v[242:245], v[4:7]
	v_mfma_f32_16x16x32_bf16 v[0:3], v[210:213], v[242:245], v[0:3]
	s_setprio 0
	s_barrier
	s_add_i32 s13, s13, 2
	s_add_u32 s10, s10, 0x100
	s_addc_u32 s11, s11, 0
	s_cmp_gt_u32 s13, 41
	s_mov_b64 s[0:1], s[2:3]
	s_cbranch_scc0 .LBB0_545
	s_and_b64 vcc, exec, s[22:23]
	s_cbranch_vccz .LBB0_548
	s_barrier

; #define PG8_STAGE(bufoff, gbase, voff) do { _Pragma("unroll") for (int _i = 0; _i < 2; ++_i) \
;         __builtin_amdgcn_global_load_lds((const unsigned*)((const char*)(gbase) + (voff)[_i]), (PG8_LAS unsigned*)(lds + (bufoff) + ldsw + _i * 8192), 16, 0, 0); } while (0)
; #define PG8_LDA(dst, b, h) do { _Pragma("unroll") for (int m = 0; m < 4; ++m) _Pragma("unroll") for (int k = 0; k < 2; ++k) dst[m][k] = *(const PG8_LAS bf16x8*)(lds + PG8_SA(b, h) + aoff + m * 2048 + k * 1024); } while (0)
; #define PG8_LDB(dst, b, h) do { _Pragma("unroll") for (int n = 0; n < 2; ++n) _Pragma("unroll") for (int k = 0; k < 2; ++k) dst[n][k] = *(const PG8_LAS bf16x8*)(lds + PG8_SB(b, h) + boff + n * 2048 + k * 1024); } while (0)
; #define PG8_MMA(ai, bj, At, Bt) do { __builtin_amdgcn_s_setprio(1); _Pragma("unroll") for (int m = 0; m < 4; ++m) _Pragma("unroll") for (int n = 0; n < 2; ++n) _Pragma("unroll") for (int k = 0; k < 2; ++k) \
;         acc[ai][bj][m][n] = __builtin_amdgcn_mfma_f32_16x16x32_bf16(Bt[n][k], At[m][k], acc[ai][bj][m][n], 0, 0, 0); __builtin_amdgcn_s_setprio(0); } while (0)
; #define PG8_WAIT_V(n) asm volatile("s_waitcnt vmcnt(" #n ")" ::: "memory")
; #define PG8_WAIT_L(n) asm volatile("s_waitcnt lgkmcnt(" #n ")" ::: "memory")
; #define PG8_BAR __builtin_amdgcn_s_barrier()
; #define PG8_SCHED __builtin_amdgcn_sched_barrier(0)
; template <class Epi, class Sched, bool ALIGN_EPI = false, bool SP2 = false>
; __device__ __forceinline__ void gemm_phase(PG8_LAS unsigned char* lds, const Gemm g, const Sched& S, const Epi& E) {
;     ...
;             PG8_LDB(B0, 0, 0); PG8_LDB(B1, 0, 1); PG8_SCHED; PG8_LDA(At, 0, 0); PG8_STAGE(PG8_SA(1, 1), a1 + hstep, voffA);
;             PG8_WAIT_V(8); PG8_WAIT_L(0); PG8_BAR; PG8_MMA(0, 0, At, B0); PG8_MMA(0, 1, At, B1); PG8_BAR; PG8_SCHED;
;             PG8_LDA(At, 0, 1); PG8_STAGE(PG8_SB(0, 0), b2, voffB); PG8_STAGE(PG8_SB(0, 1), b2 + hstep, voffB); PG8_STAGE(PG8_SA(0, 0), a2, voffA);
;             PG8_WAIT_V(8); PG8_WAIT_L(0); PG8_BAR; PG8_MMA(1, 0, At, B0); PG8_MMA(1, 1, At, B1); PG8_BAR; PG8_SCHED;
.Lsgi_peel:
	s_add_u32 s2, s0, 0xfffc0080
	s_addc_u32 s3, s1, -1
	s_cmp_eq_u32 s55, 12
	s_cselect_b32 s5, s13, s3
	s_cselect_b32 s4, s25, s2
	s_cselect_b32 s3, s23, s39
	s_cselect_b32 s2, s33, s38
	s_add_i32 m0, s6, 0xc000
	ds_read_b128 v[140:143], v254
	ds_read_b128 v[162:165], v254 offset:1024
	ds_read_b128 v[166:169], v254 offset:2048
	ds_read_b128 v[170:173], v254 offset:3072
	ds_read_b128 v[180:183], v254 offset:16384
	ds_read_b128 v[184:187], v254 offset:17408
	ds_read_b128 v[188:191], v254 offset:18432
	ds_read_b128 v[210:213], v254 offset:19456
	global_load_lds_dwordx4 v136, s[0:1]
	s_add_i32 m0, s6, 0xe000
	ds_read_b128 v[214:217], v178
	ds_read_b128 v[218:221], v178 offset:1024
	ds_read_b128 v[222:225], v178 offset:2048
	ds_read_b128 v[226:229], v178 offset:3072
	ds_read_b128 v[230:233], v178 offset:4096
	ds_read_b128 v[234:237], v178 offset:5120
	ds_read_b128 v[238:241], v178 offset:6144
	ds_read_b128 v[242:245], v178 offset:7168
	global_load_lds_dwordx4 v138, s[0:1]
	s_waitcnt vmcnt(8) lgkmcnt(0)
	s_barrier
	s_setprio 1
	v_mfma_f32_16x16x32_bf16 v[124:127], v[140:143], v[214:217], 0
	v_mfma_f32_16x16x32_bf16 v[120:123], v[166:169], v[214:217], 0
	v_mfma_f32_16x16x32_bf16 v[108:111], v[140:143], v[222:225], 0
	v_mfma_f32_16x16x32_bf16 v[104:107], v[166:169], v[222:225], 0
	v_mfma_f32_16x16x32_bf16 v[92:95], v[140:143], v[230:233], 0
	v_mfma_f32_16x16x32_bf16 v[88:91], v[166:169], v[230:233], 0
	v_mfma_f32_16x16x32_bf16 v[76:79], v[140:143], v[238:241], 0
	v_mfma_f32_16x16x32_bf16 v[72:75], v[166:169], v[238:241], 0
	v_mfma_f32_16x16x32_bf16 v[124:127], v[162:165], v[218:221], v[124:127]
	v_mfma_f32_16x16x32_bf16 v[120:123], v[170:173], v[218:221], v[120:123]
	v_mfma_f32_16x16x32_bf16 v[108:111], v[162:165], v[226:229], v[108:111]
	v_mfma_f32_16x16x32_bf16 v[104:107], v[170:173], v[226:229], v[104:107]
	v_mfma_f32_16x16x32_bf16 v[92:95], v[162:165], v[234:237], v[92:95]
	v_mfma_f32_16x16x32_bf16 v[88:91], v[170:173], v[234:237], v[88:91]
	v_mfma_f32_16x16x32_bf16 v[76:79], v[162:165], v[242:245], v[76:79]
	v_mfma_f32_16x16x32_bf16 v[72:75], v[170:173], v[242:245], v[72:75]
	v_mfma_f32_16x16x32_bf16 v[116:119], v[180:183], v[214:217], 0
	v_mfma_f32_16x16x32_bf16 v[112:115], v[188:191], v[214:217], 0
	v_mfma_f32_16x16x32_bf16 v[100:103], v[180:183], v[222:225], 0
	v_mfma_f32_16x16x32_bf16 v[96:99], v[188:191], v[222:225], 0
	v_mfma_f32_16x16x32_bf16 v[84:87], v[180:183], v[230:233], 0
	v_mfma_f32_16x16x32_bf16 v[80:83], v[188:191], v[230:233], 0
	v_mfma_f32_16x16x32_bf16 v[68:71], v[180:183], v[238:241], 0
	v_mfma_f32_16x16x32_bf16 v[64:67], v[188:191], v[238:241], 0
	v_mfma_f32_16x16x32_bf16 v[116:119], v[184:187], v[218:221], v[116:119]
	v_mfma_f32_16x16x32_bf16 v[112:115], v[210:213], v[218:221], v[112:115]
	v_mfma_f32_16x16x32_bf16 v[100:103], v[184:187], v[226:229], v[100:103]
	v_mfma_f32_16x16x32_bf16 v[96:99], v[210:213], v[226:229], v[96:99]
	v_mfma_f32_16x16x32_bf16 v[84:87], v[184:187], v[234:237], v[84:87]
	v_mfma_f32_16x16x32_bf16 v[80:83], v[210:213], v[234:237], v[80:83]
	v_mfma_f32_16x16x32_bf16 v[68:71], v[184:187], v[242:245], v[68:71]
	v_mfma_f32_16x16x32_bf16 v[64:67], v[210:213], v[242:245], v[64:67]
	s_setprio 0
	s_barrier
	s_mov_b32 m0, s31
	s_add_u32 s56, s2, 0x40000
	s_addc_u32 s57, s3, 0
	ds_read_b128 v[214:217], v178 offset:16384
	ds_read_b128 v[218:221], v178 offset:17408
	global_load_lds_dwordx4 v132, s[2:3]
	s_mov_b32 m0, s34
	ds_read_b128 v[222:225], v178 offset:18432
	ds_read_b128 v[226:229], v178 offset:19456
	global_load_lds_dwordx4 v128, s[2:3]
	s_mov_b32 m0, s35
	ds_read_b128 v[230:233], v178 offset:20480
	global_load_lds_dwordx4 v132, s[56:57]
	s_mov_b32 m0, s40
	ds_read_b128 v[234:237], v178 offset:21504
	global_load_lds_dwordx4 v128, s[56:57]
	s_mov_b32 m0, s6
	ds_read_b128 v[238:241], v178 offset:22528
	global_load_lds_dwordx4 v134, s[4:5]
	s_mov_b32 m0, s41
	ds_read_b128 v[242:245], v178 offset:23552
	global_load_lds_dwordx4 v130, s[4:5]
	s_waitcnt vmcnt(8) lgkmcnt(0)
	s_barrier
	s_setprio 1
	v_mfma_f32_16x16x32_bf16 v[60:63], v[140:143], v[214:217], 0
	v_mfma_f32_16x16x32_bf16 v[56:59], v[166:169], v[214:217], 0
	v_mfma_f32_16x16x32_bf16 v[44:47], v[140:143], v[222:225], 0
	v_mfma_f32_16x16x32_bf16 v[40:43], v[166:169], v[222:225], 0
	v_mfma_f32_16x16x32_bf16 v[28:31], v[140:143], v[230:233], 0
	v_mfma_f32_16x16x32_bf16 v[24:27], v[166:169], v[230:233], 0
	v_mfma_f32_16x16x32_bf16 v[12:15], v[140:143], v[238:241], 0
	v_mfma_f32_16x16x32_bf16 v[8:11], v[166:169], v[238:241], 0
	v_mfma_f32_16x16x32_bf16 v[60:63], v[162:165], v[218:221], v[60:63]
	v_mfma_f32_16x16x32_bf16 v[56:59], v[170:173], v[218:221], v[56:59]
	v_mfma_f32_16x16x32_bf16 v[44:47], v[162:165], v[226:229], v[44:47]
	v_mfma_f32_16x16x32_bf16 v[40:43], v[170:173], v[226:229], v[40:43]
	v_mfma_f32_16x16x32_bf16 v[28:31], v[162:165], v[234:237], v[28:31]
	v_mfma_f32_16x16x32_bf16 v[24:27], v[170:173], v[234:237], v[24:27]
	v_mfma_f32_16x16x32_bf16 v[12:15], v[162:165], v[242:245], v[12:15]
	v_mfma_f32_16x16x32_bf16 v[8:11], v[170:173], v[242:245], v[8:11]
	v_mfma_f32_16x16x32_bf16 v[52:55], v[180:183], v[214:217], 0
	v_mfma_f32_16x16x32_bf16 v[48:51], v[188:191], v[214:217], 0
	v_mfma_f32_16x16x32_bf16 v[36:39], v[180:183], v[222:225], 0
	v_mfma_f32_16x16x32_bf16 v[32:35], v[188:191], v[222:225], 0
	v_mfma_f32_16x16x32_bf16 v[20:23], v[180:183], v[230:233], 0
	v_mfma_f32_16x16x32_bf16 v[16:19], v[188:191], v[230:233], 0
	v_mfma_f32_16x16x32_bf16 v[4:7], v[180:183], v[238:241], 0
	v_mfma_f32_16x16x32_bf16 v[0:3], v[188:191], v[238:241], 0
	v_mfma_f32_16x16x32_bf16 v[52:55], v[184:187], v[218:221], v[52:55]
	v_mfma_f32_16x16x32_bf16 v[48:51], v[210:213], v[218:221], v[48:51]
	v_mfma_f32_16x16x32_bf16 v[36:39], v[184:187], v[226:229], v[36:39]
	v_mfma_f32_16x16x32_bf16 v[32:35], v[210:213], v[226:229], v[32:35]
	v_mfma_f32_16x16x32_bf16 v[20:23], v[184:187], v[234:237], v[20:23]
	v_mfma_f32_16x16x32_bf16 v[16:19], v[210:213], v[234:237], v[16:19]
	v_mfma_f32_16x16x32_bf16 v[4:7], v[184:187], v[242:245], v[4:7]
	v_mfma_f32_16x16x32_bf16 v[0:3], v[210:213], v[242:245], v[0:3]
	s_setprio 0
	s_barrier
; #define PG8_STAGE(bufoff, gbase, voff) do { _Pragma("unroll") for (int _i = 0; _i < 2; ++_i) \
;         __builtin_amdgcn_global_load_lds((const unsigned*)((const char*)(gbase) + (voff)[_i]), (PG8_LAS unsigned*)(lds + (bufoff) + ldsw + _i * 8192), 16, 0, 0); } while (0)
; #define PG8_LDA(dst, b, h) do { _Pragma("unroll") for (int m = 0; m < 4; ++m) _Pragma("unroll") for (int k = 0; k < 2; ++k) dst[m][k] = *(const PG8_LAS bf16x8*)(lds + PG8_SA(b, h) + aoff + m * 2048 + k * 1024); } while (0)
; #define PG8_LDB(dst, b, h) do { _Pragma("unroll") for (int n = 0; n < 2; ++n) _Pragma("unroll") for (int k = 0; k < 2; ++k) dst[n][k] = *(const PG8_LAS bf16x8*)(lds + PG8_SB(b, h) + boff + n * 2048 + k * 1024); } while (0)
; #define PG8_MMA(ai, bj, At, Bt) do { __builtin_amdgcn_s_setprio(1); _Pragma("unroll") for (int m = 0; m < 4; ++m) _Pragma("unroll") for (int n = 0; n < 2; ++n) _Pragma("unroll") for (int k = 0; k < 2; ++k) \
;         acc[ai][bj][m][n] = __builtin_amdgcn_mfma_f32_16x16x32_bf16(Bt[n][k], At[m][k], acc[ai][bj][m][n], 0, 0, 0); __builtin_amdgcn_s_setprio(0); } while (0)
; #define PG8_WAIT_V(n) asm volatile("s_waitcnt vmcnt(" #n ")" ::: "memory")
; #define PG8_WAIT_L(n) asm volatile("s_waitcnt lgkmcnt(" #n ")" ::: "memory")
; #define PG8_BAR __builtin_amdgcn_s_barrier()
; #define PG8_SCHED __builtin_amdgcn_sched_barrier(0)
; template <class Epi, class Sched, bool ALIGN_EPI = false, bool SP2 = false>
; __device__ __forceinline__ void gemm_phase(PG8_LAS unsigned char* lds, const Gemm g, const Sched& S, const Epi& E) {
;     ...
;             PG8_LDB(B0, 1, 0); PG8_LDB(B1, 1, 1); PG8_SCHED; PG8_LDA(At, 1, 0); PG8_STAGE(PG8_SA(0, 1), a2 + hstep, voffA);
;             PG8_WAIT_V(8); PG8_WAIT_L(0); PG8_BAR; PG8_MMA(0, 0, At, B0); PG8_MMA(0, 1, At, B1); PG8_BAR; PG8_SCHED;
;             PG8_LDA(At, 1, 1); PG8_STAGE(PG8_SB(1, 0), b3, voffB); PG8_STAGE(PG8_SB(1, 1), b3 + hstep, voffB); PG8_STAGE(PG8_SA(1, 0), a3, voffA);
;             PG8_WAIT_V(8); PG8_WAIT_L(0); PG8_BAR; PG8_MMA(1, 0, At, B0); PG8_MMA(1, 1, At, B1); PG8_BAR; PG8_SCHED;
	s_add_u32 s4, s4, 0x40000
	s_addc_u32 s5, s5, 0
	s_mov_b32 m0, s42
	ds_read_b128 v[140:143], v254 offset:32768
	ds_read_b128 v[162:165], v254 offset:33792
	ds_read_b128 v[166:169], v254 offset:34816
	ds_read_b128 v[170:173], v254 offset:35840
	ds_read_b128 v[180:183], v254 offset:49152
	ds_read_b128 v[184:187], v254 offset:50176
	ds_read_b128 v[188:191], v254 offset:51200
	ds_read_b128 v[210:213], v254 offset:52224
	global_load_lds_dwordx4 v134, s[4:5]
	s_mov_b32 m0, s43
	ds_read_b128 v[214:217], v178 offset:32768
	ds_read_b128 v[218:221], v178 offset:33792
	ds_read_b128 v[222:225], v178 offset:34816
	ds_read_b128 v[226:229], v178 offset:35840
	ds_read_b128 v[230:233], v178 offset:36864
	ds_read_b128 v[234:237], v178 offset:37888
	ds_read_b128 v[238:241], v178 offset:38912
	ds_read_b128 v[242:245], v178 offset:39936
	global_load_lds_dwordx4 v130, s[4:5]
	s_waitcnt vmcnt(8) lgkmcnt(0)
	s_barrier
	s_setprio 1
	v_mfma_f32_16x16x32_bf16 v[124:127], v[140:143], v[214:217], v[124:127]
	v_mfma_f32_16x16x32_bf16 v[120:123], v[166:169], v[214:217], v[120:123]
	v_mfma_f32_16x16x32_bf16 v[108:111], v[140:143], v[222:225], v[108:111]
	v_mfma_f32_16x16x32_bf16 v[104:107], v[166:169], v[222:225], v[104:107]
	v_mfma_f32_16x16x32_bf16 v[92:95], v[140:143], v[230:233], v[92:95]
	v_mfma_f32_16x16x32_bf16 v[88:91], v[166:169], v[230:233], v[88:91]
	v_mfma_f32_16x16x32_bf16 v[76:79], v[140:143], v[238:241], v[76:79]
	v_mfma_f32_16x16x32_bf16 v[72:75], v[166:169], v[238:241], v[72:75]
	v_mfma_f32_16x16x32_bf16 v[124:127], v[162:165], v[218:221], v[124:127]
	v_mfma_f32_16x16x32_bf16 v[120:123], v[170:173], v[218:221], v[120:123]
	v_mfma_f32_16x16x32_bf16 v[108:111], v[162:165], v[226:229], v[108:111]
	v_mfma_f32_16x16x32_bf16 v[104:107], v[170:173], v[226:229], v[104:107]
	v_mfma_f32_16x16x32_bf16 v[92:95], v[162:165], v[234:237], v[92:95]
	v_mfma_f32_16x16x32_bf16 v[88:91], v[170:173], v[234:237], v[88:91]
	v_mfma_f32_16x16x32_bf16 v[76:79], v[162:165], v[242:245], v[76:79]
	v_mfma_f32_16x16x32_bf16 v[72:75], v[170:173], v[242:245], v[72:75]
	v_mfma_f32_16x16x32_bf16 v[116:119], v[180:183], v[214:217], v[116:119]
	v_mfma_f32_16x16x32_bf16 v[112:115], v[188:191], v[214:217], v[112:115]
	v_mfma_f32_16x16x32_bf16 v[100:103], v[180:183], v[222:225], v[100:103]
	v_mfma_f32_16x16x32_bf16 v[96:99], v[188:191], v[222:225], v[96:99]
	v_mfma_f32_16x16x32_bf16 v[84:87], v[180:183], v[230:233], v[84:87]
	v_mfma_f32_16x16x32_bf16 v[80:83], v[188:191], v[230:233], v[80:83]
	v_mfma_f32_16x16x32_bf16 v[68:71], v[180:183], v[238:241], v[68:71]
	v_mfma_f32_16x16x32_bf16 v[64:67], v[188:191], v[238:241], v[64:67]
	v_mfma_f32_16x16x32_bf16 v[116:119], v[184:187], v[218:221], v[116:119]
	v_mfma_f32_16x16x32_bf16 v[112:115], v[210:213], v[218:221], v[112:115]
	v_mfma_f32_16x16x32_bf16 v[100:103], v[184:187], v[226:229], v[100:103]
	v_mfma_f32_16x16x32_bf16 v[96:99], v[210:213], v[226:229], v[96:99]
	v_mfma_f32_16x16x32_bf16 v[84:87], v[184:187], v[234:237], v[84:87]
	v_mfma_f32_16x16x32_bf16 v[80:83], v[210:213], v[234:237], v[80:83]
	v_mfma_f32_16x16x32_bf16 v[68:71], v[184:187], v[242:245], v[68:71]
	v_mfma_f32_16x16x32_bf16 v[64:67], v[210:213], v[242:245], v[64:67]
	s_setprio 0
	s_barrier
	s_mov_b32 m0, s48
	s_add_u32 s2, s2, 0x40080
	s_addc_u32 s3, s3, 0
	s_add_u32 s98, s2, 0xfffc0000
	s_addc_u32 s99, s3, -1
	ds_read_b128 v[214:217], v178 offset:49152
	ds_read_b128 v[218:221], v178 offset:50176
	global_load_lds_dwordx4 v132, s[98:99]
	s_mov_b32 m0, s49
	ds_read_b128 v[222:225], v178 offset:51200
	ds_read_b128 v[226:229], v178 offset:52224
	global_load_lds_dwordx4 v128, s[98:99]
	s_mov_b32 m0, s52
	ds_read_b128 v[230:233], v178 offset:53248
	global_load_lds_dwordx4 v132, s[2:3]
	s_mov_b32 m0, s53
	ds_read_b128 v[234:237], v178 offset:54272
	global_load_lds_dwordx4 v128, s[2:3]
	s_mov_b32 m0, s50
	s_add_u32 s100, s4, 0xfffc0080
	s_addc_u32 s101, s5, -1
	ds_read_b128 v[238:241], v178 offset:55296
	global_load_lds_dwordx4 v134, s[100:101]
	s_mov_b32 m0, s51
	ds_read_b128 v[242:245], v178 offset:56320
	global_load_lds_dwordx4 v130, s[100:101]
	s_waitcnt vmcnt(8) lgkmcnt(0)
	s_barrier
	s_setprio 1
	v_mfma_f32_16x16x32_bf16 v[60:63], v[140:143], v[214:217], v[60:63]
	v_mfma_f32_16x16x32_bf16 v[56:59], v[166:169], v[214:217], v[56:59]
	v_mfma_f32_16x16x32_bf16 v[44:47], v[140:143], v[222:225], v[44:47]
	v_mfma_f32_16x16x32_bf16 v[40:43], v[166:169], v[222:225], v[40:43]
	v_mfma_f32_16x16x32_bf16 v[28:31], v[140:143], v[230:233], v[28:31]
	v_mfma_f32_16x16x32_bf16 v[24:27], v[166:169], v[230:233], v[24:27]
	v_mfma_f32_16x16x32_bf16 v[12:15], v[140:143], v[238:241], v[12:15]
	v_mfma_f32_16x16x32_bf16 v[8:11], v[166:169], v[238:241], v[8:11]
	v_mfma_f32_16x16x32_bf16 v[60:63], v[162:165], v[218:221], v[60:63]
	v_mfma_f32_16x16x32_bf16 v[56:59], v[170:173], v[218:221], v[56:59]
	v_mfma_f32_16x16x32_bf16 v[44:47], v[162:165], v[226:229], v[44:47]
	v_mfma_f32_16x16x32_bf16 v[40:43], v[170:173], v[226:229], v[40:43]
	v_mfma_f32_16x16x32_bf16 v[28:31], v[162:165], v[234:237], v[28:31]
	v_mfma_f32_16x16x32_bf16 v[24:27], v[170:173], v[234:237], v[24:27]
	v_mfma_f32_16x16x32_bf16 v[12:15], v[162:165], v[242:245], v[12:15]
	v_mfma_f32_16x16x32_bf16 v[8:11], v[170:173], v[242:245], v[8:11]
	v_mfma_f32_16x16x32_bf16 v[52:55], v[180:183], v[214:217], v[52:55]
	v_mfma_f32_16x16x32_bf16 v[48:51], v[188:191], v[214:217], v[48:51]
	v_mfma_f32_16x16x32_bf16 v[36:39], v[180:183], v[222:225], v[36:39]
	v_mfma_f32_16x16x32_bf16 v[32:35], v[188:191], v[222:225], v[32:35]
	v_mfma_f32_16x16x32_bf16 v[20:23], v[180:183], v[230:233], v[20:23]
	v_mfma_f32_16x16x32_bf16 v[16:19], v[188:191], v[230:233], v[16:19]
	v_mfma_f32_16x16x32_bf16 v[4:7], v[180:183], v[238:241], v[4:7]
	v_mfma_f32_16x16x32_bf16 v[0:3], v[188:191], v[238:241], v[0:3]
	v_mfma_f32_16x16x32_bf16 v[52:55], v[184:187], v[218:221], v[52:55]
	v_mfma_f32_16x16x32_bf16 v[48:51], v[210:213], v[218:221], v[48:51]
	v_mfma_f32_16x16x32_bf16 v[36:39], v[184:187], v[226:229], v[36:39]
	v_mfma_f32_16x16x32_bf16 v[32:35], v[210:213], v[226:229], v[32:35]
	v_mfma_f32_16x16x32_bf16 v[20:23], v[184:187], v[234:237], v[20:23]
	v_mfma_f32_16x16x32_bf16 v[16:19], v[210:213], v[234:237], v[16:19]
	v_mfma_f32_16x16x32_bf16 v[4:7], v[184:187], v[242:245], v[4:7]
	v_mfma_f32_16x16x32_bf16 v[0:3], v[210:213], v[242:245], v[0:3]
	s_setprio 0
	s_barrier
	s_add_i32 s55, s55, 2
	s_add_u32 s0, s0, 0x100
	s_addc_u32 s1, s1, 0
	s_add_u32 s38, s38, 0x100
	s_addc_u32 s39, s39, 0
	s_cmp_gt_u32 s55, 13
; #define PG8_STAGE(bufoff, gbase, voff) do { _Pragma("unroll") for (int _i = 0; _i < 2; ++_i) \
;         __builtin_amdgcn_global_load_lds((const unsigned*)((const char*)(gbase) + (voff)[_i]), (PG8_LAS unsigned*)(lds + (bufoff) + ldsw + _i * 8192), 16, 0, 0); } while (0)
; #define PG8_LDA(dst, b, h) do { _Pragma("unroll") for (int m = 0; m < 4; ++m) _Pragma("unroll") for (int k = 0; k < 2; ++k) dst[m][k] = *(const PG8_LAS bf16x8*)(lds + PG8_SA(b, h) + aoff + m * 2048 + k * 1024); } while (0)
; #define PG8_LDB(dst, b, h) do { _Pragma("unroll") for (int n = 0; n < 2; ++n) _Pragma("unroll") for (int k = 0; k < 2; ++k) dst[n][k] = *(const PG8_LAS bf16x8*)(lds + PG8_SB(b, h) + boff + n * 2048 + k * 1024); } while (0)
; #define PG8_MMA(ai, bj, At, Bt) do { __builtin_amdgcn_s_setprio(1); _Pragma("unroll") for (int m = 0; m < 4; ++m) _Pragma("unroll") for (int n = 0; n < 2; ++n) _Pragma("unroll") for (int k = 0; k < 2; ++k) \
;         acc[ai][bj][m][n] = __builtin_amdgcn_mfma_f32_16x16x32_bf16(Bt[n][k], At[m][k], acc[ai][bj][m][n], 0, 0, 0); __builtin_amdgcn_s_setprio(0); } while (0)
; #define PG8_WAIT_V(n) asm volatile("s_waitcnt vmcnt(" #n ")" ::: "memory")
; #define PG8_WAIT_L(n) asm volatile("s_waitcnt lgkmcnt(" #n ")" ::: "memory")
; #define PG8_BAR __builtin_amdgcn_s_barrier()
; #define PG8_SCHED __builtin_amdgcn_sched_barrier(0)
; template <class Epi, class Sched, bool ALIGN_EPI = false, bool SP2 = false>
; __device__ __forceinline__ void gemm_phase(PG8_LAS unsigned char* lds, const Gemm g, const Sched& S, const Epi& E) {
;     ...
;             PG8_LDB(B0, 0, 0); PG8_LDB(B1, 0, 1); PG8_SCHED; PG8_LDA(At, 0, 0); PG8_STAGE(PG8_SA(1, 1), a1 + hstep, voffA);
;             PG8_WAIT_V(8); PG8_WAIT_L(0); PG8_BAR; PG8_MMA(0, 0, At, B0); PG8_MMA(0, 1, At, B1); PG8_BAR; PG8_SCHED;
;             PG8_LDA(At, 0, 1); PG8_STAGE(PG8_SB(0, 0), b2, voffB); PG8_STAGE(PG8_SB(0, 1), b2 + hstep, voffB); PG8_STAGE(PG8_SA(0, 0), a2, voffA);
;             PG8_WAIT_V(8); PG8_WAIT_L(0); PG8_BAR; PG8_MMA(1, 0, At, B0); PG8_MMA(1, 1, At, B1); PG8_BAR; PG8_SCHED;
.LBB0_749:
	s_add_u32 s2, s0, 0xfffc0080
	s_addc_u32 s3, s1, -1
	s_cmp_eq_u32 s55, 12
	s_cselect_b32 s5, s13, s3
	s_cselect_b32 s4, s25, s2
	s_cselect_b32 s3, s23, s39
	s_cselect_b32 s2, s33, s38
	s_add_i32 m0, s6, 0xc000
	ds_read_b128 v[140:143], v254
	ds_read_b128 v[162:165], v254 offset:1024
	ds_read_b128 v[166:169], v254 offset:2048
	ds_read_b128 v[170:173], v254 offset:3072
	ds_read_b128 v[180:183], v254 offset:16384
	ds_read_b128 v[184:187], v254 offset:17408
	ds_read_b128 v[188:191], v254 offset:18432
	ds_read_b128 v[210:213], v254 offset:19456
	global_load_lds_dwordx4 v136, s[0:1]
	s_add_i32 m0, s6, 0xe000
	ds_read_b128 v[214:217], v178
	ds_read_b128 v[218:221], v178 offset:1024
	ds_read_b128 v[222:225], v178 offset:2048
	ds_read_b128 v[226:229], v178 offset:3072
	ds_read_b128 v[230:233], v178 offset:4096
	ds_read_b128 v[234:237], v178 offset:5120
	ds_read_b128 v[238:241], v178 offset:6144
	ds_read_b128 v[242:245], v178 offset:7168
	global_load_lds_dwordx4 v138, s[0:1]
	s_waitcnt vmcnt(8) lgkmcnt(0)
	s_barrier
	s_setprio 1
	v_mfma_f32_16x16x32_bf16 v[124:127], v[140:143], v[214:217], v[124:127]
	v_mfma_f32_16x16x32_bf16 v[120:123], v[166:169], v[214:217], v[120:123]
	v_mfma_f32_16x16x32_bf16 v[108:111], v[140:143], v[222:225], v[108:111]
	v_mfma_f32_16x16x32_bf16 v[104:107], v[166:169], v[222:225], v[104:107]
	v_mfma_f32_16x16x32_bf16 v[92:95], v[140:143], v[230:233], v[92:95]
	v_mfma_f32_16x16x32_bf16 v[88:91], v[166:169], v[230:233], v[88:91]
	v_mfma_f32_16x16x32_bf16 v[76:79], v[140:143], v[238:241], v[76:79]
	v_mfma_f32_16x16x32_bf16 v[72:75], v[166:169], v[238:241], v[72:75]
	v_mfma_f32_16x16x32_bf16 v[124:127], v[162:165], v[218:221], v[124:127]
	v_mfma_f32_16x16x32_bf16 v[120:123], v[170:173], v[218:221], v[120:123]
	v_mfma_f32_16x16x32_bf16 v[108:111], v[162:165], v[226:229], v[108:111]
	v_mfma_f32_16x16x32_bf16 v[104:107], v[170:173], v[226:229], v[104:107]
	v_mfma_f32_16x16x32_bf16 v[92:95], v[162:165], v[234:237], v[92:95]
	v_mfma_f32_16x16x32_bf16 v[88:91], v[170:173], v[234:237], v[88:91]
	v_mfma_f32_16x16x32_bf16 v[76:79], v[162:165], v[242:245], v[76:79]
	v_mfma_f32_16x16x32_bf16 v[72:75], v[170:173], v[242:245], v[72:75]
	v_mfma_f32_16x16x32_bf16 v[116:119], v[180:183], v[214:217], v[116:119]
	v_mfma_f32_16x16x32_bf16 v[112:115], v[188:191], v[214:217], v[112:115]
	v_mfma_f32_16x16x32_bf16 v[100:103], v[180:183], v[222:225], v[100:103]
	v_mfma_f32_16x16x32_bf16 v[96:99], v[188:191], v[222:225], v[96:99]
	v_mfma_f32_16x16x32_bf16 v[84:87], v[180:183], v[230:233], v[84:87]
	v_mfma_f32_16x16x32_bf16 v[80:83], v[188:191], v[230:233], v[80:83]
	v_mfma_f32_16x16x32_bf16 v[68:71], v[180:183], v[238:241], v[68:71]
	v_mfma_f32_16x16x32_bf16 v[64:67], v[188:191], v[238:241], v[64:67]
	v_mfma_f32_16x16x32_bf16 v[116:119], v[184:187], v[218:221], v[116:119]
	v_mfma_f32_16x16x32_bf16 v[112:115], v[210:213], v[218:221], v[112:115]
	v_mfma_f32_16x16x32_bf16 v[100:103], v[184:187], v[226:229], v[100:103]
	v_mfma_f32_16x16x32_bf16 v[96:99], v[210:213], v[226:229], v[96:99]
	v_mfma_f32_16x16x32_bf16 v[84:87], v[184:187], v[234:237], v[84:87]
	v_mfma_f32_16x16x32_bf16 v[80:83], v[210:213], v[234:237], v[80:83]
	v_mfma_f32_16x16x32_bf16 v[68:71], v[184:187], v[242:245], v[68:71]
	v_mfma_f32_16x16x32_bf16 v[64:67], v[210:213], v[242:245], v[64:67]
	s_setprio 0
	s_barrier
	s_mov_b32 m0, s31
	s_add_u32 s56, s2, 0x40000
	s_addc_u32 s57, s3, 0
	ds_read_b128 v[214:217], v178 offset:16384
	ds_read_b128 v[218:221], v178 offset:17408
	global_load_lds_dwordx4 v132, s[2:3]
	s_mov_b32 m0, s34
	ds_read_b128 v[222:225], v178 offset:18432
	ds_read_b128 v[226:229], v178 offset:19456
	global_load_lds_dwordx4 v128, s[2:3]
	s_mov_b32 m0, s35
	ds_read_b128 v[230:233], v178 offset:20480
	global_load_lds_dwordx4 v132, s[56:57]
	s_mov_b32 m0, s40
	ds_read_b128 v[234:237], v178 offset:21504
	global_load_lds_dwordx4 v128, s[56:57]
	s_mov_b32 m0, s6
	ds_read_b128 v[238:241], v178 offset:22528
	global_load_lds_dwordx4 v134, s[4:5]
	s_mov_b32 m0, s41
	ds_read_b128 v[242:245], v178 offset:23552
	global_load_lds_dwordx4 v130, s[4:5]
	s_waitcnt vmcnt(8) lgkmcnt(0)
	s_barrier
	s_setprio 1
	v_mfma_f32_16x16x32_bf16 v[60:63], v[140:143], v[214:217], v[60:63]
	v_mfma_f32_16x16x32_bf16 v[56:59], v[166:169], v[214:217], v[56:59]
	v_mfma_f32_16x16x32_bf16 v[44:47], v[140:143], v[222:225], v[44:47]
	v_mfma_f32_16x16x32_bf16 v[40:43], v[166:169], v[222:225], v[40:43]
	v_mfma_f32_16x16x32_bf16 v[28:31], v[140:143], v[230:233], v[28:31]
	v_mfma_f32_16x16x32_bf16 v[24:27], v[166:169], v[230:233], v[24:27]
	v_mfma_f32_16x16x32_bf16 v[12:15], v[140:143], v[238:241], v[12:15]
	v_mfma_f32_16x16x32_bf16 v[8:11], v[166:169], v[238:241], v[8:11]
	v_mfma_f32_16x16x32_bf16 v[60:63], v[162:165], v[218:221], v[60:63]
	v_mfma_f32_16x16x32_bf16 v[56:59], v[170:173], v[218:221], v[56:59]
	v_mfma_f32_16x16x32_bf16 v[44:47], v[162:165], v[226:229], v[44:47]
	v_mfma_f32_16x16x32_bf16 v[40:43], v[170:173], v[226:229], v[40:43]
	v_mfma_f32_16x16x32_bf16 v[28:31], v[162:165], v[234:237], v[28:31]
	v_mfma_f32_16x16x32_bf16 v[24:27], v[170:173], v[234:237], v[24:27]
	v_mfma_f32_16x16x32_bf16 v[12:15], v[162:165], v[242:245], v[12:15]
	v_mfma_f32_16x16x32_bf16 v[8:11], v[170:173], v[242:245], v[8:11]
	v_mfma_f32_16x16x32_bf16 v[52:55], v[180:183], v[214:217], v[52:55]
	v_mfma_f32_16x16x32_bf16 v[48:51], v[188:191], v[214:217], v[48:51]
	v_mfma_f32_16x16x32_bf16 v[36:39], v[180:183], v[222:225], v[36:39]
	v_mfma_f32_16x16x32_bf16 v[32:35], v[188:191], v[222:225], v[32:35]
	v_mfma_f32_16x16x32_bf16 v[20:23], v[180:183], v[230:233], v[20:23]
	v_mfma_f32_16x16x32_bf16 v[16:19], v[188:191], v[230:233], v[16:19]
	v_mfma_f32_16x16x32_bf16 v[4:7], v[180:183], v[238:241], v[4:7]
	v_mfma_f32_16x16x32_bf16 v[0:3], v[188:191], v[238:241], v[0:3]
	v_mfma_f32_16x16x32_bf16 v[52:55], v[184:187], v[218:221], v[52:55]
	v_mfma_f32_16x16x32_bf16 v[48:51], v[210:213], v[218:221], v[48:51]
	v_mfma_f32_16x16x32_bf16 v[36:39], v[184:187], v[226:229], v[36:39]
	v_mfma_f32_16x16x32_bf16 v[32:35], v[210:213], v[226:229], v[32:35]
	v_mfma_f32_16x16x32_bf16 v[20:23], v[184:187], v[234:237], v[20:23]
	v_mfma_f32_16x16x32_bf16 v[16:19], v[210:213], v[234:237], v[16:19]
	v_mfma_f32_16x16x32_bf16 v[4:7], v[184:187], v[242:245], v[4:7]
	v_mfma_f32_16x16x32_bf16 v[0:3], v[210:213], v[242:245], v[0:3]
	s_setprio 0
	s_barrier
; #define PG8_STAGE(bufoff, gbase, voff) do { _Pragma("unroll") for (int _i = 0; _i < 2; ++_i) \
;         __builtin_amdgcn_global_load_lds((const unsigned*)((const char*)(gbase) + (voff)[_i]), (PG8_LAS unsigned*)(lds + (bufoff) + ldsw + _i * 8192), 16, 0, 0); } while (0)
; #define PG8_LDA(dst, b, h) do { _Pragma("unroll") for (int m = 0; m < 4; ++m) _Pragma("unroll") for (int k = 0; k < 2; ++k) dst[m][k] = *(const PG8_LAS bf16x8*)(lds + PG8_SA(b, h) + aoff + m * 2048 + k * 1024); } while (0)
; #define PG8_LDB(dst, b, h) do { _Pragma("unroll") for (int n = 0; n < 2; ++n) _Pragma("unroll") for (int k = 0; k < 2; ++k) dst[n][k] = *(const PG8_LAS bf16x8*)(lds + PG8_SB(b, h) + boff + n * 2048 + k * 1024); } while (0)
; #define PG8_MMA(ai, bj, At, Bt) do { __builtin_amdgcn_s_setprio(1); _Pragma("unroll") for (int m = 0; m < 4; ++m) _Pragma("unroll") for (int n = 0; n < 2; ++n) _Pragma("unroll") for (int k = 0; k < 2; ++k) \
;         acc[ai][bj][m][n] = __builtin_amdgcn_mfma_f32_16x16x32_bf16(Bt[n][k], At[m][k], acc[ai][bj][m][n], 0, 0, 0); __builtin_amdgcn_s_setprio(0); } while (0)
; #define PG8_WAIT_V(n) asm volatile("s_waitcnt vmcnt(" #n ")" ::: "memory")
; #define PG8_WAIT_L(n) asm volatile("s_waitcnt lgkmcnt(" #n ")" ::: "memory")
; #define PG8_BAR __builtin_amdgcn_s_barrier()
; #define PG8_SCHED __builtin_amdgcn_sched_barrier(0)
; template <class Epi, class Sched, bool ALIGN_EPI = false, bool SP2 = false>
; __device__ __forceinline__ void gemm_phase(PG8_LAS unsigned char* lds, const Gemm g, const Sched& S, const Epi& E) {
;     ...
;             PG8_LDB(B0, 1, 0); PG8_LDB(B1, 1, 1); PG8_SCHED; PG8_LDA(At, 1, 0); PG8_STAGE(PG8_SA(0, 1), a2 + hstep, voffA);
;             PG8_WAIT_V(8); PG8_WAIT_L(0); PG8_BAR; PG8_MMA(0, 0, At, B0); PG8_MMA(0, 1, At, B1); PG8_BAR; PG8_SCHED;
;             PG8_LDA(At, 1, 1); PG8_STAGE(PG8_SB(1, 0), b3, voffB); PG8_STAGE(PG8_SB(1, 1), b3 + hstep, voffB); PG8_STAGE(PG8_SA(1, 0), a3, voffA);
;             PG8_WAIT_V(8); PG8_WAIT_L(0); PG8_BAR; PG8_MMA(1, 0, At, B0); PG8_MMA(1, 1, At, B1); PG8_BAR; PG8_SCHED;
;     ...
;         if constexpr (ALIGN_EPI) { if (wr == 0) PG8_BAR; }
	s_add_u32 s4, s4, 0x40000
	s_addc_u32 s5, s5, 0
	s_mov_b32 m0, s42
	ds_read_b128 v[140:143], v254 offset:32768
	ds_read_b128 v[162:165], v254 offset:33792
	ds_read_b128 v[166:169], v254 offset:34816
	ds_read_b128 v[170:173], v254 offset:35840
	ds_read_b128 v[180:183], v254 offset:49152
	ds_read_b128 v[184:187], v254 offset:50176
	ds_read_b128 v[188:191], v254 offset:51200
	ds_read_b128 v[210:213], v254 offset:52224
	global_load_lds_dwordx4 v134, s[4:5]
	s_mov_b32 m0, s43
	ds_read_b128 v[214:217], v178 offset:32768
	ds_read_b128 v[218:221], v178 offset:33792
	ds_read_b128 v[222:225], v178 offset:34816
	ds_read_b128 v[226:229], v178 offset:35840
	ds_read_b128 v[230:233], v178 offset:36864
	ds_read_b128 v[234:237], v178 offset:37888
	ds_read_b128 v[238:241], v178 offset:38912
	ds_read_b128 v[242:245], v178 offset:39936
	global_load_lds_dwordx4 v130, s[4:5]
	s_waitcnt vmcnt(8) lgkmcnt(0)
	s_barrier
	s_setprio 1
	v_mfma_f32_16x16x32_bf16 v[124:127], v[140:143], v[214:217], v[124:127]
	v_mfma_f32_16x16x32_bf16 v[120:123], v[166:169], v[214:217], v[120:123]
	v_mfma_f32_16x16x32_bf16 v[108:111], v[140:143], v[222:225], v[108:111]
	v_mfma_f32_16x16x32_bf16 v[104:107], v[166:169], v[222:225], v[104:107]
	v_mfma_f32_16x16x32_bf16 v[92:95], v[140:143], v[230:233], v[92:95]
	v_mfma_f32_16x16x32_bf16 v[88:91], v[166:169], v[230:233], v[88:91]
	v_mfma_f32_16x16x32_bf16 v[76:79], v[140:143], v[238:241], v[76:79]
	v_mfma_f32_16x16x32_bf16 v[72:75], v[166:169], v[238:241], v[72:75]
	v_mfma_f32_16x16x32_bf16 v[124:127], v[162:165], v[218:221], v[124:127]
	v_mfma_f32_16x16x32_bf16 v[120:123], v[170:173], v[218:221], v[120:123]
	v_mfma_f32_16x16x32_bf16 v[108:111], v[162:165], v[226:229], v[108:111]
	v_mfma_f32_16x16x32_bf16 v[104:107], v[170:173], v[226:229], v[104:107]
	v_mfma_f32_16x16x32_bf16 v[92:95], v[162:165], v[234:237], v[92:95]
	v_mfma_f32_16x16x32_bf16 v[88:91], v[170:173], v[234:237], v[88:91]
	v_mfma_f32_16x16x32_bf16 v[76:79], v[162:165], v[242:245], v[76:79]
	v_mfma_f32_16x16x32_bf16 v[72:75], v[170:173], v[242:245], v[72:75]
	v_mfma_f32_16x16x32_bf16 v[116:119], v[180:183], v[214:217], v[116:119]
	v_mfma_f32_16x16x32_bf16 v[112:115], v[188:191], v[214:217], v[112:115]
	v_mfma_f32_16x16x32_bf16 v[100:103], v[180:183], v[222:225], v[100:103]
	v_mfma_f32_16x16x32_bf16 v[96:99], v[188:191], v[222:225], v[96:99]
	v_mfma_f32_16x16x32_bf16 v[84:87], v[180:183], v[230:233], v[84:87]
	v_mfma_f32_16x16x32_bf16 v[80:83], v[188:191], v[230:233], v[80:83]
	v_mfma_f32_16x16x32_bf16 v[68:71], v[180:183], v[238:241], v[68:71]
	v_mfma_f32_16x16x32_bf16 v[64:67], v[188:191], v[238:241], v[64:67]
	v_mfma_f32_16x16x32_bf16 v[116:119], v[184:187], v[218:221], v[116:119]
	v_mfma_f32_16x16x32_bf16 v[112:115], v[210:213], v[218:221], v[112:115]
	v_mfma_f32_16x16x32_bf16 v[100:103], v[184:187], v[226:229], v[100:103]
	v_mfma_f32_16x16x32_bf16 v[96:99], v[210:213], v[226:229], v[96:99]
	v_mfma_f32_16x16x32_bf16 v[84:87], v[184:187], v[234:237], v[84:87]
	v_mfma_f32_16x16x32_bf16 v[80:83], v[210:213], v[234:237], v[80:83]
	v_mfma_f32_16x16x32_bf16 v[68:71], v[184:187], v[242:245], v[68:71]
	v_mfma_f32_16x16x32_bf16 v[64:67], v[210:213], v[242:245], v[64:67]
	s_setprio 0
	s_barrier
	s_mov_b32 m0, s48
	s_add_u32 s2, s2, 0x40080
	s_addc_u32 s3, s3, 0
	s_add_u32 s98, s2, 0xfffc0000
	s_addc_u32 s99, s3, -1
	ds_read_b128 v[214:217], v178 offset:49152
	ds_read_b128 v[218:221], v178 offset:50176
	global_load_lds_dwordx4 v132, s[98:99]
	s_mov_b32 m0, s49
	ds_read_b128 v[222:225], v178 offset:51200
	ds_read_b128 v[226:229], v178 offset:52224
	global_load_lds_dwordx4 v128, s[98:99]
	s_mov_b32 m0, s52
	ds_read_b128 v[230:233], v178 offset:53248
	global_load_lds_dwordx4 v132, s[2:3]
	s_mov_b32 m0, s53
	ds_read_b128 v[234:237], v178 offset:54272
	global_load_lds_dwordx4 v128, s[2:3]
	s_mov_b32 m0, s50
	s_add_u32 s100, s4, 0xfffc0080
	s_addc_u32 s101, s5, -1
	ds_read_b128 v[238:241], v178 offset:55296
	global_load_lds_dwordx4 v134, s[100:101]
	s_mov_b32 m0, s51
	ds_read_b128 v[242:245], v178 offset:56320
	global_load_lds_dwordx4 v130, s[100:101]
	s_waitcnt vmcnt(8) lgkmcnt(0)
	s_barrier
	s_setprio 1
	v_mfma_f32_16x16x32_bf16 v[60:63], v[140:143], v[214:217], v[60:63]
	v_mfma_f32_16x16x32_bf16 v[56:59], v[166:169], v[214:217], v[56:59]
	v_mfma_f32_16x16x32_bf16 v[44:47], v[140:143], v[222:225], v[44:47]
	v_mfma_f32_16x16x32_bf16 v[40:43], v[166:169], v[222:225], v[40:43]
	v_mfma_f32_16x16x32_bf16 v[28:31], v[140:143], v[230:233], v[28:31]
	v_mfma_f32_16x16x32_bf16 v[24:27], v[166:169], v[230:233], v[24:27]
	v_mfma_f32_16x16x32_bf16 v[12:15], v[140:143], v[238:241], v[12:15]
	v_mfma_f32_16x16x32_bf16 v[8:11], v[166:169], v[238:241], v[8:11]
	v_mfma_f32_16x16x32_bf16 v[60:63], v[162:165], v[218:221], v[60:63]
	v_mfma_f32_16x16x32_bf16 v[56:59], v[170:173], v[218:221], v[56:59]
	v_mfma_f32_16x16x32_bf16 v[44:47], v[162:165], v[226:229], v[44:47]
	v_mfma_f32_16x16x32_bf16 v[40:43], v[170:173], v[226:229], v[40:43]
	v_mfma_f32_16x16x32_bf16 v[28:31], v[162:165], v[234:237], v[28:31]
	v_mfma_f32_16x16x32_bf16 v[24:27], v[170:173], v[234:237], v[24:27]
	v_mfma_f32_16x16x32_bf16 v[12:15], v[162:165], v[242:245], v[12:15]
	v_mfma_f32_16x16x32_bf16 v[8:11], v[170:173], v[242:245], v[8:11]
	v_mfma_f32_16x16x32_bf16 v[52:55], v[180:183], v[214:217], v[52:55]
	v_mfma_f32_16x16x32_bf16 v[48:51], v[188:191], v[214:217], v[48:51]
	v_mfma_f32_16x16x32_bf16 v[36:39], v[180:183], v[222:225], v[36:39]
	v_mfma_f32_16x16x32_bf16 v[32:35], v[188:191], v[222:225], v[32:35]
	v_mfma_f32_16x16x32_bf16 v[20:23], v[180:183], v[230:233], v[20:23]
	v_mfma_f32_16x16x32_bf16 v[16:19], v[188:191], v[230:233], v[16:19]
	v_mfma_f32_16x16x32_bf16 v[4:7], v[180:183], v[238:241], v[4:7]
	v_mfma_f32_16x16x32_bf16 v[0:3], v[188:191], v[238:241], v[0:3]
	v_mfma_f32_16x16x32_bf16 v[52:55], v[184:187], v[218:221], v[52:55]
	v_mfma_f32_16x16x32_bf16 v[48:51], v[210:213], v[218:221], v[48:51]
	v_mfma_f32_16x16x32_bf16 v[36:39], v[184:187], v[226:229], v[36:39]
	v_mfma_f32_16x16x32_bf16 v[32:35], v[210:213], v[226:229], v[32:35]
	v_mfma_f32_16x16x32_bf16 v[20:23], v[184:187], v[234:237], v[20:23]
	v_mfma_f32_16x16x32_bf16 v[16:19], v[210:213], v[234:237], v[16:19]
	v_mfma_f32_16x16x32_bf16 v[4:7], v[184:187], v[242:245], v[4:7]
	v_mfma_f32_16x16x32_bf16 v[0:3], v[210:213], v[242:245], v[0:3]
	s_setprio 0
	s_barrier
	s_add_i32 s55, s55, 2
	s_add_u32 s0, s0, 0x100
	s_addc_u32 s1, s1, 0
	s_add_u32 s38, s38, 0x100
	s_addc_u32 s39, s39, 0
	s_cmp_gt_u32 s55, 13
	s_cbranch_scc0 .LBB0_749
	s_and_b64 vcc, exec, s[18:19]
	s_cbranch_vccz .LBB0_752
	s_barrier

; #define PG8_STAGE(bufoff, gbase, voff) do { _Pragma("unroll") for (int _i = 0; _i < 2; ++_i) \
;         __builtin_amdgcn_global_load_lds((const unsigned*)((const char*)(gbase) + (voff)[_i]), (PG8_LAS unsigned*)(lds + (bufoff) + ldsw + _i * 8192), 16, 0, 0); } while (0)
; #define PG8_LDA(dst, b, h) do { _Pragma("unroll") for (int m = 0; m < 4; ++m) _Pragma("unroll") for (int k = 0; k < 2; ++k) dst[m][k] = *(const PG8_LAS bf16x8*)(lds + PG8_SA(b, h) + aoff + m * 2048 + k * 1024); } while (0)
; #define PG8_LDB(dst, b, h) do { _Pragma("unroll") for (int n = 0; n < 2; ++n) _Pragma("unroll") for (int k = 0; k < 2; ++k) dst[n][k] = *(const PG8_LAS bf16x8*)(lds + PG8_SB(b, h) + boff + n * 2048 + k * 1024); } while (0)
; #define PG8_MMA(ai, bj, At, Bt) do { __builtin_amdgcn_s_setprio(1); _Pragma("unroll") for (int m = 0; m < 4; ++m) _Pragma("unroll") for (int n = 0; n < 2; ++n) _Pragma("unroll") for (int k = 0; k < 2; ++k) \
;         acc[ai][bj][m][n] = __builtin_amdgcn_mfma_f32_16x16x32_bf16(Bt[n][k], At[m][k], acc[ai][bj][m][n], 0, 0, 0); __builtin_amdgcn_s_setprio(0); } while (0)
; #define PG8_WAIT_V(n) asm volatile("s_waitcnt vmcnt(" #n ")" ::: "memory")
; #define PG8_WAIT_L(n) asm volatile("s_waitcnt lgkmcnt(" #n ")" ::: "memory")
; template <class Epi, class Sched, bool ALIGN_EPI = false, bool SP2 = false>
; __device__ __forceinline__ void gemm_phase(PG8_LAS unsigned char* lds, const Gemm g, const Sched& S, const Epi& E) {
;     ...
;             const bool last = (t == nt - 2);
;             const char* a1 = cA + (size_t)(t + 1) * kstep;
;             const char* a2 = last ? nA : cA + (size_t)(t + 2) * kstep; const char* b2 = last ? nB : cB + (size_t)(t + 2) * kstep;
;             const char* a3 = a2 + kstep; const char* b3 = b2 + kstep;
;             if (last && has_next) S.a_ready(nxt);
;             if constexpr (SP2) {
;             PG8_LDB(B0, 0, 0); PG8_LDB(B1, 0, 1); PG8_SCHED; PG8_LDA(At, 0, 0); PG8_STAGE(PG8_SA(1, 1), a1 + hstep, voffA);
;             PG8_WAIT_V(8); PG8_WAIT_L(0); PG8_BAR; PG8_MMA(0, 0, At, B0); PG8_MMA(0, 1, At, B1); PG8_BAR; PG8_SCHED;
;             PG8_LDA(At, 0, 1); PG8_STAGE(PG8_SB(0, 0), b2, voffB); PG8_STAGE(PG8_SB(0, 1), b2 + hstep, voffB); PG8_STAGE(PG8_SA(0, 0), a2, voffA);
;             PG8_WAIT_V(8); PG8_WAIT_L(0); PG8_BAR; PG8_MMA(1, 0, At, B0); PG8_MMA(1, 1, At, B1); PG8_BAR; PG8_SCHED;
.Labi_peel:
	s_waitcnt lgkmcnt(0)
	s_add_u32 s2, s0, 0xfffc0080
	s_addc_u32 s3, s1, -1
	s_cmp_eq_u32 s52, 12
	s_cselect_b32 s5, s17, s3
	s_cselect_b32 s4, s48, s2
	s_cselect_b32 s3, s15, s51
	s_cselect_b32 s2, s49, s50
	s_add_i32 m0, s6, 0xc000
	ds_read_b128 v[140:143], v254
	ds_read_b128 v[162:165], v254 offset:1024
	ds_read_b128 v[166:169], v254 offset:2048
	ds_read_b128 v[176:179], v254 offset:3072
	ds_read_b128 v[180:183], v254 offset:16384
	ds_read_b128 v[184:187], v254 offset:17408
	ds_read_b128 v[188:191], v254 offset:18432
	ds_read_b128 v[210:213], v254 offset:19456
	global_load_lds_dwordx4 v136, s[0:1]
	s_add_i32 m0, s6, 0xe000
	ds_read_b128 v[214:217], v173
	ds_read_b128 v[218:221], v173 offset:1024
	ds_read_b128 v[222:225], v173 offset:2048
	ds_read_b128 v[226:229], v173 offset:3072
	ds_read_b128 v[230:233], v173 offset:4096
	ds_read_b128 v[234:237], v173 offset:5120
	ds_read_b128 v[238:241], v173 offset:6144
	ds_read_b128 v[242:245], v173 offset:7168
	global_load_lds_dwordx4 v138, s[0:1]
	s_waitcnt vmcnt(8) lgkmcnt(0)
	s_barrier
	s_setprio 1
	v_mfma_f32_16x16x32_bf16 v[124:127], v[140:143], v[214:217], 0
	v_mfma_f32_16x16x32_bf16 v[120:123], v[166:169], v[214:217], 0
	v_mfma_f32_16x16x32_bf16 v[112:115], v[140:143], v[222:225], 0
	v_mfma_f32_16x16x32_bf16 v[104:107], v[166:169], v[222:225], 0
	v_mfma_f32_16x16x32_bf16 v[96:99], v[140:143], v[230:233], 0
	v_mfma_f32_16x16x32_bf16 v[88:91], v[166:169], v[230:233], 0
	v_mfma_f32_16x16x32_bf16 v[80:83], v[140:143], v[238:241], 0
	v_mfma_f32_16x16x32_bf16 v[72:75], v[166:169], v[238:241], 0
	v_mfma_f32_16x16x32_bf16 v[124:127], v[162:165], v[218:221], v[124:127]
	v_mfma_f32_16x16x32_bf16 v[120:123], v[176:179], v[218:221], v[120:123]
	v_mfma_f32_16x16x32_bf16 v[112:115], v[162:165], v[226:229], v[112:115]
	v_mfma_f32_16x16x32_bf16 v[104:107], v[176:179], v[226:229], v[104:107]
	v_mfma_f32_16x16x32_bf16 v[96:99], v[162:165], v[234:237], v[96:99]
	v_mfma_f32_16x16x32_bf16 v[88:91], v[176:179], v[234:237], v[88:91]
	v_mfma_f32_16x16x32_bf16 v[80:83], v[162:165], v[242:245], v[80:83]
	v_mfma_f32_16x16x32_bf16 v[72:75], v[176:179], v[242:245], v[72:75]
	v_mfma_f32_16x16x32_bf16 v[116:119], v[180:183], v[214:217], 0
	v_mfma_f32_16x16x32_bf16 v[108:111], v[188:191], v[214:217], 0
	v_mfma_f32_16x16x32_bf16 v[100:103], v[180:183], v[222:225], 0
	v_mfma_f32_16x16x32_bf16 v[92:95], v[188:191], v[222:225], 0
	v_mfma_f32_16x16x32_bf16 v[84:87], v[180:183], v[230:233], 0
	v_mfma_f32_16x16x32_bf16 v[76:79], v[188:191], v[230:233], 0
	v_mfma_f32_16x16x32_bf16 v[68:71], v[180:183], v[238:241], 0
	v_mfma_f32_16x16x32_bf16 v[64:67], v[188:191], v[238:241], 0
	v_mfma_f32_16x16x32_bf16 v[116:119], v[184:187], v[218:221], v[116:119]
	v_mfma_f32_16x16x32_bf16 v[108:111], v[210:213], v[218:221], v[108:111]
	v_mfma_f32_16x16x32_bf16 v[100:103], v[184:187], v[226:229], v[100:103]
	v_mfma_f32_16x16x32_bf16 v[92:95], v[210:213], v[226:229], v[92:95]
	v_mfma_f32_16x16x32_bf16 v[84:87], v[184:187], v[234:237], v[84:87]
	v_mfma_f32_16x16x32_bf16 v[76:79], v[210:213], v[234:237], v[76:79]
	v_mfma_f32_16x16x32_bf16 v[68:71], v[184:187], v[242:245], v[68:71]
	v_mfma_f32_16x16x32_bf16 v[64:67], v[210:213], v[242:245], v[64:67]
	s_setprio 0
	s_barrier
	s_mov_b32 m0, s27
	s_add_u32 s54, s2, 0x40000
	s_addc_u32 s55, s3, 0
	ds_read_b128 v[214:217], v173 offset:16384
	ds_read_b128 v[218:221], v173 offset:17408
	global_load_lds_dwordx4 v132, s[2:3]
	s_mov_b32 m0, s28
	ds_read_b128 v[222:225], v173 offset:18432
	ds_read_b128 v[226:229], v173 offset:19456
	global_load_lds_dwordx4 v128, s[2:3]
	s_mov_b32 m0, s29
	ds_read_b128 v[230:233], v173 offset:20480
	global_load_lds_dwordx4 v132, s[54:55]
	s_mov_b32 m0, s30
	ds_read_b128 v[234:237], v173 offset:21504
	global_load_lds_dwordx4 v128, s[54:55]
	s_mov_b32 m0, s6
	ds_read_b128 v[238:241], v173 offset:22528
	global_load_lds_dwordx4 v134, s[4:5]
	s_mov_b32 m0, s31
	ds_read_b128 v[242:245], v173 offset:23552
	global_load_lds_dwordx4 v130, s[4:5]
	s_waitcnt vmcnt(8) lgkmcnt(0)
	s_barrier
	s_setprio 1
	v_mfma_f32_16x16x32_bf16 v[60:63], v[140:143], v[214:217], 0
	v_mfma_f32_16x16x32_bf16 v[56:59], v[166:169], v[214:217], 0
	v_mfma_f32_16x16x32_bf16 v[48:51], v[140:143], v[222:225], 0
	v_mfma_f32_16x16x32_bf16 v[40:43], v[166:169], v[222:225], 0
	v_mfma_f32_16x16x32_bf16 v[32:35], v[140:143], v[230:233], 0
	v_mfma_f32_16x16x32_bf16 v[24:27], v[166:169], v[230:233], 0
	v_mfma_f32_16x16x32_bf16 v[16:19], v[140:143], v[238:241], 0
	v_mfma_f32_16x16x32_bf16 v[8:11], v[166:169], v[238:241], 0
	v_mfma_f32_16x16x32_bf16 v[60:63], v[162:165], v[218:221], v[60:63]
	v_mfma_f32_16x16x32_bf16 v[56:59], v[176:179], v[218:221], v[56:59]
	v_mfma_f32_16x16x32_bf16 v[48:51], v[162:165], v[226:229], v[48:51]
	v_mfma_f32_16x16x32_bf16 v[40:43], v[176:179], v[226:229], v[40:43]
	v_mfma_f32_16x16x32_bf16 v[32:35], v[162:165], v[234:237], v[32:35]
	v_mfma_f32_16x16x32_bf16 v[24:27], v[176:179], v[234:237], v[24:27]
	v_mfma_f32_16x16x32_bf16 v[16:19], v[162:165], v[242:245], v[16:19]
	v_mfma_f32_16x16x32_bf16 v[8:11], v[176:179], v[242:245], v[8:11]
	v_mfma_f32_16x16x32_bf16 v[52:55], v[180:183], v[214:217], 0
	v_mfma_f32_16x16x32_bf16 v[44:47], v[188:191], v[214:217], 0
	v_mfma_f32_16x16x32_bf16 v[36:39], v[180:183], v[222:225], 0
	v_mfma_f32_16x16x32_bf16 v[28:31], v[188:191], v[222:225], 0
	v_mfma_f32_16x16x32_bf16 v[20:23], v[180:183], v[230:233], 0
	v_mfma_f32_16x16x32_bf16 v[12:15], v[188:191], v[230:233], 0
	v_mfma_f32_16x16x32_bf16 v[4:7], v[180:183], v[238:241], 0
	v_mfma_f32_16x16x32_bf16 v[0:3], v[188:191], v[238:241], 0
	v_mfma_f32_16x16x32_bf16 v[52:55], v[184:187], v[218:221], v[52:55]
	v_mfma_f32_16x16x32_bf16 v[44:47], v[210:213], v[218:221], v[44:47]
	v_mfma_f32_16x16x32_bf16 v[36:39], v[184:187], v[226:229], v[36:39]
	v_mfma_f32_16x16x32_bf16 v[28:31], v[210:213], v[226:229], v[28:31]
	v_mfma_f32_16x16x32_bf16 v[20:23], v[184:187], v[234:237], v[20:23]
	v_mfma_f32_16x16x32_bf16 v[12:15], v[210:213], v[234:237], v[12:15]
	v_mfma_f32_16x16x32_bf16 v[4:7], v[184:187], v[242:245], v[4:7]
	v_mfma_f32_16x16x32_bf16 v[0:3], v[210:213], v[242:245], v[0:3]
	s_setprio 0
	s_barrier
; #define PG8_STAGE(bufoff, gbase, voff) do { _Pragma("unroll") for (int _i = 0; _i < 2; ++_i) \
;         __builtin_amdgcn_global_load_lds((const unsigned*)((const char*)(gbase) + (voff)[_i]), (PG8_LAS unsigned*)(lds + (bufoff) + ldsw + _i * 8192), 16, 0, 0); } while (0)
; #define PG8_LDA(dst, b, h) do { _Pragma("unroll") for (int m = 0; m < 4; ++m) _Pragma("unroll") for (int k = 0; k < 2; ++k) dst[m][k] = *(const PG8_LAS bf16x8*)(lds + PG8_SA(b, h) + aoff + m * 2048 + k * 1024); } while (0)
; #define PG8_LDB(dst, b, h) do { _Pragma("unroll") for (int n = 0; n < 2; ++n) _Pragma("unroll") for (int k = 0; k < 2; ++k) dst[n][k] = *(const PG8_LAS bf16x8*)(lds + PG8_SB(b, h) + boff + n * 2048 + k * 1024); } while (0)
; #define PG8_MMA(ai, bj, At, Bt) do { __builtin_amdgcn_s_setprio(1); _Pragma("unroll") for (int m = 0; m < 4; ++m) _Pragma("unroll") for (int n = 0; n < 2; ++n) _Pragma("unroll") for (int k = 0; k < 2; ++k) \
;         acc[ai][bj][m][n] = __builtin_amdgcn_mfma_f32_16x16x32_bf16(Bt[n][k], At[m][k], acc[ai][bj][m][n], 0, 0, 0); __builtin_amdgcn_s_setprio(0); } while (0)
; #define PG8_WAIT_V(n) asm volatile("s_waitcnt vmcnt(" #n ")" ::: "memory")
; #define PG8_WAIT_L(n) asm volatile("s_waitcnt lgkmcnt(" #n ")" ::: "memory")
; #define PG8_BAR __builtin_amdgcn_s_barrier()
; #define PG8_SCHED __builtin_amdgcn_sched_barrier(0)
; template <class Epi, class Sched, bool ALIGN_EPI = false, bool SP2 = false>
; __device__ __forceinline__ void gemm_phase(PG8_LAS unsigned char* lds, const Gemm g, const Sched& S, const Epi& E) {
;     ...
;         for (int t = 0; t < nt; t += 2) {
;     ...
;             PG8_LDB(B0, 1, 0); PG8_LDB(B1, 1, 1); PG8_SCHED; PG8_LDA(At, 1, 0); PG8_STAGE(PG8_SA(0, 1), a2 + hstep, voffA);
;             PG8_WAIT_V(8); PG8_WAIT_L(0); PG8_BAR; PG8_MMA(0, 0, At, B0); PG8_MMA(0, 1, At, B1); PG8_BAR; PG8_SCHED;
;             PG8_LDA(At, 1, 1); PG8_STAGE(PG8_SB(1, 0), b3, voffB); PG8_STAGE(PG8_SB(1, 1), b3 + hstep, voffB); PG8_STAGE(PG8_SA(1, 0), a3, voffA);
;             PG8_WAIT_V(8); PG8_WAIT_L(0); PG8_BAR; PG8_MMA(1, 0, At, B0); PG8_MMA(1, 1, At, B1); PG8_BAR; PG8_SCHED;
	s_add_u32 s4, s4, 0x40000
	s_addc_u32 s5, s5, 0
	s_mov_b32 m0, s33
	ds_read_b128 v[140:143], v254 offset:32768
	ds_read_b128 v[162:165], v254 offset:33792
	ds_read_b128 v[166:169], v254 offset:34816
	ds_read_b128 v[176:179], v254 offset:35840
	ds_read_b128 v[180:183], v254 offset:49152
	ds_read_b128 v[184:187], v254 offset:50176
	ds_read_b128 v[188:191], v254 offset:51200
	ds_read_b128 v[210:213], v254 offset:52224
	global_load_lds_dwordx4 v134, s[4:5]
	s_mov_b32 m0, s34
	ds_read_b128 v[214:217], v173 offset:32768
	ds_read_b128 v[218:221], v173 offset:33792
	ds_read_b128 v[222:225], v173 offset:34816
	ds_read_b128 v[226:229], v173 offset:35840
	ds_read_b128 v[230:233], v173 offset:36864
	ds_read_b128 v[234:237], v173 offset:37888
	ds_read_b128 v[238:241], v173 offset:38912
	ds_read_b128 v[242:245], v173 offset:39936
	global_load_lds_dwordx4 v130, s[4:5]
	s_waitcnt vmcnt(8) lgkmcnt(0)
	s_barrier
	s_setprio 1
	v_mfma_f32_16x16x32_bf16 v[124:127], v[140:143], v[214:217], v[124:127]
	v_mfma_f32_16x16x32_bf16 v[120:123], v[166:169], v[214:217], v[120:123]
	v_mfma_f32_16x16x32_bf16 v[112:115], v[140:143], v[222:225], v[112:115]
	v_mfma_f32_16x16x32_bf16 v[104:107], v[166:169], v[222:225], v[104:107]
	v_mfma_f32_16x16x32_bf16 v[96:99], v[140:143], v[230:233], v[96:99]
	v_mfma_f32_16x16x32_bf16 v[88:91], v[166:169], v[230:233], v[88:91]
	v_mfma_f32_16x16x32_bf16 v[80:83], v[140:143], v[238:241], v[80:83]
	v_mfma_f32_16x16x32_bf16 v[72:75], v[166:169], v[238:241], v[72:75]
	v_mfma_f32_16x16x32_bf16 v[124:127], v[162:165], v[218:221], v[124:127]
	v_mfma_f32_16x16x32_bf16 v[120:123], v[176:179], v[218:221], v[120:123]
	v_mfma_f32_16x16x32_bf16 v[112:115], v[162:165], v[226:229], v[112:115]
	v_mfma_f32_16x16x32_bf16 v[104:107], v[176:179], v[226:229], v[104:107]
	v_mfma_f32_16x16x32_bf16 v[96:99], v[162:165], v[234:237], v[96:99]
	v_mfma_f32_16x16x32_bf16 v[88:91], v[176:179], v[234:237], v[88:91]
	v_mfma_f32_16x16x32_bf16 v[80:83], v[162:165], v[242:245], v[80:83]
	v_mfma_f32_16x16x32_bf16 v[72:75], v[176:179], v[242:245], v[72:75]
	v_mfma_f32_16x16x32_bf16 v[116:119], v[180:183], v[214:217], v[116:119]
	v_mfma_f32_16x16x32_bf16 v[108:111], v[188:191], v[214:217], v[108:111]
	v_mfma_f32_16x16x32_bf16 v[100:103], v[180:183], v[222:225], v[100:103]
	v_mfma_f32_16x16x32_bf16 v[92:95], v[188:191], v[222:225], v[92:95]
	v_mfma_f32_16x16x32_bf16 v[84:87], v[180:183], v[230:233], v[84:87]
	v_mfma_f32_16x16x32_bf16 v[76:79], v[188:191], v[230:233], v[76:79]
	v_mfma_f32_16x16x32_bf16 v[68:71], v[180:183], v[238:241], v[68:71]
	v_mfma_f32_16x16x32_bf16 v[64:67], v[188:191], v[238:241], v[64:67]
	v_mfma_f32_16x16x32_bf16 v[116:119], v[184:187], v[218:221], v[116:119]
	v_mfma_f32_16x16x32_bf16 v[108:111], v[210:213], v[218:221], v[108:111]
	v_mfma_f32_16x16x32_bf16 v[100:103], v[184:187], v[226:229], v[100:103]
	v_mfma_f32_16x16x32_bf16 v[92:95], v[210:213], v[226:229], v[92:95]
	v_mfma_f32_16x16x32_bf16 v[84:87], v[184:187], v[234:237], v[84:87]
	v_mfma_f32_16x16x32_bf16 v[76:79], v[210:213], v[234:237], v[76:79]
	v_mfma_f32_16x16x32_bf16 v[68:71], v[184:187], v[242:245], v[68:71]
	v_mfma_f32_16x16x32_bf16 v[64:67], v[210:213], v[242:245], v[64:67]
	s_setprio 0
	s_barrier
	s_mov_b32 m0, s37
	s_add_u32 s2, s2, 0x40080
	s_addc_u32 s3, s3, 0
	s_add_u32 s98, s2, 0xfffc0000
	s_addc_u32 s99, s3, -1
	ds_read_b128 v[214:217], v173 offset:49152
	ds_read_b128 v[218:221], v173 offset:50176
	global_load_lds_dwordx4 v132, s[98:99]
	s_mov_b32 m0, s38
	ds_read_b128 v[222:225], v173 offset:51200
	ds_read_b128 v[226:229], v173 offset:52224
	global_load_lds_dwordx4 v128, s[98:99]
	s_mov_b32 m0, s41
	ds_read_b128 v[230:233], v173 offset:53248
	global_load_lds_dwordx4 v132, s[2:3]
	s_mov_b32 m0, s42
	ds_read_b128 v[234:237], v173 offset:54272
	global_load_lds_dwordx4 v128, s[2:3]
	s_mov_b32 m0, s39
	s_add_u32 s100, s4, 0xfffc0080
	s_addc_u32 s101, s5, -1
	ds_read_b128 v[238:241], v173 offset:55296
	global_load_lds_dwordx4 v134, s[100:101]
	s_mov_b32 m0, s40
	ds_read_b128 v[242:245], v173 offset:56320
	global_load_lds_dwordx4 v130, s[100:101]
	s_waitcnt vmcnt(8) lgkmcnt(0)
	s_barrier
	s_setprio 1
	v_mfma_f32_16x16x32_bf16 v[60:63], v[140:143], v[214:217], v[60:63]
	v_mfma_f32_16x16x32_bf16 v[56:59], v[166:169], v[214:217], v[56:59]
	v_mfma_f32_16x16x32_bf16 v[48:51], v[140:143], v[222:225], v[48:51]
	v_mfma_f32_16x16x32_bf16 v[40:43], v[166:169], v[222:225], v[40:43]
	v_mfma_f32_16x16x32_bf16 v[32:35], v[140:143], v[230:233], v[32:35]
	v_mfma_f32_16x16x32_bf16 v[24:27], v[166:169], v[230:233], v[24:27]
	v_mfma_f32_16x16x32_bf16 v[16:19], v[140:143], v[238:241], v[16:19]
	v_mfma_f32_16x16x32_bf16 v[8:11], v[166:169], v[238:241], v[8:11]
	v_mfma_f32_16x16x32_bf16 v[60:63], v[162:165], v[218:221], v[60:63]
	v_mfma_f32_16x16x32_bf16 v[56:59], v[176:179], v[218:221], v[56:59]
	v_mfma_f32_16x16x32_bf16 v[48:51], v[162:165], v[226:229], v[48:51]
	v_mfma_f32_16x16x32_bf16 v[40:43], v[176:179], v[226:229], v[40:43]
	v_mfma_f32_16x16x32_bf16 v[32:35], v[162:165], v[234:237], v[32:35]
	v_mfma_f32_16x16x32_bf16 v[24:27], v[176:179], v[234:237], v[24:27]
	v_mfma_f32_16x16x32_bf16 v[16:19], v[162:165], v[242:245], v[16:19]
	v_mfma_f32_16x16x32_bf16 v[8:11], v[176:179], v[242:245], v[8:11]
	v_mfma_f32_16x16x32_bf16 v[52:55], v[180:183], v[214:217], v[52:55]
	v_mfma_f32_16x16x32_bf16 v[44:47], v[188:191], v[214:217], v[44:47]
	v_mfma_f32_16x16x32_bf16 v[36:39], v[180:183], v[222:225], v[36:39]
	v_mfma_f32_16x16x32_bf16 v[28:31], v[188:191], v[222:225], v[28:31]
	v_mfma_f32_16x16x32_bf16 v[20:23], v[180:183], v[230:233], v[20:23]
	v_mfma_f32_16x16x32_bf16 v[12:15], v[188:191], v[230:233], v[12:15]
	v_mfma_f32_16x16x32_bf16 v[4:7], v[180:183], v[238:241], v[4:7]
	v_mfma_f32_16x16x32_bf16 v[0:3], v[188:191], v[238:241], v[0:3]
	v_mfma_f32_16x16x32_bf16 v[52:55], v[184:187], v[218:221], v[52:55]
	v_mfma_f32_16x16x32_bf16 v[44:47], v[210:213], v[218:221], v[44:47]
	v_mfma_f32_16x16x32_bf16 v[36:39], v[184:187], v[226:229], v[36:39]
	v_mfma_f32_16x16x32_bf16 v[28:31], v[210:213], v[226:229], v[28:31]
	v_mfma_f32_16x16x32_bf16 v[20:23], v[184:187], v[234:237], v[20:23]
	v_mfma_f32_16x16x32_bf16 v[12:15], v[210:213], v[234:237], v[12:15]
	v_mfma_f32_16x16x32_bf16 v[4:7], v[184:187], v[242:245], v[4:7]
	v_mfma_f32_16x16x32_bf16 v[0:3], v[210:213], v[242:245], v[0:3]
	s_setprio 0
	s_barrier
	s_add_i32 s52, s52, 2
	s_add_u32 s0, s0, 0x100
	s_addc_u32 s1, s1, 0
	s_add_u32 s50, s50, 0x100
	s_addc_u32 s51, s51, 0
	s_cmp_gt_u32 s52, 13
; #define PG8_STAGE(bufoff, gbase, voff) do { _Pragma("unroll") for (int _i = 0; _i < 2; ++_i) \
;         __builtin_amdgcn_global_load_lds((const unsigned*)((const char*)(gbase) + (voff)[_i]), (PG8_LAS unsigned*)(lds + (bufoff) + ldsw + _i * 8192), 16, 0, 0); } while (0)
; #define PG8_LDA(dst, b, h) do { _Pragma("unroll") for (int m = 0; m < 4; ++m) _Pragma("unroll") for (int k = 0; k < 2; ++k) dst[m][k] = *(const PG8_LAS bf16x8*)(lds + PG8_SA(b, h) + aoff + m * 2048 + k * 1024); } while (0)
; #define PG8_LDB(dst, b, h) do { _Pragma("unroll") for (int n = 0; n < 2; ++n) _Pragma("unroll") for (int k = 0; k < 2; ++k) dst[n][k] = *(const PG8_LAS bf16x8*)(lds + PG8_SB(b, h) + boff + n * 2048 + k * 1024); } while (0)
; #define PG8_MMA(ai, bj, At, Bt) do { __builtin_amdgcn_s_setprio(1); _Pragma("unroll") for (int m = 0; m < 4; ++m) _Pragma("unroll") for (int n = 0; n < 2; ++n) _Pragma("unroll") for (int k = 0; k < 2; ++k) \
;         acc[ai][bj][m][n] = __builtin_amdgcn_mfma_f32_16x16x32_bf16(Bt[n][k], At[m][k], acc[ai][bj][m][n], 0, 0, 0); __builtin_amdgcn_s_setprio(0); } while (0)
; #define PG8_WAIT_V(n) asm volatile("s_waitcnt vmcnt(" #n ")" ::: "memory")
; #define PG8_WAIT_L(n) asm volatile("s_waitcnt lgkmcnt(" #n ")" ::: "memory")
; template <class Epi, class Sched, bool ALIGN_EPI = false, bool SP2 = false>
; __device__ __forceinline__ void gemm_phase(PG8_LAS unsigned char* lds, const Gemm g, const Sched& S, const Epi& E) {
;     ...
;             const bool last = (t == nt - 2);
;             const char* a1 = cA + (size_t)(t + 1) * kstep;
;             const char* a2 = last ? nA : cA + (size_t)(t + 2) * kstep; const char* b2 = last ? nB : cB + (size_t)(t + 2) * kstep;
;             const char* a3 = a2 + kstep; const char* b3 = b2 + kstep;
;             if (last && has_next) S.a_ready(nxt);
;             if constexpr (SP2) {
;             PG8_LDB(B0, 0, 0); PG8_LDB(B1, 0, 1); PG8_SCHED; PG8_LDA(At, 0, 0); PG8_STAGE(PG8_SA(1, 1), a1 + hstep, voffA);
;             PG8_WAIT_V(8); PG8_WAIT_L(0); PG8_BAR; PG8_MMA(0, 0, At, B0); PG8_MMA(0, 1, At, B1); PG8_BAR; PG8_SCHED;
;             PG8_LDA(At, 0, 1); PG8_STAGE(PG8_SB(0, 0), b2, voffB); PG8_STAGE(PG8_SB(0, 1), b2 + hstep, voffB); PG8_STAGE(PG8_SA(0, 0), a2, voffA);
;             PG8_WAIT_V(8); PG8_WAIT_L(0); PG8_BAR; PG8_MMA(1, 0, At, B0); PG8_MMA(1, 1, At, B1); PG8_BAR; PG8_SCHED;
.LBB0_792:
	s_waitcnt lgkmcnt(0)
	s_add_u32 s2, s0, 0xfffc0080
	s_addc_u32 s3, s1, -1
	s_cmp_eq_u32 s52, 12
	s_cselect_b32 s5, s17, s3
	s_cselect_b32 s4, s48, s2
	s_cselect_b32 s3, s15, s51
	s_cselect_b32 s2, s49, s50
	s_add_i32 m0, s6, 0xc000
	ds_read_b128 v[140:143], v254
	ds_read_b128 v[162:165], v254 offset:1024
	ds_read_b128 v[166:169], v254 offset:2048
	ds_read_b128 v[176:179], v254 offset:3072
	ds_read_b128 v[180:183], v254 offset:16384
	ds_read_b128 v[184:187], v254 offset:17408
	ds_read_b128 v[188:191], v254 offset:18432
	ds_read_b128 v[210:213], v254 offset:19456
	global_load_lds_dwordx4 v136, s[0:1]
	s_add_i32 m0, s6, 0xe000
	ds_read_b128 v[214:217], v173
	ds_read_b128 v[218:221], v173 offset:1024
	ds_read_b128 v[222:225], v173 offset:2048
	ds_read_b128 v[226:229], v173 offset:3072
	ds_read_b128 v[230:233], v173 offset:4096
	ds_read_b128 v[234:237], v173 offset:5120
	ds_read_b128 v[238:241], v173 offset:6144
	ds_read_b128 v[242:245], v173 offset:7168
	global_load_lds_dwordx4 v138, s[0:1]
	s_waitcnt vmcnt(8) lgkmcnt(0)
	s_barrier
	s_setprio 1
	v_mfma_f32_16x16x32_bf16 v[124:127], v[140:143], v[214:217], v[124:127]
	v_mfma_f32_16x16x32_bf16 v[120:123], v[166:169], v[214:217], v[120:123]
	v_mfma_f32_16x16x32_bf16 v[112:115], v[140:143], v[222:225], v[112:115]
	v_mfma_f32_16x16x32_bf16 v[104:107], v[166:169], v[222:225], v[104:107]
	v_mfma_f32_16x16x32_bf16 v[96:99], v[140:143], v[230:233], v[96:99]
	v_mfma_f32_16x16x32_bf16 v[88:91], v[166:169], v[230:233], v[88:91]
	v_mfma_f32_16x16x32_bf16 v[80:83], v[140:143], v[238:241], v[80:83]
	v_mfma_f32_16x16x32_bf16 v[72:75], v[166:169], v[238:241], v[72:75]
	v_mfma_f32_16x16x32_bf16 v[124:127], v[162:165], v[218:221], v[124:127]
	v_mfma_f32_16x16x32_bf16 v[120:123], v[176:179], v[218:221], v[120:123]
	v_mfma_f32_16x16x32_bf16 v[112:115], v[162:165], v[226:229], v[112:115]
	v_mfma_f32_16x16x32_bf16 v[104:107], v[176:179], v[226:229], v[104:107]
	v_mfma_f32_16x16x32_bf16 v[96:99], v[162:165], v[234:237], v[96:99]
	v_mfma_f32_16x16x32_bf16 v[88:91], v[176:179], v[234:237], v[88:91]
	v_mfma_f32_16x16x32_bf16 v[80:83], v[162:165], v[242:245], v[80:83]
	v_mfma_f32_16x16x32_bf16 v[72:75], v[176:179], v[242:245], v[72:75]
	v_mfma_f32_16x16x32_bf16 v[116:119], v[180:183], v[214:217], v[116:119]
	v_mfma_f32_16x16x32_bf16 v[108:111], v[188:191], v[214:217], v[108:111]
	v_mfma_f32_16x16x32_bf16 v[100:103], v[180:183], v[222:225], v[100:103]
	v_mfma_f32_16x16x32_bf16 v[92:95], v[188:191], v[222:225], v[92:95]
	v_mfma_f32_16x16x32_bf16 v[84:87], v[180:183], v[230:233], v[84:87]
	v_mfma_f32_16x16x32_bf16 v[76:79], v[188:191], v[230:233], v[76:79]
	v_mfma_f32_16x16x32_bf16 v[68:71], v[180:183], v[238:241], v[68:71]
	v_mfma_f32_16x16x32_bf16 v[64:67], v[188:191], v[238:241], v[64:67]
	v_mfma_f32_16x16x32_bf16 v[116:119], v[184:187], v[218:221], v[116:119]
	v_mfma_f32_16x16x32_bf16 v[108:111], v[210:213], v[218:221], v[108:111]
	v_mfma_f32_16x16x32_bf16 v[100:103], v[184:187], v[226:229], v[100:103]
	v_mfma_f32_16x16x32_bf16 v[92:95], v[210:213], v[226:229], v[92:95]
	v_mfma_f32_16x16x32_bf16 v[84:87], v[184:187], v[234:237], v[84:87]
	v_mfma_f32_16x16x32_bf16 v[76:79], v[210:213], v[234:237], v[76:79]
	v_mfma_f32_16x16x32_bf16 v[68:71], v[184:187], v[242:245], v[68:71]
	v_mfma_f32_16x16x32_bf16 v[64:67], v[210:213], v[242:245], v[64:67]
	s_setprio 0
	s_barrier
	s_mov_b32 m0, s27
	s_add_u32 s54, s2, 0x40000
	s_addc_u32 s55, s3, 0
	ds_read_b128 v[214:217], v173 offset:16384
	ds_read_b128 v[218:221], v173 offset:17408
	global_load_lds_dwordx4 v132, s[2:3]
	s_mov_b32 m0, s28
	ds_read_b128 v[222:225], v173 offset:18432
	ds_read_b128 v[226:229], v173 offset:19456
	global_load_lds_dwordx4 v128, s[2:3]
	s_mov_b32 m0, s29
	ds_read_b128 v[230:233], v173 offset:20480
	global_load_lds_dwordx4 v132, s[54:55]
	s_mov_b32 m0, s30
	ds_read_b128 v[234:237], v173 offset:21504
	global_load_lds_dwordx4 v128, s[54:55]
	s_mov_b32 m0, s6
	ds_read_b128 v[238:241], v173 offset:22528
	global_load_lds_dwordx4 v134, s[4:5]
	s_mov_b32 m0, s31
	ds_read_b128 v[242:245], v173 offset:23552
	global_load_lds_dwordx4 v130, s[4:5]
	s_waitcnt vmcnt(8) lgkmcnt(0)
	s_barrier
	s_setprio 1
	v_mfma_f32_16x16x32_bf16 v[60:63], v[140:143], v[214:217], v[60:63]
	v_mfma_f32_16x16x32_bf16 v[56:59], v[166:169], v[214:217], v[56:59]
	v_mfma_f32_16x16x32_bf16 v[48:51], v[140:143], v[222:225], v[48:51]
	v_mfma_f32_16x16x32_bf16 v[40:43], v[166:169], v[222:225], v[40:43]
	v_mfma_f32_16x16x32_bf16 v[32:35], v[140:143], v[230:233], v[32:35]
	v_mfma_f32_16x16x32_bf16 v[24:27], v[166:169], v[230:233], v[24:27]
	v_mfma_f32_16x16x32_bf16 v[16:19], v[140:143], v[238:241], v[16:19]
	v_mfma_f32_16x16x32_bf16 v[8:11], v[166:169], v[238:241], v[8:11]
	v_mfma_f32_16x16x32_bf16 v[60:63], v[162:165], v[218:221], v[60:63]
	v_mfma_f32_16x16x32_bf16 v[56:59], v[176:179], v[218:221], v[56:59]
	v_mfma_f32_16x16x32_bf16 v[48:51], v[162:165], v[226:229], v[48:51]
	v_mfma_f32_16x16x32_bf16 v[40:43], v[176:179], v[226:229], v[40:43]
	v_mfma_f32_16x16x32_bf16 v[32:35], v[162:165], v[234:237], v[32:35]
	v_mfma_f32_16x16x32_bf16 v[24:27], v[176:179], v[234:237], v[24:27]
	v_mfma_f32_16x16x32_bf16 v[16:19], v[162:165], v[242:245], v[16:19]
	v_mfma_f32_16x16x32_bf16 v[8:11], v[176:179], v[242:245], v[8:11]
	v_mfma_f32_16x16x32_bf16 v[52:55], v[180:183], v[214:217], v[52:55]
	v_mfma_f32_16x16x32_bf16 v[44:47], v[188:191], v[214:217], v[44:47]
	v_mfma_f32_16x16x32_bf16 v[36:39], v[180:183], v[222:225], v[36:39]
	v_mfma_f32_16x16x32_bf16 v[28:31], v[188:191], v[222:225], v[28:31]
	v_mfma_f32_16x16x32_bf16 v[20:23], v[180:183], v[230:233], v[20:23]
	v_mfma_f32_16x16x32_bf16 v[12:15], v[188:191], v[230:233], v[12:15]
	v_mfma_f32_16x16x32_bf16 v[4:7], v[180:183], v[238:241], v[4:7]
	v_mfma_f32_16x16x32_bf16 v[0:3], v[188:191], v[238:241], v[0:3]
	v_mfma_f32_16x16x32_bf16 v[52:55], v[184:187], v[218:221], v[52:55]
	v_mfma_f32_16x16x32_bf16 v[44:47], v[210:213], v[218:221], v[44:47]
	v_mfma_f32_16x16x32_bf16 v[36:39], v[184:187], v[226:229], v[36:39]
	v_mfma_f32_16x16x32_bf16 v[28:31], v[210:213], v[226:229], v[28:31]
	v_mfma_f32_16x16x32_bf16 v[20:23], v[184:187], v[234:237], v[20:23]
	v_mfma_f32_16x16x32_bf16 v[12:15], v[210:213], v[234:237], v[12:15]
	v_mfma_f32_16x16x32_bf16 v[4:7], v[184:187], v[242:245], v[4:7]
	v_mfma_f32_16x16x32_bf16 v[0:3], v[210:213], v[242:245], v[0:3]
	s_setprio 0
	s_barrier
; #define PG8_STAGE(bufoff, gbase, voff) do { _Pragma("unroll") for (int _i = 0; _i < 2; ++_i) \
;         __builtin_amdgcn_global_load_lds((const unsigned*)((const char*)(gbase) + (voff)[_i]), (PG8_LAS unsigned*)(lds + (bufoff) + ldsw + _i * 8192), 16, 0, 0); } while (0)
; #define PG8_LDA(dst, b, h) do { _Pragma("unroll") for (int m = 0; m < 4; ++m) _Pragma("unroll") for (int k = 0; k < 2; ++k) dst[m][k] = *(const PG8_LAS bf16x8*)(lds + PG8_SA(b, h) + aoff + m * 2048 + k * 1024); } while (0)
; #define PG8_LDB(dst, b, h) do { _Pragma("unroll") for (int n = 0; n < 2; ++n) _Pragma("unroll") for (int k = 0; k < 2; ++k) dst[n][k] = *(const PG8_LAS bf16x8*)(lds + PG8_SB(b, h) + boff + n * 2048 + k * 1024); } while (0)
; #define PG8_MMA(ai, bj, At, Bt) do { __builtin_amdgcn_s_setprio(1); _Pragma("unroll") for (int m = 0; m < 4; ++m) _Pragma("unroll") for (int n = 0; n < 2; ++n) _Pragma("unroll") for (int k = 0; k < 2; ++k) \
;         acc[ai][bj][m][n] = __builtin_amdgcn_mfma_f32_16x16x32_bf16(Bt[n][k], At[m][k], acc[ai][bj][m][n], 0, 0, 0); __builtin_amdgcn_s_setprio(0); } while (0)
; template <class Epi, class Sched, bool ALIGN_EPI = false, bool SP2 = false>
; __device__ __forceinline__ void gemm_phase(PG8_LAS unsigned char* lds, const Gemm g, const Sched& S, const Epi& E) {
;     ...
;         for (int t = 0; t < nt; t += 2) {
;             const bool last = (t == nt - 2);
;             const char* a1 = cA + (size_t)(t + 1) * kstep;
;             const char* a2 = last ? nA : cA + (size_t)(t + 2) * kstep; const char* b2 = last ? nB : cB + (size_t)(t + 2) * kstep;
;             const char* a3 = a2 + kstep; const char* b3 = b2 + kstep;
;             if (last && has_next) S.a_ready(nxt);
;     ...
;             PG8_LDB(B0, 1, 0); PG8_LDB(B1, 1, 1); PG8_SCHED; PG8_LDA(At, 1, 0); PG8_STAGE(PG8_SA(0, 1), a2 + hstep, voffA);
;             PG8_WAIT_V(8); PG8_WAIT_L(0); PG8_BAR; PG8_MMA(0, 0, At, B0); PG8_MMA(0, 1, At, B1); PG8_BAR; PG8_SCHED;
;             PG8_LDA(At, 1, 1); PG8_STAGE(PG8_SB(1, 0), b3, voffB); PG8_STAGE(PG8_SB(1, 1), b3 + hstep, voffB); PG8_STAGE(PG8_SA(1, 0), a3, voffA);
;             PG8_WAIT_V(8); PG8_WAIT_L(0); PG8_BAR; PG8_MMA(1, 0, At, B0); PG8_MMA(1, 1, At, B1); PG8_BAR; PG8_SCHED;
;     ...
;         if constexpr (ALIGN_EPI) { if (wr == 0) PG8_BAR; }
;         if constexpr (!Epi::AFTER_DRAIN) { E(acc, cur, ui, wr, wc, fr, fq); S.done(cur); }
;         if (!has_next) break;
	s_add_u32 s4, s4, 0x40000
	s_addc_u32 s5, s5, 0
	s_mov_b32 m0, s33
	ds_read_b128 v[140:143], v254 offset:32768
	ds_read_b128 v[162:165], v254 offset:33792
	ds_read_b128 v[166:169], v254 offset:34816
	ds_read_b128 v[176:179], v254 offset:35840
	ds_read_b128 v[180:183], v254 offset:49152
	ds_read_b128 v[184:187], v254 offset:50176
	ds_read_b128 v[188:191], v254 offset:51200
	ds_read_b128 v[210:213], v254 offset:52224
	global_load_lds_dwordx4 v134, s[4:5]
	s_mov_b32 m0, s34
	ds_read_b128 v[214:217], v173 offset:32768
	ds_read_b128 v[218:221], v173 offset:33792
	ds_read_b128 v[222:225], v173 offset:34816
	ds_read_b128 v[226:229], v173 offset:35840
	ds_read_b128 v[230:233], v173 offset:36864
	ds_read_b128 v[234:237], v173 offset:37888
	ds_read_b128 v[238:241], v173 offset:38912
	ds_read_b128 v[242:245], v173 offset:39936
	global_load_lds_dwordx4 v130, s[4:5]
	s_waitcnt vmcnt(8) lgkmcnt(0)
	s_barrier
	s_setprio 1
	v_mfma_f32_16x16x32_bf16 v[124:127], v[140:143], v[214:217], v[124:127]
	v_mfma_f32_16x16x32_bf16 v[120:123], v[166:169], v[214:217], v[120:123]
	v_mfma_f32_16x16x32_bf16 v[112:115], v[140:143], v[222:225], v[112:115]
	v_mfma_f32_16x16x32_bf16 v[104:107], v[166:169], v[222:225], v[104:107]
	v_mfma_f32_16x16x32_bf16 v[96:99], v[140:143], v[230:233], v[96:99]
	v_mfma_f32_16x16x32_bf16 v[88:91], v[166:169], v[230:233], v[88:91]
	v_mfma_f32_16x16x32_bf16 v[80:83], v[140:143], v[238:241], v[80:83]
	v_mfma_f32_16x16x32_bf16 v[72:75], v[166:169], v[238:241], v[72:75]
	v_mfma_f32_16x16x32_bf16 v[124:127], v[162:165], v[218:221], v[124:127]
	v_mfma_f32_16x16x32_bf16 v[120:123], v[176:179], v[218:221], v[120:123]
	v_mfma_f32_16x16x32_bf16 v[112:115], v[162:165], v[226:229], v[112:115]
	v_mfma_f32_16x16x32_bf16 v[104:107], v[176:179], v[226:229], v[104:107]
	v_mfma_f32_16x16x32_bf16 v[96:99], v[162:165], v[234:237], v[96:99]
	v_mfma_f32_16x16x32_bf16 v[88:91], v[176:179], v[234:237], v[88:91]
	v_mfma_f32_16x16x32_bf16 v[80:83], v[162:165], v[242:245], v[80:83]
	v_mfma_f32_16x16x32_bf16 v[72:75], v[176:179], v[242:245], v[72:75]
	v_mfma_f32_16x16x32_bf16 v[116:119], v[180:183], v[214:217], v[116:119]
	v_mfma_f32_16x16x32_bf16 v[108:111], v[188:191], v[214:217], v[108:111]
	v_mfma_f32_16x16x32_bf16 v[100:103], v[180:183], v[222:225], v[100:103]
	v_mfma_f32_16x16x32_bf16 v[92:95], v[188:191], v[222:225], v[92:95]
	v_mfma_f32_16x16x32_bf16 v[84:87], v[180:183], v[230:233], v[84:87]
	v_mfma_f32_16x16x32_bf16 v[76:79], v[188:191], v[230:233], v[76:79]
	v_mfma_f32_16x16x32_bf16 v[68:71], v[180:183], v[238:241], v[68:71]
	v_mfma_f32_16x16x32_bf16 v[64:67], v[188:191], v[238:241], v[64:67]
	v_mfma_f32_16x16x32_bf16 v[116:119], v[184:187], v[218:221], v[116:119]
	v_mfma_f32_16x16x32_bf16 v[108:111], v[210:213], v[218:221], v[108:111]
	v_mfma_f32_16x16x32_bf16 v[100:103], v[184:187], v[226:229], v[100:103]
	v_mfma_f32_16x16x32_bf16 v[92:95], v[210:213], v[226:229], v[92:95]
	v_mfma_f32_16x16x32_bf16 v[84:87], v[184:187], v[234:237], v[84:87]
	v_mfma_f32_16x16x32_bf16 v[76:79], v[210:213], v[234:237], v[76:79]
	v_mfma_f32_16x16x32_bf16 v[68:71], v[184:187], v[242:245], v[68:71]
	v_mfma_f32_16x16x32_bf16 v[64:67], v[210:213], v[242:245], v[64:67]
	s_setprio 0
	s_barrier
	s_mov_b32 m0, s37
	s_add_u32 s2, s2, 0x40080
	s_addc_u32 s3, s3, 0
	s_add_u32 s98, s2, 0xfffc0000
	s_addc_u32 s99, s3, -1
	ds_read_b128 v[214:217], v173 offset:49152
	ds_read_b128 v[218:221], v173 offset:50176
	global_load_lds_dwordx4 v132, s[98:99]
	s_mov_b32 m0, s38
	ds_read_b128 v[222:225], v173 offset:51200
	ds_read_b128 v[226:229], v173 offset:52224
	global_load_lds_dwordx4 v128, s[98:99]
	s_mov_b32 m0, s41
	ds_read_b128 v[230:233], v173 offset:53248
	global_load_lds_dwordx4 v132, s[2:3]
	s_mov_b32 m0, s42
	ds_read_b128 v[234:237], v173 offset:54272
	global_load_lds_dwordx4 v128, s[2:3]
	s_mov_b32 m0, s39
	s_add_u32 s100, s4, 0xfffc0080
	s_addc_u32 s101, s5, -1
	ds_read_b128 v[238:241], v173 offset:55296
	global_load_lds_dwordx4 v134, s[100:101]
	s_mov_b32 m0, s40
	ds_read_b128 v[242:245], v173 offset:56320
	global_load_lds_dwordx4 v130, s[100:101]
	s_waitcnt vmcnt(8) lgkmcnt(0)
	s_barrier
	s_setprio 1
	v_mfma_f32_16x16x32_bf16 v[60:63], v[140:143], v[214:217], v[60:63]
	v_mfma_f32_16x16x32_bf16 v[56:59], v[166:169], v[214:217], v[56:59]
	v_mfma_f32_16x16x32_bf16 v[48:51], v[140:143], v[222:225], v[48:51]
	v_mfma_f32_16x16x32_bf16 v[40:43], v[166:169], v[222:225], v[40:43]
	v_mfma_f32_16x16x32_bf16 v[32:35], v[140:143], v[230:233], v[32:35]
	v_mfma_f32_16x16x32_bf16 v[24:27], v[166:169], v[230:233], v[24:27]
	v_mfma_f32_16x16x32_bf16 v[16:19], v[140:143], v[238:241], v[16:19]
	v_mfma_f32_16x16x32_bf16 v[8:11], v[166:169], v[238:241], v[8:11]
	v_mfma_f32_16x16x32_bf16 v[60:63], v[162:165], v[218:221], v[60:63]
	v_mfma_f32_16x16x32_bf16 v[56:59], v[176:179], v[218:221], v[56:59]
	v_mfma_f32_16x16x32_bf16 v[48:51], v[162:165], v[226:229], v[48:51]
	v_mfma_f32_16x16x32_bf16 v[40:43], v[176:179], v[226:229], v[40:43]
	v_mfma_f32_16x16x32_bf16 v[32:35], v[162:165], v[234:237], v[32:35]
	v_mfma_f32_16x16x32_bf16 v[24:27], v[176:179], v[234:237], v[24:27]
	v_mfma_f32_16x16x32_bf16 v[16:19], v[162:165], v[242:245], v[16:19]
	v_mfma_f32_16x16x32_bf16 v[8:11], v[176:179], v[242:245], v[8:11]
	v_mfma_f32_16x16x32_bf16 v[52:55], v[180:183], v[214:217], v[52:55]
	v_mfma_f32_16x16x32_bf16 v[44:47], v[188:191], v[214:217], v[44:47]
	v_mfma_f32_16x16x32_bf16 v[36:39], v[180:183], v[222:225], v[36:39]
	v_mfma_f32_16x16x32_bf16 v[28:31], v[188:191], v[222:225], v[28:31]
	v_mfma_f32_16x16x32_bf16 v[20:23], v[180:183], v[230:233], v[20:23]
	v_mfma_f32_16x16x32_bf16 v[12:15], v[188:191], v[230:233], v[12:15]
	v_mfma_f32_16x16x32_bf16 v[4:7], v[180:183], v[238:241], v[4:7]
	v_mfma_f32_16x16x32_bf16 v[0:3], v[188:191], v[238:241], v[0:3]
	v_mfma_f32_16x16x32_bf16 v[52:55], v[184:187], v[218:221], v[52:55]
	v_mfma_f32_16x16x32_bf16 v[44:47], v[210:213], v[218:221], v[44:47]
	v_mfma_f32_16x16x32_bf16 v[36:39], v[184:187], v[226:229], v[36:39]
	v_mfma_f32_16x16x32_bf16 v[28:31], v[210:213], v[226:229], v[28:31]
	v_mfma_f32_16x16x32_bf16 v[20:23], v[184:187], v[234:237], v[20:23]
	v_mfma_f32_16x16x32_bf16 v[12:15], v[210:213], v[234:237], v[12:15]
	v_mfma_f32_16x16x32_bf16 v[4:7], v[184:187], v[242:245], v[4:7]
	v_mfma_f32_16x16x32_bf16 v[0:3], v[210:213], v[242:245], v[0:3]
	s_setprio 0
	s_barrier
	s_add_i32 s52, s52, 2
	s_add_u32 s0, s0, 0x100
	s_addc_u32 s1, s1, 0
	s_add_u32 s50, s50, 0x100
	s_addc_u32 s51, s51, 0
	s_cmp_gt_u32 s52, 13
	s_cbranch_scc0 .LBB0_792
	s_and_b64 vcc, exec, s[12:13]
	s_cbranch_vccz .LBB0_795
	s_barrier

; #define PG8_STAGE(bufoff, gbase, voff) do { _Pragma("unroll") for (int _i = 0; _i < 2; ++_i) \
;         __builtin_amdgcn_global_load_lds((const unsigned*)((const char*)(gbase) + (voff)[_i]), (PG8_LAS unsigned*)(lds + (bufoff) + ldsw + _i * 8192), 16, 0, 0); } while (0)
; #define PG8_LDA(dst, b, h) do { _Pragma("unroll") for (int m = 0; m < 4; ++m) _Pragma("unroll") for (int k = 0; k < 2; ++k) dst[m][k] = *(const PG8_LAS bf16x8*)(lds + PG8_SA(b, h) + aoff + m * 2048 + k * 1024); } while (0)
; #define PG8_LDB(dst, b, h) do { _Pragma("unroll") for (int n = 0; n < 2; ++n) _Pragma("unroll") for (int k = 0; k < 2; ++k) dst[n][k] = *(const PG8_LAS bf16x8*)(lds + PG8_SB(b, h) + boff + n * 2048 + k * 1024); } while (0)
; #define PG8_MMA(ai, bj, At, Bt) do { __builtin_amdgcn_s_setprio(1); _Pragma("unroll") for (int m = 0; m < 4; ++m) _Pragma("unroll") for (int n = 0; n < 2; ++n) _Pragma("unroll") for (int k = 0; k < 2; ++k) \
;         acc[ai][bj][m][n] = __builtin_amdgcn_mfma_f32_16x16x32_bf16(Bt[n][k], At[m][k], acc[ai][bj][m][n], 0, 0, 0); __builtin_amdgcn_s_setprio(0); } while (0)
; #define PG8_WAIT_V(n) asm volatile("s_waitcnt vmcnt(" #n ")" ::: "memory")
; #define PG8_WAIT_L(n) asm volatile("s_waitcnt lgkmcnt(" #n ")" ::: "memory")
; template <class Epi, class Sched, bool ALIGN_EPI = false, bool SP2 = false>
; __device__ __forceinline__ void gemm_phase(PG8_LAS unsigned char* lds, const Gemm g, const Sched& S, const Epi& E) {
;     ...
;             const bool last = (t == nt - 2);
;             const char* a1 = cA + (size_t)(t + 1) * kstep;
;             const char* a2 = last ? nA : cA + (size_t)(t + 2) * kstep; const char* b2 = last ? nB : cB + (size_t)(t + 2) * kstep;
;             const char* a3 = a2 + kstep; const char* b3 = b2 + kstep;
;             if (last && has_next) S.a_ready(nxt);
;             if constexpr (SP2) {
;             PG8_LDB(B0, 0, 0); PG8_LDB(B1, 0, 1); PG8_SCHED; PG8_LDA(At, 0, 0); PG8_STAGE(PG8_SA(1, 1), a1 + hstep, voffA);
;             PG8_WAIT_V(8); PG8_WAIT_L(0); PG8_BAR; PG8_MMA(0, 0, At, B0); PG8_MMA(0, 1, At, B1); PG8_BAR; PG8_SCHED;
;             PG8_LDA(At, 0, 1); PG8_STAGE(PG8_SB(0, 0), b2, voffB); PG8_STAGE(PG8_SB(0, 1), b2 + hstep, voffB); PG8_STAGE(PG8_SA(0, 0), a2, voffA);
;             PG8_WAIT_V(8); PG8_WAIT_L(0); PG8_BAR; PG8_MMA(1, 0, At, B0); PG8_MMA(1, 1, At, B1); PG8_BAR; PG8_SCHED;
.Lsgo_peel:
	s_add_u32 s2, s0, 0xfffc0080
	s_addc_u32 s3, s1, -1
	s_cmp_eq_u32 s55, 12
	s_cselect_b32 s5, s23, s3
	s_cselect_b32 s4, s51, s2
	s_cselect_b32 s3, s21, s54
	s_cselect_b32 s2, s52, s53
	s_add_i32 m0, s31, 0xc000
	ds_read_b128 v[140:143], v254
	ds_read_b128 v[166:169], v254 offset:1024
	ds_read_b128 v[170:173], v254 offset:2048
	ds_read_b128 v[174:177], v254 offset:3072
	ds_read_b128 v[178:181], v254 offset:16384
	ds_read_b128 v[182:185], v254 offset:17408
	ds_read_b128 v[186:189], v254 offset:18432
	ds_read_b128 v[210:213], v254 offset:19456
	global_load_lds_dwordx4 v136, s[0:1]
	s_add_i32 m0, s31, 0xe000
	ds_read_b128 v[214:217], v163
	ds_read_b128 v[218:221], v163 offset:1024
	ds_read_b128 v[222:225], v163 offset:2048
	ds_read_b128 v[226:229], v163 offset:3072
	ds_read_b128 v[230:233], v163 offset:4096
	ds_read_b128 v[234:237], v163 offset:5120
	ds_read_b128 v[238:241], v163 offset:6144
	ds_read_b128 v[242:245], v163 offset:7168
	global_load_lds_dwordx4 v138, s[0:1]
	s_waitcnt vmcnt(8) lgkmcnt(0)
	s_barrier
	s_setprio 1
	v_mfma_f32_16x16x32_bf16 v[124:127], v[140:143], v[214:217], 0
	v_mfma_f32_16x16x32_bf16 v[120:123], v[170:173], v[214:217], 0
	v_mfma_f32_16x16x32_bf16 v[108:111], v[140:143], v[222:225], 0
	v_mfma_f32_16x16x32_bf16 v[104:107], v[170:173], v[222:225], 0
	v_mfma_f32_16x16x32_bf16 v[92:95], v[140:143], v[230:233], 0
	v_mfma_f32_16x16x32_bf16 v[88:91], v[170:173], v[230:233], 0
	v_mfma_f32_16x16x32_bf16 v[76:79], v[140:143], v[238:241], 0
	v_mfma_f32_16x16x32_bf16 v[72:75], v[170:173], v[238:241], 0
	v_mfma_f32_16x16x32_bf16 v[124:127], v[166:169], v[218:221], v[124:127]
	v_mfma_f32_16x16x32_bf16 v[120:123], v[174:177], v[218:221], v[120:123]
	v_mfma_f32_16x16x32_bf16 v[108:111], v[166:169], v[226:229], v[108:111]
	v_mfma_f32_16x16x32_bf16 v[104:107], v[174:177], v[226:229], v[104:107]
	v_mfma_f32_16x16x32_bf16 v[92:95], v[166:169], v[234:237], v[92:95]
	v_mfma_f32_16x16x32_bf16 v[88:91], v[174:177], v[234:237], v[88:91]
	v_mfma_f32_16x16x32_bf16 v[76:79], v[166:169], v[242:245], v[76:79]
	v_mfma_f32_16x16x32_bf16 v[72:75], v[174:177], v[242:245], v[72:75]
	v_mfma_f32_16x16x32_bf16 v[116:119], v[178:181], v[214:217], 0
	v_mfma_f32_16x16x32_bf16 v[112:115], v[186:189], v[214:217], 0
	v_mfma_f32_16x16x32_bf16 v[100:103], v[178:181], v[222:225], 0
	v_mfma_f32_16x16x32_bf16 v[96:99], v[186:189], v[222:225], 0
	v_mfma_f32_16x16x32_bf16 v[84:87], v[178:181], v[230:233], 0
	v_mfma_f32_16x16x32_bf16 v[80:83], v[186:189], v[230:233], 0
	v_mfma_f32_16x16x32_bf16 v[68:71], v[178:181], v[238:241], 0
	v_mfma_f32_16x16x32_bf16 v[64:67], v[186:189], v[238:241], 0
	v_mfma_f32_16x16x32_bf16 v[116:119], v[182:185], v[218:221], v[116:119]
	v_mfma_f32_16x16x32_bf16 v[112:115], v[210:213], v[218:221], v[112:115]
	v_mfma_f32_16x16x32_bf16 v[100:103], v[182:185], v[226:229], v[100:103]
	v_mfma_f32_16x16x32_bf16 v[96:99], v[210:213], v[226:229], v[96:99]
	v_mfma_f32_16x16x32_bf16 v[84:87], v[182:185], v[234:237], v[84:87]
	v_mfma_f32_16x16x32_bf16 v[80:83], v[210:213], v[234:237], v[80:83]
	v_mfma_f32_16x16x32_bf16 v[68:71], v[182:185], v[242:245], v[68:71]
	v_mfma_f32_16x16x32_bf16 v[64:67], v[210:213], v[242:245], v[64:67]
	s_setprio 0
	s_barrier
	s_mov_b32 m0, s33
	s_add_u32 s56, s2, 0x40000
	s_addc_u32 s57, s3, 0
	ds_read_b128 v[214:217], v163 offset:16384
	ds_read_b128 v[218:221], v163 offset:17408
	global_load_lds_dwordx4 v132, s[2:3]
	s_mov_b32 m0, s34
	ds_read_b128 v[222:225], v163 offset:18432
	ds_read_b128 v[226:229], v163 offset:19456
	global_load_lds_dwordx4 v128, s[2:3]
	s_mov_b32 m0, s35
	ds_read_b128 v[230:233], v163 offset:20480
	global_load_lds_dwordx4 v132, s[56:57]
	s_mov_b32 m0, s36
	ds_read_b128 v[234:237], v163 offset:21504
	global_load_lds_dwordx4 v128, s[56:57]
	s_mov_b32 m0, s31
	ds_read_b128 v[238:241], v163 offset:22528
	global_load_lds_dwordx4 v134, s[4:5]
	s_mov_b32 m0, s37
	ds_read_b128 v[242:245], v163 offset:23552
	global_load_lds_dwordx4 v130, s[4:5]
	s_waitcnt vmcnt(8) lgkmcnt(0)
	s_barrier
	s_setprio 1
	v_mfma_f32_16x16x32_bf16 v[60:63], v[140:143], v[214:217], 0
	v_mfma_f32_16x16x32_bf16 v[56:59], v[170:173], v[214:217], 0
	v_mfma_f32_16x16x32_bf16 v[44:47], v[140:143], v[222:225], 0
	v_mfma_f32_16x16x32_bf16 v[40:43], v[170:173], v[222:225], 0
	v_mfma_f32_16x16x32_bf16 v[28:31], v[140:143], v[230:233], 0
	v_mfma_f32_16x16x32_bf16 v[24:27], v[170:173], v[230:233], 0
	v_mfma_f32_16x16x32_bf16 v[12:15], v[140:143], v[238:241], 0
	v_mfma_f32_16x16x32_bf16 v[8:11], v[170:173], v[238:241], 0
	v_mfma_f32_16x16x32_bf16 v[60:63], v[166:169], v[218:221], v[60:63]
	v_mfma_f32_16x16x32_bf16 v[56:59], v[174:177], v[218:221], v[56:59]
	v_mfma_f32_16x16x32_bf16 v[44:47], v[166:169], v[226:229], v[44:47]
	v_mfma_f32_16x16x32_bf16 v[40:43], v[174:177], v[226:229], v[40:43]
	v_mfma_f32_16x16x32_bf16 v[28:31], v[166:169], v[234:237], v[28:31]
	v_mfma_f32_16x16x32_bf16 v[24:27], v[174:177], v[234:237], v[24:27]
	v_mfma_f32_16x16x32_bf16 v[12:15], v[166:169], v[242:245], v[12:15]
	v_mfma_f32_16x16x32_bf16 v[8:11], v[174:177], v[242:245], v[8:11]
	v_mfma_f32_16x16x32_bf16 v[52:55], v[178:181], v[214:217], 0
	v_mfma_f32_16x16x32_bf16 v[48:51], v[186:189], v[214:217], 0
	v_mfma_f32_16x16x32_bf16 v[36:39], v[178:181], v[222:225], 0
	v_mfma_f32_16x16x32_bf16 v[32:35], v[186:189], v[222:225], 0
	v_mfma_f32_16x16x32_bf16 v[20:23], v[178:181], v[230:233], 0
	v_mfma_f32_16x16x32_bf16 v[16:19], v[186:189], v[230:233], 0
	v_mfma_f32_16x16x32_bf16 v[4:7], v[178:181], v[238:241], 0
	v_mfma_f32_16x16x32_bf16 v[0:3], v[186:189], v[238:241], 0
	v_mfma_f32_16x16x32_bf16 v[52:55], v[182:185], v[218:221], v[52:55]
	v_mfma_f32_16x16x32_bf16 v[48:51], v[210:213], v[218:221], v[48:51]
	v_mfma_f32_16x16x32_bf16 v[36:39], v[182:185], v[226:229], v[36:39]
	v_mfma_f32_16x16x32_bf16 v[32:35], v[210:213], v[226:229], v[32:35]
	v_mfma_f32_16x16x32_bf16 v[20:23], v[182:185], v[234:237], v[20:23]
	v_mfma_f32_16x16x32_bf16 v[16:19], v[210:213], v[234:237], v[16:19]
	v_mfma_f32_16x16x32_bf16 v[4:7], v[182:185], v[242:245], v[4:7]
	v_mfma_f32_16x16x32_bf16 v[0:3], v[210:213], v[242:245], v[0:3]
	s_setprio 0
	s_barrier
; #define PG8_STAGE(bufoff, gbase, voff) do { _Pragma("unroll") for (int _i = 0; _i < 2; ++_i) \
;         __builtin_amdgcn_global_load_lds((const unsigned*)((const char*)(gbase) + (voff)[_i]), (PG8_LAS unsigned*)(lds + (bufoff) + ldsw + _i * 8192), 16, 0, 0); } while (0)
; #define PG8_LDA(dst, b, h) do { _Pragma("unroll") for (int m = 0; m < 4; ++m) _Pragma("unroll") for (int k = 0; k < 2; ++k) dst[m][k] = *(const PG8_LAS bf16x8*)(lds + PG8_SA(b, h) + aoff + m * 2048 + k * 1024); } while (0)
; #define PG8_LDB(dst, b, h) do { _Pragma("unroll") for (int n = 0; n < 2; ++n) _Pragma("unroll") for (int k = 0; k < 2; ++k) dst[n][k] = *(const PG8_LAS bf16x8*)(lds + PG8_SB(b, h) + boff + n * 2048 + k * 1024); } while (0)
; #define PG8_MMA(ai, bj, At, Bt) do { __builtin_amdgcn_s_setprio(1); _Pragma("unroll") for (int m = 0; m < 4; ++m) _Pragma("unroll") for (int n = 0; n < 2; ++n) _Pragma("unroll") for (int k = 0; k < 2; ++k) \
;         acc[ai][bj][m][n] = __builtin_amdgcn_mfma_f32_16x16x32_bf16(Bt[n][k], At[m][k], acc[ai][bj][m][n], 0, 0, 0); __builtin_amdgcn_s_setprio(0); } while (0)
; #define PG8_WAIT_V(n) asm volatile("s_waitcnt vmcnt(" #n ")" ::: "memory")
; #define PG8_WAIT_L(n) asm volatile("s_waitcnt lgkmcnt(" #n ")" ::: "memory")
; #define PG8_BAR __builtin_amdgcn_s_barrier()
; #define PG8_SCHED __builtin_amdgcn_sched_barrier(0)
; template <class Epi, class Sched, bool ALIGN_EPI = false, bool SP2 = false>
; __device__ __forceinline__ void gemm_phase(PG8_LAS unsigned char* lds, const Gemm g, const Sched& S, const Epi& E) {
;     ...
;         for (int t = 0; t < nt; t += 2) {
;     ...
;             PG8_LDB(B0, 1, 0); PG8_LDB(B1, 1, 1); PG8_SCHED; PG8_LDA(At, 1, 0); PG8_STAGE(PG8_SA(0, 1), a2 + hstep, voffA);
;             PG8_WAIT_V(8); PG8_WAIT_L(0); PG8_BAR; PG8_MMA(0, 0, At, B0); PG8_MMA(0, 1, At, B1); PG8_BAR; PG8_SCHED;
;             PG8_LDA(At, 1, 1); PG8_STAGE(PG8_SB(1, 0), b3, voffB); PG8_STAGE(PG8_SB(1, 1), b3 + hstep, voffB); PG8_STAGE(PG8_SA(1, 0), a3, voffA);
;             PG8_WAIT_V(8); PG8_WAIT_L(0); PG8_BAR; PG8_MMA(1, 0, At, B0); PG8_MMA(1, 1, At, B1); PG8_BAR; PG8_SCHED;
	s_add_u32 s4, s4, 0x40000
	s_addc_u32 s5, s5, 0
	s_mov_b32 m0, s38
	ds_read_b128 v[140:143], v254 offset:32768
	ds_read_b128 v[166:169], v254 offset:33792
	ds_read_b128 v[170:173], v254 offset:34816
	ds_read_b128 v[174:177], v254 offset:35840
	ds_read_b128 v[178:181], v254 offset:49152
	ds_read_b128 v[182:185], v254 offset:50176
	ds_read_b128 v[186:189], v254 offset:51200
	ds_read_b128 v[210:213], v254 offset:52224
	global_load_lds_dwordx4 v134, s[4:5]
	s_mov_b32 m0, s39
	ds_read_b128 v[214:217], v163 offset:32768
	ds_read_b128 v[218:221], v163 offset:33792
	ds_read_b128 v[222:225], v163 offset:34816
	ds_read_b128 v[226:229], v163 offset:35840
	ds_read_b128 v[230:233], v163 offset:36864
	ds_read_b128 v[234:237], v163 offset:37888
	ds_read_b128 v[238:241], v163 offset:38912
	ds_read_b128 v[242:245], v163 offset:39936
	global_load_lds_dwordx4 v130, s[4:5]
	s_waitcnt vmcnt(8) lgkmcnt(0)
	s_barrier
	s_setprio 1
	v_mfma_f32_16x16x32_bf16 v[124:127], v[140:143], v[214:217], v[124:127]
	v_mfma_f32_16x16x32_bf16 v[120:123], v[170:173], v[214:217], v[120:123]
	v_mfma_f32_16x16x32_bf16 v[108:111], v[140:143], v[222:225], v[108:111]
	v_mfma_f32_16x16x32_bf16 v[104:107], v[170:173], v[222:225], v[104:107]
	v_mfma_f32_16x16x32_bf16 v[92:95], v[140:143], v[230:233], v[92:95]
	v_mfma_f32_16x16x32_bf16 v[88:91], v[170:173], v[230:233], v[88:91]
	v_mfma_f32_16x16x32_bf16 v[76:79], v[140:143], v[238:241], v[76:79]
	v_mfma_f32_16x16x32_bf16 v[72:75], v[170:173], v[238:241], v[72:75]
	v_mfma_f32_16x16x32_bf16 v[124:127], v[166:169], v[218:221], v[124:127]
	v_mfma_f32_16x16x32_bf16 v[120:123], v[174:177], v[218:221], v[120:123]
	v_mfma_f32_16x16x32_bf16 v[108:111], v[166:169], v[226:229], v[108:111]
	v_mfma_f32_16x16x32_bf16 v[104:107], v[174:177], v[226:229], v[104:107]
	v_mfma_f32_16x16x32_bf16 v[92:95], v[166:169], v[234:237], v[92:95]
	v_mfma_f32_16x16x32_bf16 v[88:91], v[174:177], v[234:237], v[88:91]
	v_mfma_f32_16x16x32_bf16 v[76:79], v[166:169], v[242:245], v[76:79]
	v_mfma_f32_16x16x32_bf16 v[72:75], v[174:177], v[242:245], v[72:75]
	v_mfma_f32_16x16x32_bf16 v[116:119], v[178:181], v[214:217], v[116:119]
	v_mfma_f32_16x16x32_bf16 v[112:115], v[186:189], v[214:217], v[112:115]
	v_mfma_f32_16x16x32_bf16 v[100:103], v[178:181], v[222:225], v[100:103]
	v_mfma_f32_16x16x32_bf16 v[96:99], v[186:189], v[222:225], v[96:99]
	v_mfma_f32_16x16x32_bf16 v[84:87], v[178:181], v[230:233], v[84:87]
	v_mfma_f32_16x16x32_bf16 v[80:83], v[186:189], v[230:233], v[80:83]
	v_mfma_f32_16x16x32_bf16 v[68:71], v[178:181], v[238:241], v[68:71]
	v_mfma_f32_16x16x32_bf16 v[64:67], v[186:189], v[238:241], v[64:67]
	v_mfma_f32_16x16x32_bf16 v[116:119], v[182:185], v[218:221], v[116:119]
	v_mfma_f32_16x16x32_bf16 v[112:115], v[210:213], v[218:221], v[112:115]
	v_mfma_f32_16x16x32_bf16 v[100:103], v[182:185], v[226:229], v[100:103]
	v_mfma_f32_16x16x32_bf16 v[96:99], v[210:213], v[226:229], v[96:99]
	v_mfma_f32_16x16x32_bf16 v[84:87], v[182:185], v[234:237], v[84:87]
	v_mfma_f32_16x16x32_bf16 v[80:83], v[210:213], v[234:237], v[80:83]
	v_mfma_f32_16x16x32_bf16 v[68:71], v[182:185], v[242:245], v[68:71]
	v_mfma_f32_16x16x32_bf16 v[64:67], v[210:213], v[242:245], v[64:67]
	s_setprio 0
	s_barrier
	s_mov_b32 m0, s43
	s_add_u32 s2, s2, 0x40080
	s_addc_u32 s3, s3, 0
	s_add_u32 s98, s2, 0xfffc0000
	s_addc_u32 s99, s3, -1
	ds_read_b128 v[214:217], v163 offset:49152
	ds_read_b128 v[218:221], v163 offset:50176
	global_load_lds_dwordx4 v132, s[98:99]
	s_mov_b32 m0, s44
	ds_read_b128 v[222:225], v163 offset:51200
	ds_read_b128 v[226:229], v163 offset:52224
	global_load_lds_dwordx4 v128, s[98:99]
	s_mov_b32 m0, s48
	ds_read_b128 v[230:233], v163 offset:53248
	global_load_lds_dwordx4 v132, s[2:3]
	s_mov_b32 m0, s49
	ds_read_b128 v[234:237], v163 offset:54272
	global_load_lds_dwordx4 v128, s[2:3]
	s_mov_b32 m0, s45
	s_add_u32 s100, s4, 0xfffc0080
	s_addc_u32 s101, s5, -1
	ds_read_b128 v[238:241], v163 offset:55296
	global_load_lds_dwordx4 v134, s[100:101]
	s_mov_b32 m0, s47
	ds_read_b128 v[242:245], v163 offset:56320
	global_load_lds_dwordx4 v130, s[100:101]
	s_waitcnt vmcnt(8) lgkmcnt(0)
	s_barrier
	s_setprio 1
	v_mfma_f32_16x16x32_bf16 v[60:63], v[140:143], v[214:217], v[60:63]
	v_mfma_f32_16x16x32_bf16 v[56:59], v[170:173], v[214:217], v[56:59]
	v_mfma_f32_16x16x32_bf16 v[44:47], v[140:143], v[222:225], v[44:47]
	v_mfma_f32_16x16x32_bf16 v[40:43], v[170:173], v[222:225], v[40:43]
	v_mfma_f32_16x16x32_bf16 v[28:31], v[140:143], v[230:233], v[28:31]
	v_mfma_f32_16x16x32_bf16 v[24:27], v[170:173], v[230:233], v[24:27]
	v_mfma_f32_16x16x32_bf16 v[12:15], v[140:143], v[238:241], v[12:15]
	v_mfma_f32_16x16x32_bf16 v[8:11], v[170:173], v[238:241], v[8:11]
	v_mfma_f32_16x16x32_bf16 v[60:63], v[166:169], v[218:221], v[60:63]
	v_mfma_f32_16x16x32_bf16 v[56:59], v[174:177], v[218:221], v[56:59]
	v_mfma_f32_16x16x32_bf16 v[44:47], v[166:169], v[226:229], v[44:47]
	v_mfma_f32_16x16x32_bf16 v[40:43], v[174:177], v[226:229], v[40:43]
	v_mfma_f32_16x16x32_bf16 v[28:31], v[166:169], v[234:237], v[28:31]
	v_mfma_f32_16x16x32_bf16 v[24:27], v[174:177], v[234:237], v[24:27]
	v_mfma_f32_16x16x32_bf16 v[12:15], v[166:169], v[242:245], v[12:15]
	v_mfma_f32_16x16x32_bf16 v[8:11], v[174:177], v[242:245], v[8:11]
	v_mfma_f32_16x16x32_bf16 v[52:55], v[178:181], v[214:217], v[52:55]
	v_mfma_f32_16x16x32_bf16 v[48:51], v[186:189], v[214:217], v[48:51]
	v_mfma_f32_16x16x32_bf16 v[36:39], v[178:181], v[222:225], v[36:39]
	v_mfma_f32_16x16x32_bf16 v[32:35], v[186:189], v[222:225], v[32:35]
	v_mfma_f32_16x16x32_bf16 v[20:23], v[178:181], v[230:233], v[20:23]
	v_mfma_f32_16x16x32_bf16 v[16:19], v[186:189], v[230:233], v[16:19]
	v_mfma_f32_16x16x32_bf16 v[4:7], v[178:181], v[238:241], v[4:7]
	v_mfma_f32_16x16x32_bf16 v[0:3], v[186:189], v[238:241], v[0:3]
	v_mfma_f32_16x16x32_bf16 v[52:55], v[182:185], v[218:221], v[52:55]
	v_mfma_f32_16x16x32_bf16 v[48:51], v[210:213], v[218:221], v[48:51]
	v_mfma_f32_16x16x32_bf16 v[36:39], v[182:185], v[226:229], v[36:39]
	v_mfma_f32_16x16x32_bf16 v[32:35], v[210:213], v[226:229], v[32:35]
	v_mfma_f32_16x16x32_bf16 v[20:23], v[182:185], v[234:237], v[20:23]
	v_mfma_f32_16x16x32_bf16 v[16:19], v[210:213], v[234:237], v[16:19]
	v_mfma_f32_16x16x32_bf16 v[4:7], v[182:185], v[242:245], v[4:7]
	v_mfma_f32_16x16x32_bf16 v[0:3], v[210:213], v[242:245], v[0:3]
	s_setprio 0
	s_barrier
	s_add_i32 s55, s55, 2
	s_add_u32 s0, s0, 0x100
	s_addc_u32 s1, s1, 0
	s_add_u32 s53, s53, 0x100
	s_addc_u32 s54, s54, 0
	s_cmp_gt_u32 s55, 13
; #define PG8_STAGE(bufoff, gbase, voff) do { _Pragma("unroll") for (int _i = 0; _i < 2; ++_i) \
;         __builtin_amdgcn_global_load_lds((const unsigned*)((const char*)(gbase) + (voff)[_i]), (PG8_LAS unsigned*)(lds + (bufoff) + ldsw + _i * 8192), 16, 0, 0); } while (0)
; #define PG8_LDA(dst, b, h) do { _Pragma("unroll") for (int m = 0; m < 4; ++m) _Pragma("unroll") for (int k = 0; k < 2; ++k) dst[m][k] = *(const PG8_LAS bf16x8*)(lds + PG8_SA(b, h) + aoff + m * 2048 + k * 1024); } while (0)
; #define PG8_LDB(dst, b, h) do { _Pragma("unroll") for (int n = 0; n < 2; ++n) _Pragma("unroll") for (int k = 0; k < 2; ++k) dst[n][k] = *(const PG8_LAS bf16x8*)(lds + PG8_SB(b, h) + boff + n * 2048 + k * 1024); } while (0)
; #define PG8_MMA(ai, bj, At, Bt) do { __builtin_amdgcn_s_setprio(1); _Pragma("unroll") for (int m = 0; m < 4; ++m) _Pragma("unroll") for (int n = 0; n < 2; ++n) _Pragma("unroll") for (int k = 0; k < 2; ++k) \
;         acc[ai][bj][m][n] = __builtin_amdgcn_mfma_f32_16x16x32_bf16(Bt[n][k], At[m][k], acc[ai][bj][m][n], 0, 0, 0); __builtin_amdgcn_s_setprio(0); } while (0)
; #define PG8_WAIT_V(n) asm volatile("s_waitcnt vmcnt(" #n ")" ::: "memory")
; #define PG8_WAIT_L(n) asm volatile("s_waitcnt lgkmcnt(" #n ")" ::: "memory")
; template <class Epi, class Sched, bool ALIGN_EPI = false, bool SP2 = false>
; __device__ __forceinline__ void gemm_phase(PG8_LAS unsigned char* lds, const Gemm g, const Sched& S, const Epi& E) {
;     ...
;             const bool last = (t == nt - 2);
;             const char* a1 = cA + (size_t)(t + 1) * kstep;
;             const char* a2 = last ? nA : cA + (size_t)(t + 2) * kstep; const char* b2 = last ? nB : cB + (size_t)(t + 2) * kstep;
;             const char* a3 = a2 + kstep; const char* b3 = b2 + kstep;
;             if (last && has_next) S.a_ready(nxt);
;             if constexpr (SP2) {
;             PG8_LDB(B0, 0, 0); PG8_LDB(B1, 0, 1); PG8_SCHED; PG8_LDA(At, 0, 0); PG8_STAGE(PG8_SA(1, 1), a1 + hstep, voffA);
;             PG8_WAIT_V(8); PG8_WAIT_L(0); PG8_BAR; PG8_MMA(0, 0, At, B0); PG8_MMA(0, 1, At, B1); PG8_BAR; PG8_SCHED;
;             PG8_LDA(At, 0, 1); PG8_STAGE(PG8_SB(0, 0), b2, voffB); PG8_STAGE(PG8_SB(0, 1), b2 + hstep, voffB); PG8_STAGE(PG8_SA(0, 0), a2, voffA);
;             PG8_WAIT_V(8); PG8_WAIT_L(0); PG8_BAR; PG8_MMA(1, 0, At, B0); PG8_MMA(1, 1, At, B1); PG8_BAR; PG8_SCHED;
.LBB0_1042:
	s_add_u32 s2, s0, 0xfffc0080
	s_addc_u32 s3, s1, -1
	s_cmp_eq_u32 s55, 12
	s_cselect_b32 s5, s23, s3
	s_cselect_b32 s4, s51, s2
	s_cselect_b32 s3, s21, s54
	s_cselect_b32 s2, s52, s53
	s_add_i32 m0, s31, 0xc000
	ds_read_b128 v[140:143], v254
	ds_read_b128 v[166:169], v254 offset:1024
	ds_read_b128 v[170:173], v254 offset:2048
	ds_read_b128 v[174:177], v254 offset:3072
	ds_read_b128 v[178:181], v254 offset:16384
	ds_read_b128 v[182:185], v254 offset:17408
	ds_read_b128 v[186:189], v254 offset:18432
	ds_read_b128 v[210:213], v254 offset:19456
	global_load_lds_dwordx4 v136, s[0:1]
	s_add_i32 m0, s31, 0xe000
	ds_read_b128 v[214:217], v163
	ds_read_b128 v[218:221], v163 offset:1024
	ds_read_b128 v[222:225], v163 offset:2048
	ds_read_b128 v[226:229], v163 offset:3072
	ds_read_b128 v[230:233], v163 offset:4096
	ds_read_b128 v[234:237], v163 offset:5120
	ds_read_b128 v[238:241], v163 offset:6144
	ds_read_b128 v[242:245], v163 offset:7168
	global_load_lds_dwordx4 v138, s[0:1]
	s_waitcnt vmcnt(8) lgkmcnt(0)
	s_barrier
	s_setprio 1
	v_mfma_f32_16x16x32_bf16 v[124:127], v[140:143], v[214:217], v[124:127]
	v_mfma_f32_16x16x32_bf16 v[120:123], v[170:173], v[214:217], v[120:123]
	v_mfma_f32_16x16x32_bf16 v[108:111], v[140:143], v[222:225], v[108:111]
	v_mfma_f32_16x16x32_bf16 v[104:107], v[170:173], v[222:225], v[104:107]
	v_mfma_f32_16x16x32_bf16 v[92:95], v[140:143], v[230:233], v[92:95]
	v_mfma_f32_16x16x32_bf16 v[88:91], v[170:173], v[230:233], v[88:91]
	v_mfma_f32_16x16x32_bf16 v[76:79], v[140:143], v[238:241], v[76:79]
	v_mfma_f32_16x16x32_bf16 v[72:75], v[170:173], v[238:241], v[72:75]
	v_mfma_f32_16x16x32_bf16 v[124:127], v[166:169], v[218:221], v[124:127]
	v_mfma_f32_16x16x32_bf16 v[120:123], v[174:177], v[218:221], v[120:123]
	v_mfma_f32_16x16x32_bf16 v[108:111], v[166:169], v[226:229], v[108:111]
	v_mfma_f32_16x16x32_bf16 v[104:107], v[174:177], v[226:229], v[104:107]
	v_mfma_f32_16x16x32_bf16 v[92:95], v[166:169], v[234:237], v[92:95]
	v_mfma_f32_16x16x32_bf16 v[88:91], v[174:177], v[234:237], v[88:91]
	v_mfma_f32_16x16x32_bf16 v[76:79], v[166:169], v[242:245], v[76:79]
	v_mfma_f32_16x16x32_bf16 v[72:75], v[174:177], v[242:245], v[72:75]
	v_mfma_f32_16x16x32_bf16 v[116:119], v[178:181], v[214:217], v[116:119]
	v_mfma_f32_16x16x32_bf16 v[112:115], v[186:189], v[214:217], v[112:115]
	v_mfma_f32_16x16x32_bf16 v[100:103], v[178:181], v[222:225], v[100:103]
	v_mfma_f32_16x16x32_bf16 v[96:99], v[186:189], v[222:225], v[96:99]
	v_mfma_f32_16x16x32_bf16 v[84:87], v[178:181], v[230:233], v[84:87]
	v_mfma_f32_16x16x32_bf16 v[80:83], v[186:189], v[230:233], v[80:83]
	v_mfma_f32_16x16x32_bf16 v[68:71], v[178:181], v[238:241], v[68:71]
	v_mfma_f32_16x16x32_bf16 v[64:67], v[186:189], v[238:241], v[64:67]
	v_mfma_f32_16x16x32_bf16 v[116:119], v[182:185], v[218:221], v[116:119]
	v_mfma_f32_16x16x32_bf16 v[112:115], v[210:213], v[218:221], v[112:115]
	v_mfma_f32_16x16x32_bf16 v[100:103], v[182:185], v[226:229], v[100:103]
	v_mfma_f32_16x16x32_bf16 v[96:99], v[210:213], v[226:229], v[96:99]
	v_mfma_f32_16x16x32_bf16 v[84:87], v[182:185], v[234:237], v[84:87]
	v_mfma_f32_16x16x32_bf16 v[80:83], v[210:213], v[234:237], v[80:83]
	v_mfma_f32_16x16x32_bf16 v[68:71], v[182:185], v[242:245], v[68:71]
	v_mfma_f32_16x16x32_bf16 v[64:67], v[210:213], v[242:245], v[64:67]
	s_setprio 0
	s_barrier
	s_mov_b32 m0, s33
	s_add_u32 s56, s2, 0x40000
	s_addc_u32 s57, s3, 0
	ds_read_b128 v[214:217], v163 offset:16384
	ds_read_b128 v[218:221], v163 offset:17408
	global_load_lds_dwordx4 v132, s[2:3]
	s_mov_b32 m0, s34
	ds_read_b128 v[222:225], v163 offset:18432
	ds_read_b128 v[226:229], v163 offset:19456
	global_load_lds_dwordx4 v128, s[2:3]
	s_mov_b32 m0, s35
	ds_read_b128 v[230:233], v163 offset:20480
	global_load_lds_dwordx4 v132, s[56:57]
	s_mov_b32 m0, s36
	ds_read_b128 v[234:237], v163 offset:21504
	global_load_lds_dwordx4 v128, s[56:57]
	s_mov_b32 m0, s31
	ds_read_b128 v[238:241], v163 offset:22528
	global_load_lds_dwordx4 v134, s[4:5]
	s_mov_b32 m0, s37
	ds_read_b128 v[242:245], v163 offset:23552
	global_load_lds_dwordx4 v130, s[4:5]
	s_waitcnt vmcnt(8) lgkmcnt(0)
	s_barrier
	s_setprio 1
	v_mfma_f32_16x16x32_bf16 v[60:63], v[140:143], v[214:217], v[60:63]
	v_mfma_f32_16x16x32_bf16 v[56:59], v[170:173], v[214:217], v[56:59]
	v_mfma_f32_16x16x32_bf16 v[44:47], v[140:143], v[222:225], v[44:47]
	v_mfma_f32_16x16x32_bf16 v[40:43], v[170:173], v[222:225], v[40:43]
	v_mfma_f32_16x16x32_bf16 v[28:31], v[140:143], v[230:233], v[28:31]
	v_mfma_f32_16x16x32_bf16 v[24:27], v[170:173], v[230:233], v[24:27]
	v_mfma_f32_16x16x32_bf16 v[12:15], v[140:143], v[238:241], v[12:15]
	v_mfma_f32_16x16x32_bf16 v[8:11], v[170:173], v[238:241], v[8:11]
	v_mfma_f32_16x16x32_bf16 v[60:63], v[166:169], v[218:221], v[60:63]
	v_mfma_f32_16x16x32_bf16 v[56:59], v[174:177], v[218:221], v[56:59]
	v_mfma_f32_16x16x32_bf16 v[44:47], v[166:169], v[226:229], v[44:47]
	v_mfma_f32_16x16x32_bf16 v[40:43], v[174:177], v[226:229], v[40:43]
	v_mfma_f32_16x16x32_bf16 v[28:31], v[166:169], v[234:237], v[28:31]
	v_mfma_f32_16x16x32_bf16 v[24:27], v[174:177], v[234:237], v[24:27]
	v_mfma_f32_16x16x32_bf16 v[12:15], v[166:169], v[242:245], v[12:15]
	v_mfma_f32_16x16x32_bf16 v[8:11], v[174:177], v[242:245], v[8:11]
	v_mfma_f32_16x16x32_bf16 v[52:55], v[178:181], v[214:217], v[52:55]
	v_mfma_f32_16x16x32_bf16 v[48:51], v[186:189], v[214:217], v[48:51]
	v_mfma_f32_16x16x32_bf16 v[36:39], v[178:181], v[222:225], v[36:39]
	v_mfma_f32_16x16x32_bf16 v[32:35], v[186:189], v[222:225], v[32:35]
	v_mfma_f32_16x16x32_bf16 v[20:23], v[178:181], v[230:233], v[20:23]
	v_mfma_f32_16x16x32_bf16 v[16:19], v[186:189], v[230:233], v[16:19]
	v_mfma_f32_16x16x32_bf16 v[4:7], v[178:181], v[238:241], v[4:7]
	v_mfma_f32_16x16x32_bf16 v[0:3], v[186:189], v[238:241], v[0:3]
	v_mfma_f32_16x16x32_bf16 v[52:55], v[182:185], v[218:221], v[52:55]
	v_mfma_f32_16x16x32_bf16 v[48:51], v[210:213], v[218:221], v[48:51]
	v_mfma_f32_16x16x32_bf16 v[36:39], v[182:185], v[226:229], v[36:39]
	v_mfma_f32_16x16x32_bf16 v[32:35], v[210:213], v[226:229], v[32:35]
	v_mfma_f32_16x16x32_bf16 v[20:23], v[182:185], v[234:237], v[20:23]
	v_mfma_f32_16x16x32_bf16 v[16:19], v[210:213], v[234:237], v[16:19]
	v_mfma_f32_16x16x32_bf16 v[4:7], v[182:185], v[242:245], v[4:7]
	v_mfma_f32_16x16x32_bf16 v[0:3], v[210:213], v[242:245], v[0:3]
	s_setprio 0
	s_barrier
; #define PG8_STAGE(bufoff, gbase, voff) do { _Pragma("unroll") for (int _i = 0; _i < 2; ++_i) \
;         __builtin_amdgcn_global_load_lds((const unsigned*)((const char*)(gbase) + (voff)[_i]), (PG8_LAS unsigned*)(lds + (bufoff) + ldsw + _i * 8192), 16, 0, 0); } while (0)
; #define PG8_LDA(dst, b, h) do { _Pragma("unroll") for (int m = 0; m < 4; ++m) _Pragma("unroll") for (int k = 0; k < 2; ++k) dst[m][k] = *(const PG8_LAS bf16x8*)(lds + PG8_SA(b, h) + aoff + m * 2048 + k * 1024); } while (0)
; #define PG8_LDB(dst, b, h) do { _Pragma("unroll") for (int n = 0; n < 2; ++n) _Pragma("unroll") for (int k = 0; k < 2; ++k) dst[n][k] = *(const PG8_LAS bf16x8*)(lds + PG8_SB(b, h) + boff + n * 2048 + k * 1024); } while (0)
; #define PG8_MMA(ai, bj, At, Bt) do { __builtin_amdgcn_s_setprio(1); _Pragma("unroll") for (int m = 0; m < 4; ++m) _Pragma("unroll") for (int n = 0; n < 2; ++n) _Pragma("unroll") for (int k = 0; k < 2; ++k) \
;         acc[ai][bj][m][n] = __builtin_amdgcn_mfma_f32_16x16x32_bf16(Bt[n][k], At[m][k], acc[ai][bj][m][n], 0, 0, 0); __builtin_amdgcn_s_setprio(0); } while (0)
; template <class Epi, class Sched, bool ALIGN_EPI = false, bool SP2 = false>
; __device__ __forceinline__ void gemm_phase(PG8_LAS unsigned char* lds, const Gemm g, const Sched& S, const Epi& E) {
;     ...
;         for (int t = 0; t < nt; t += 2) {
;             const bool last = (t == nt - 2);
;             const char* a1 = cA + (size_t)(t + 1) * kstep;
;             const char* a2 = last ? nA : cA + (size_t)(t + 2) * kstep; const char* b2 = last ? nB : cB + (size_t)(t + 2) * kstep;
;             const char* a3 = a2 + kstep; const char* b3 = b2 + kstep;
;             if (last && has_next) S.a_ready(nxt);
;     ...
;             PG8_LDB(B0, 1, 0); PG8_LDB(B1, 1, 1); PG8_SCHED; PG8_LDA(At, 1, 0); PG8_STAGE(PG8_SA(0, 1), a2 + hstep, voffA);
;             PG8_WAIT_V(8); PG8_WAIT_L(0); PG8_BAR; PG8_MMA(0, 0, At, B0); PG8_MMA(0, 1, At, B1); PG8_BAR; PG8_SCHED;
;             PG8_LDA(At, 1, 1); PG8_STAGE(PG8_SB(1, 0), b3, voffB); PG8_STAGE(PG8_SB(1, 1), b3 + hstep, voffB); PG8_STAGE(PG8_SA(1, 0), a3, voffA);
;             PG8_WAIT_V(8); PG8_WAIT_L(0); PG8_BAR; PG8_MMA(1, 0, At, B0); PG8_MMA(1, 1, At, B1); PG8_BAR; PG8_SCHED;
;     ...
;         if constexpr (ALIGN_EPI) { if (wr == 0) PG8_BAR; }
;         if constexpr (!Epi::AFTER_DRAIN) { E(acc, cur, ui, wr, wc, fr, fq); S.done(cur); }
;         if (!has_next) break;
	s_add_u32 s4, s4, 0x40000
	s_addc_u32 s5, s5, 0
	s_mov_b32 m0, s38
	ds_read_b128 v[140:143], v254 offset:32768
	ds_read_b128 v[166:169], v254 offset:33792
	ds_read_b128 v[170:173], v254 offset:34816
	ds_read_b128 v[174:177], v254 offset:35840
	ds_read_b128 v[178:181], v254 offset:49152
	ds_read_b128 v[182:185], v254 offset:50176
	ds_read_b128 v[186:189], v254 offset:51200
	ds_read_b128 v[210:213], v254 offset:52224
	global_load_lds_dwordx4 v134, s[4:5]
	s_mov_b32 m0, s39
	ds_read_b128 v[214:217], v163 offset:32768
	ds_read_b128 v[218:221], v163 offset:33792
	ds_read_b128 v[222:225], v163 offset:34816
	ds_read_b128 v[226:229], v163 offset:35840
	ds_read_b128 v[230:233], v163 offset:36864
	ds_read_b128 v[234:237], v163 offset:37888
	ds_read_b128 v[238:241], v163 offset:38912
	ds_read_b128 v[242:245], v163 offset:39936
	global_load_lds_dwordx4 v130, s[4:5]
	s_waitcnt vmcnt(8) lgkmcnt(0)
	s_barrier
	s_setprio 1
	v_mfma_f32_16x16x32_bf16 v[124:127], v[140:143], v[214:217], v[124:127]
	v_mfma_f32_16x16x32_bf16 v[120:123], v[170:173], v[214:217], v[120:123]
	v_mfma_f32_16x16x32_bf16 v[108:111], v[140:143], v[222:225], v[108:111]
	v_mfma_f32_16x16x32_bf16 v[104:107], v[170:173], v[222:225], v[104:107]
	v_mfma_f32_16x16x32_bf16 v[92:95], v[140:143], v[230:233], v[92:95]
	v_mfma_f32_16x16x32_bf16 v[88:91], v[170:173], v[230:233], v[88:91]
	v_mfma_f32_16x16x32_bf16 v[76:79], v[140:143], v[238:241], v[76:79]
	v_mfma_f32_16x16x32_bf16 v[72:75], v[170:173], v[238:241], v[72:75]
	v_mfma_f32_16x16x32_bf16 v[124:127], v[166:169], v[218:221], v[124:127]
	v_mfma_f32_16x16x32_bf16 v[120:123], v[174:177], v[218:221], v[120:123]
	v_mfma_f32_16x16x32_bf16 v[108:111], v[166:169], v[226:229], v[108:111]
	v_mfma_f32_16x16x32_bf16 v[104:107], v[174:177], v[226:229], v[104:107]
	v_mfma_f32_16x16x32_bf16 v[92:95], v[166:169], v[234:237], v[92:95]
	v_mfma_f32_16x16x32_bf16 v[88:91], v[174:177], v[234:237], v[88:91]
	v_mfma_f32_16x16x32_bf16 v[76:79], v[166:169], v[242:245], v[76:79]
	v_mfma_f32_16x16x32_bf16 v[72:75], v[174:177], v[242:245], v[72:75]
	v_mfma_f32_16x16x32_bf16 v[116:119], v[178:181], v[214:217], v[116:119]
	v_mfma_f32_16x16x32_bf16 v[112:115], v[186:189], v[214:217], v[112:115]
	v_mfma_f32_16x16x32_bf16 v[100:103], v[178:181], v[222:225], v[100:103]
	v_mfma_f32_16x16x32_bf16 v[96:99], v[186:189], v[222:225], v[96:99]
	v_mfma_f32_16x16x32_bf16 v[84:87], v[178:181], v[230:233], v[84:87]
	v_mfma_f32_16x16x32_bf16 v[80:83], v[186:189], v[230:233], v[80:83]
	v_mfma_f32_16x16x32_bf16 v[68:71], v[178:181], v[238:241], v[68:71]
	v_mfma_f32_16x16x32_bf16 v[64:67], v[186:189], v[238:241], v[64:67]
	v_mfma_f32_16x16x32_bf16 v[116:119], v[182:185], v[218:221], v[116:119]
	v_mfma_f32_16x16x32_bf16 v[112:115], v[210:213], v[218:221], v[112:115]
	v_mfma_f32_16x16x32_bf16 v[100:103], v[182:185], v[226:229], v[100:103]
	v_mfma_f32_16x16x32_bf16 v[96:99], v[210:213], v[226:229], v[96:99]
	v_mfma_f32_16x16x32_bf16 v[84:87], v[182:185], v[234:237], v[84:87]
	v_mfma_f32_16x16x32_bf16 v[80:83], v[210:213], v[234:237], v[80:83]
	v_mfma_f32_16x16x32_bf16 v[68:71], v[182:185], v[242:245], v[68:71]
	v_mfma_f32_16x16x32_bf16 v[64:67], v[210:213], v[242:245], v[64:67]
	s_setprio 0
	s_barrier
	s_mov_b32 m0, s43
	s_add_u32 s2, s2, 0x40080
	s_addc_u32 s3, s3, 0
	s_add_u32 s98, s2, 0xfffc0000
	s_addc_u32 s99, s3, -1
	ds_read_b128 v[214:217], v163 offset:49152
	ds_read_b128 v[218:221], v163 offset:50176
	global_load_lds_dwordx4 v132, s[98:99]
	s_mov_b32 m0, s44
	ds_read_b128 v[222:225], v163 offset:51200
	ds_read_b128 v[226:229], v163 offset:52224
	global_load_lds_dwordx4 v128, s[98:99]
	s_mov_b32 m0, s48
	ds_read_b128 v[230:233], v163 offset:53248
	global_load_lds_dwordx4 v132, s[2:3]
	s_mov_b32 m0, s49
	ds_read_b128 v[234:237], v163 offset:54272
	global_load_lds_dwordx4 v128, s[2:3]
	s_mov_b32 m0, s45
	s_add_u32 s100, s4, 0xfffc0080
	s_addc_u32 s101, s5, -1
	ds_read_b128 v[238:241], v163 offset:55296
	global_load_lds_dwordx4 v134, s[100:101]
	s_mov_b32 m0, s47
	ds_read_b128 v[242:245], v163 offset:56320
	global_load_lds_dwordx4 v130, s[100:101]
	s_waitcnt vmcnt(8) lgkmcnt(0)
	s_barrier
	s_setprio 1
	v_mfma_f32_16x16x32_bf16 v[60:63], v[140:143], v[214:217], v[60:63]
	v_mfma_f32_16x16x32_bf16 v[56:59], v[170:173], v[214:217], v[56:59]
	v_mfma_f32_16x16x32_bf16 v[44:47], v[140:143], v[222:225], v[44:47]
	v_mfma_f32_16x16x32_bf16 v[40:43], v[170:173], v[222:225], v[40:43]
	v_mfma_f32_16x16x32_bf16 v[28:31], v[140:143], v[230:233], v[28:31]
	v_mfma_f32_16x16x32_bf16 v[24:27], v[170:173], v[230:233], v[24:27]
	v_mfma_f32_16x16x32_bf16 v[12:15], v[140:143], v[238:241], v[12:15]
	v_mfma_f32_16x16x32_bf16 v[8:11], v[170:173], v[238:241], v[8:11]
	v_mfma_f32_16x16x32_bf16 v[60:63], v[166:169], v[218:221], v[60:63]
	v_mfma_f32_16x16x32_bf16 v[56:59], v[174:177], v[218:221], v[56:59]
	v_mfma_f32_16x16x32_bf16 v[44:47], v[166:169], v[226:229], v[44:47]
	v_mfma_f32_16x16x32_bf16 v[40:43], v[174:177], v[226:229], v[40:43]
	v_mfma_f32_16x16x32_bf16 v[28:31], v[166:169], v[234:237], v[28:31]
	v_mfma_f32_16x16x32_bf16 v[24:27], v[174:177], v[234:237], v[24:27]
	v_mfma_f32_16x16x32_bf16 v[12:15], v[166:169], v[242:245], v[12:15]
	v_mfma_f32_16x16x32_bf16 v[8:11], v[174:177], v[242:245], v[8:11]
	v_mfma_f32_16x16x32_bf16 v[52:55], v[178:181], v[214:217], v[52:55]
	v_mfma_f32_16x16x32_bf16 v[48:51], v[186:189], v[214:217], v[48:51]
	v_mfma_f32_16x16x32_bf16 v[36:39], v[178:181], v[222:225], v[36:39]
	v_mfma_f32_16x16x32_bf16 v[32:35], v[186:189], v[222:225], v[32:35]
	v_mfma_f32_16x16x32_bf16 v[20:23], v[178:181], v[230:233], v[20:23]
	v_mfma_f32_16x16x32_bf16 v[16:19], v[186:189], v[230:233], v[16:19]
	v_mfma_f32_16x16x32_bf16 v[4:7], v[178:181], v[238:241], v[4:7]
	v_mfma_f32_16x16x32_bf16 v[0:3], v[186:189], v[238:241], v[0:3]
	v_mfma_f32_16x16x32_bf16 v[52:55], v[182:185], v[218:221], v[52:55]
	v_mfma_f32_16x16x32_bf16 v[48:51], v[210:213], v[218:221], v[48:51]
	v_mfma_f32_16x16x32_bf16 v[36:39], v[182:185], v[226:229], v[36:39]
	v_mfma_f32_16x16x32_bf16 v[32:35], v[210:213], v[226:229], v[32:35]
	v_mfma_f32_16x16x32_bf16 v[20:23], v[182:185], v[234:237], v[20:23]
	v_mfma_f32_16x16x32_bf16 v[16:19], v[210:213], v[234:237], v[16:19]
	v_mfma_f32_16x16x32_bf16 v[4:7], v[182:185], v[242:245], v[4:7]
	v_mfma_f32_16x16x32_bf16 v[0:3], v[210:213], v[242:245], v[0:3]
	s_setprio 0
	s_barrier
	s_add_i32 s55, s55, 2
	s_add_u32 s0, s0, 0x100
	s_addc_u32 s1, s1, 0
	s_add_u32 s53, s53, 0x100
	s_addc_u32 s54, s54, 0
	s_cmp_gt_u32 s55, 13
	s_cbranch_scc0 .LBB0_1042
	s_and_b64 vcc, exec, s[18:19]
	s_cbranch_vccz .LBB0_1045
	s_barrier
